# priority flips moved off the barrier->MFMA / MFMA->barrier edges; GEMM prologue issues all seven half-tiles before its first wait; rest as best stack
# baseline (speedup 1.0000x reference)
; #define PG8_STAGE(bufoff, gbase, voff) do { _Pragma("unroll") for (int _i = 0; _i < 2; ++_i) \
;         __builtin_amdgcn_global_load_lds((const unsigned*)((const char*)(gbase) + (voff)[_i]), (PG8_LAS unsigned*)(lds + (bufoff) + ldsw + _i * 8192), 16, 0, 0); } while (0)
; #define PG8_WAIT_V(n) asm volatile("s_waitcnt vmcnt(" #n ")" ::: "memory")
; #define PG8_BAR __builtin_amdgcn_s_barrier()
; template <class Epi, class Sched, bool ALIGN_EPI = false, bool SP2 = false>
; __device__ __forceinline__ void gemm_phase(PG8_LAS unsigned char* lds, const Gemm g, const Sched& S, const Epi& E, const int wid) {
;     ...
;     const int aoff = lds_byte(wr * 64 + fr, fq * 8), boff = lds_byte(wc * 32 + fr, fq * 8);
;     ...
;     if constexpr (SP2) {
;         PG8_STAGE(PG8_SB(0, 0), cB, voffB); PG8_STAGE(PG8_SB(0, 1), cB + hstepB, voffB); PG8_STAGE(PG8_SA(0, 0), cA, voffA); PG8_STAGE(PG8_SA(0, 1), cA + hstepA, voffA);
;         if (wr == 1) PG8_BAR;
;         PG8_WAIT_V(2); PG8_BAR;
;         PG8_STAGE(PG8_SB(1, 0), cB + kstep, voffB); PG8_STAGE(PG8_SA(1, 0), cA + kstep, voffA); PG8_STAGE(PG8_SB(1, 1), cB + hstepB + kstep, voffB);
;         PG8_WAIT_V(6); PG8_BAR;
.LBB0_108:
	s_mov_b64 s[12:13], 0x80
	s_add_i32 m0, s58, 0x18000
	v_lshl_add_u64 v[6:7], v[6:7], 0, s[12:13]
	global_load_lds_dwordx4 v[6:7], off
	v_lshl_add_u64 v[4:5], v[4:5], 0, s[12:13]
	s_add_i32 m0, s58, 0x1a000
	s_add_i32 s63, s58, 0x8000
	s_add_i32 s64, s58, 0xa000
	global_load_lds_dwordx4 v[4:5], off
	v_lshl_add_u64 v[0:1], v[0:1], 0, s[12:13]
	s_mov_b32 m0, s63
	s_add_u32 s4, s46, 0x40080
	global_load_lds_dwordx4 v[0:1], off
	v_lshl_add_u64 v[0:1], v[2:3], 0, s[12:13]
	s_mov_b32 m0, s64
	s_addc_u32 s5, s47, 0
	global_load_lds_dwordx4 v[0:1], off
	s_add_i32 m0, s58, 0x1c000
	v_lshl_add_u64 v[0:1], s[4:5], 0, v[130:131]
	global_load_lds_dwordx4 v[0:1], off
	v_lshl_add_u64 v[0:1], s[4:5], 0, v[134:135]
	s_add_i32 m0, s58, 0x1e000
	v_ashrrev_i32_e32 v2, 6, v8
	global_load_lds_dwordx4 v[0:1], off
	s_waitcnt vmcnt(8)
	s_barrier
	v_and_b32_e32 v0, 15, v8
	v_or_b32_e32 v152, s72, v0
	v_lshlrev_b32_e32 v3, 6, v152
	v_and_b32_e32 v4, 48, v8
	s_movk_i32 s4, 0x3c0
	v_readlane_b32 s3, v250, 27
	v_and_or_b32 v3, v3, s4, v4
	v_lshl_or_b32 v0, v0, 6, v4
	v_lshl_add_u32 v5, v2, 10, s3
	v_readlane_b32 s3, v250, 28
	v_lshlrev_b32_e32 v4, 2, v8
	v_and_b32_e32 v4, 32, v4
	v_add_lshl_u32 v2, v2, s3, 10
	s_cmp_gt_i32 s55, 0
	v_ashrrev_i32_e32 v1, 1, v8
	v_bitop3_b32 v153, v0, v2, v4 bitop3:0xde
	s_cselect_b64 s[18:19], -1, 0
	s_add_i32 s65, s55, -2
	v_readlane_b32 s3, v250, 18
	v_lshlrev_b32_e32 v0, 14, v9
	v_and_b32_e32 v1, -8, v1
	s_cmpk_lt_u32 s3, 0x100
	v_readlane_b32 s3, v250, 21
	v_and_b32_e32 v0, 0xffff8000, v0
	v_lshl_add_u32 v0, v10, 11, v0
	v_add_u32_e32 v154, s3, v1
	v_and_b32_e32 v1, 1, v9
	v_lshl_or_b32 v0, v1, 6, v0
	v_lshl_add_u32 v136, v11, 1, v0
	v_lshlrev_b32_e32 v0, 14, v12
	v_lshlrev_b32_e32 v6, 2, v152
	v_and_b32_e32 v0, 0xffff8000, v0
	v_and_b32_e32 v6, 32, v6
	s_waitcnt vmcnt(6)
	v_lshl_add_u32 v0, v13, 11, v0
	v_and_b32_e32 v1, 1, v12
	v_bitop3_b32 v3, v3, v5, v6 bitop3:0xde
	s_cselect_b64 s[24:25], -1, 0
	v_lshl_or_b32 v0, v1, 6, v0
	s_add_i32 s69, 0, 0x10000
	s_add_i32 s70, 0, 0x14000
	s_ashr_i32 s66, s42, 31
	s_mov_b32 s67, s42
	s_ashr_i32 s68, s2, 31
	v_mov_b32_e32 v137, v131
	v_lshl_add_u32 v138, v14, 1, v0
	v_mov_b32_e32 v139, v131
	v_mov_b64_e32 v[140:141], 0x200
	v_mov_b64_e32 v[142:143], 0x1ff
	v_add_u32_e32 v155, s69, v153
	v_add_u32_e32 v156, s70, v153
	v_add_u32_e32 v157, 0, v3
	s_barrier
	s_branch .LBB0_111

; #define PG8_STAGE(bufoff, gbase, voff) do { _Pragma("unroll") for (int _i = 0; _i < 2; ++_i) \
;         __builtin_amdgcn_global_load_lds((const unsigned*)((const char*)(gbase) + (voff)[_i]), (PG8_LAS unsigned*)(lds + (bufoff) + ldsw + _i * 8192), 16, 0, 0); } while (0)
; #define PG8_LDA(dst, b, h) do { _Pragma("unroll") for (int m = 0; m < 4; ++m) _Pragma("unroll") for (int k = 0; k < 2; ++k) dst[m][k] = *(const PG8_LAS bf16x8*)(lds + PG8_SA(b, h) + aoff + m * 2048 + k * 1024); } while (0)
; #define PG8_LDB(dst, b, h) do { _Pragma("unroll") for (int n = 0; n < 2; ++n) _Pragma("unroll") for (int k = 0; k < 2; ++k) dst[n][k] = *(const PG8_LAS bf16x8*)(lds + PG8_SB(b, h) + boff + n * 2048 + k * 1024); } while (0)
; #define PG8_MMA(ai, bj, At, Bt) do { __builtin_amdgcn_s_setprio(1); _Pragma("unroll") for (int m = 0; m < 4; ++m) _Pragma("unroll") for (int n = 0; n < 2; ++n) _Pragma("unroll") for (int k = 0; k < 2; ++k) \
;         acc[ai][bj][m][n] = __builtin_amdgcn_mfma_f32_16x16x32_bf16(Bt[n][k], At[m][k], acc[ai][bj][m][n], 0, 0, 0); __builtin_amdgcn_s_setprio(0); } while (0)
; #define PG8_WAIT_V(n) asm volatile("s_waitcnt vmcnt(" #n ")" ::: "memory")
; #define PG8_WAIT_L(n) asm volatile("s_waitcnt lgkmcnt(" #n ")" ::: "memory")
; template <class Epi, class Sched, bool ALIGN_EPI = false, bool SP2 = false>
; __device__ __forceinline__ void gemm_phase(PG8_LAS unsigned char* lds, const Gemm g, const Sched& S, const Epi& E, const int wid) {
;     ...
;             const bool last = (t == nt - 2);
;             const char* a1 = cA + (size_t)(t + 1) * kstep;
;             const char* a2 = last ? nA : cA + (size_t)(t + 2) * kstep; const char* b2 = last ? nB : cB + (size_t)(t + 2) * kstep;
;             const char* a3 = a2 + kstep; const char* b3 = b2 + kstep;
;             if (last && has_next) S.a_ready(nxt);
;             if constexpr (SP2) {
;             PG8_LDB(B0, 0, 0); PG8_LDB(B1, 0, 1); PG8_SCHED; PG8_LDA(At, 0, 0); PG8_STAGE(PG8_SA(1, 1), a1 + hstepA, voffA);
;             PG8_WAIT_V(8); PG8_WAIT_L(0); PG8_BAR; PG8_MMA(0, 0, At, B0); PG8_MMA(0, 1, At, B1); PG8_BAR; PG8_SCHED;
;             PG8_LDA(At, 0, 1); PG8_STAGE(PG8_SB(0, 0), b2, voffB); PG8_STAGE(PG8_SB(0, 1), b2 + hstepB, voffB); PG8_STAGE(PG8_SA(0, 0), a2, voffA);
;             PG8_WAIT_V(8); PG8_WAIT_L(0); PG8_BAR; PG8_MMA(1, 0, At, B0); PG8_MMA(1, 1, At, B1); PG8_BAR; PG8_SCHED;
.LBB0_119:
	ds_read_b128 v[144:147], v155
	ds_read_b128 v[148:151], v155 offset:1024
	ds_read_b128 v[158:161], v155 offset:2048
	ds_read_b128 v[162:165], v155 offset:3072
	ds_read_b128 v[166:169], v156
	ds_read_b128 v[170:173], v156 offset:1024
	ds_read_b128 v[174:177], v156 offset:2048
	ds_read_b128 v[180:183], v156 offset:3072
	s_add_i32 s41, s35, 2
	s_add_u32 s46, s44, 0xfffc0080
	s_addc_u32 s47, s45, -1
	s_cmp_eq_u32 s65, s35
	s_cselect_b32 s49, s37, s47
	s_cselect_b32 s48, s36, s46
	s_cselect_b32 s47, s39, s31
	s_cselect_b32 s46, s38, s7
	v_lshl_add_u64 v[216:217], s[44:45], 0, v[136:137]
	s_add_i32 m0, s58, 0xc000
	ds_read_b128 v[184:187], v157
	ds_read_b128 v[188:191], v157 offset:1024
	ds_read_b128 v[192:195], v157 offset:2048
	ds_read_b128 v[196:199], v157 offset:3072
	ds_read_b128 v[200:203], v157 offset:4096
	ds_read_b128 v[204:207], v157 offset:5120
	ds_read_b128 v[208:211], v157 offset:6144
	ds_read_b128 v[212:215], v157 offset:7168
	global_load_lds_dwordx4 v[216:217], off
	v_lshl_add_u64 v[216:217], s[44:45], 0, v[138:139]
	s_add_i32 m0, s58, 0xe000
	s_nop 0
	global_load_lds_dwordx4 v[216:217], off
	s_waitcnt vmcnt(8)
	s_waitcnt lgkmcnt(0)
	s_setprio 1
	s_barrier
	v_mfma_f32_16x16x32_bf16 v[124:127], v[144:147], v[184:187], v[124:127]
	v_mfma_f32_16x16x32_bf16 v[120:123], v[158:161], v[184:187], v[120:123]
	v_mfma_f32_16x16x32_bf16 v[108:111], v[144:147], v[192:195], v[108:111]
	v_mfma_f32_16x16x32_bf16 v[104:107], v[158:161], v[192:195], v[104:107]
	v_mfma_f32_16x16x32_bf16 v[92:95], v[144:147], v[200:203], v[92:95]
	v_mfma_f32_16x16x32_bf16 v[88:91], v[158:161], v[200:203], v[88:91]
	v_mfma_f32_16x16x32_bf16 v[76:79], v[144:147], v[208:211], v[76:79]
	v_mfma_f32_16x16x32_bf16 v[72:75], v[158:161], v[208:211], v[72:75]
	v_mfma_f32_16x16x32_bf16 v[124:127], v[148:151], v[188:191], v[124:127]
	v_mfma_f32_16x16x32_bf16 v[120:123], v[162:165], v[188:191], v[120:123]
	v_mfma_f32_16x16x32_bf16 v[108:111], v[148:151], v[196:199], v[108:111]
	v_mfma_f32_16x16x32_bf16 v[104:107], v[162:165], v[196:199], v[104:107]
	v_mfma_f32_16x16x32_bf16 v[92:95], v[148:151], v[204:207], v[92:95]
	v_mfma_f32_16x16x32_bf16 v[88:91], v[162:165], v[204:207], v[88:91]
	v_mfma_f32_16x16x32_bf16 v[76:79], v[148:151], v[212:215], v[76:79]
	v_mfma_f32_16x16x32_bf16 v[72:75], v[162:165], v[212:215], v[72:75]
	s_setprio 0
	s_setprio 1
	v_mfma_f32_16x16x32_bf16 v[116:119], v[166:169], v[184:187], v[116:119]
	v_mfma_f32_16x16x32_bf16 v[112:115], v[174:177], v[184:187], v[112:115]
	v_mfma_f32_16x16x32_bf16 v[100:103], v[166:169], v[192:195], v[100:103]
	v_mfma_f32_16x16x32_bf16 v[96:99], v[174:177], v[192:195], v[96:99]
	v_mfma_f32_16x16x32_bf16 v[84:87], v[166:169], v[200:203], v[84:87]
	v_mfma_f32_16x16x32_bf16 v[80:83], v[174:177], v[200:203], v[80:83]
	v_mfma_f32_16x16x32_bf16 v[68:71], v[166:169], v[208:211], v[68:71]
	v_mfma_f32_16x16x32_bf16 v[64:67], v[174:177], v[208:211], v[64:67]
	v_mfma_f32_16x16x32_bf16 v[116:119], v[170:173], v[188:191], v[116:119]
	v_mfma_f32_16x16x32_bf16 v[112:115], v[180:183], v[188:191], v[112:115]
	v_mfma_f32_16x16x32_bf16 v[100:103], v[170:173], v[196:199], v[100:103]
	v_mfma_f32_16x16x32_bf16 v[96:99], v[180:183], v[196:199], v[96:99]
	v_mfma_f32_16x16x32_bf16 v[84:87], v[170:173], v[204:207], v[84:87]
	v_mfma_f32_16x16x32_bf16 v[80:83], v[180:183], v[204:207], v[80:83]
	v_mfma_f32_16x16x32_bf16 v[68:71], v[170:173], v[212:215], v[68:71]
	v_mfma_f32_16x16x32_bf16 v[64:67], v[180:183], v[212:215], v[64:67]
	s_barrier
	s_setprio 0
	s_add_i32 s35, s69, s0
	v_lshl_add_u64 v[216:217], s[46:47], 0, v[130:131]
	s_mov_b32 m0, s35
	ds_read_b128 v[184:187], v157 offset:16384
	ds_read_b128 v[188:191], v157 offset:17408
	ds_read_b128 v[192:195], v157 offset:18432
	ds_read_b128 v[196:199], v157 offset:19456
	ds_read_b128 v[200:203], v157 offset:20480
	ds_read_b128 v[204:207], v157 offset:21504
	ds_read_b128 v[208:211], v157 offset:22528
	ds_read_b128 v[212:215], v157 offset:23552
	global_load_lds_dwordx4 v[216:217], off
	s_add_i32 m0, s35, 0x2000
	s_add_u32 s72, s46, 0x40000
	v_lshl_add_u64 v[218:219], s[46:47], 0, v[134:135]
	s_addc_u32 s73, s47, 0
	s_add_i32 s35, s70, s0
	global_load_lds_dwordx4 v[218:219], off
	v_lshl_add_u64 v[220:221], s[72:73], 0, v[130:131]
	s_mov_b32 m0, s35
	v_lshl_add_u64 v[222:223], s[48:49], 0, v[132:133]
	global_load_lds_dwordx4 v[220:221], off
	v_lshl_add_u64 v[220:221], s[72:73], 0, v[134:135]
	s_add_i32 m0, s35, 0x2000
	s_nop 0
	global_load_lds_dwordx4 v[220:221], off
	v_lshl_add_u64 v[220:221], s[48:49], 0, v[128:129]
	s_mov_b32 m0, s58
	s_nop 0
	global_load_lds_dwordx4 v[220:221], off
	s_mov_b32 m0, s59
	s_nop 0
	global_load_lds_dwordx4 v[222:223], off
	s_waitcnt vmcnt(8)
	s_waitcnt lgkmcnt(0)
	s_setprio 1
	s_barrier
; #define PG8_STAGE(bufoff, gbase, voff) do { _Pragma("unroll") for (int _i = 0; _i < 2; ++_i) \
;         __builtin_amdgcn_global_load_lds((const unsigned*)((const char*)(gbase) + (voff)[_i]), (PG8_LAS unsigned*)(lds + (bufoff) + ldsw + _i * 8192), 16, 0, 0); } while (0)
; #define PG8_LDA(dst, b, h) do { _Pragma("unroll") for (int m = 0; m < 4; ++m) _Pragma("unroll") for (int k = 0; k < 2; ++k) dst[m][k] = *(const PG8_LAS bf16x8*)(lds + PG8_SA(b, h) + aoff + m * 2048 + k * 1024); } while (0)
; #define PG8_LDB(dst, b, h) do { _Pragma("unroll") for (int n = 0; n < 2; ++n) _Pragma("unroll") for (int k = 0; k < 2; ++k) dst[n][k] = *(const PG8_LAS bf16x8*)(lds + PG8_SB(b, h) + boff + n * 2048 + k * 1024); } while (0)
; #define PG8_MMA(ai, bj, At, Bt) do { __builtin_amdgcn_s_setprio(1); _Pragma("unroll") for (int m = 0; m < 4; ++m) _Pragma("unroll") for (int n = 0; n < 2; ++n) _Pragma("unroll") for (int k = 0; k < 2; ++k) \
;         acc[ai][bj][m][n] = __builtin_amdgcn_mfma_f32_16x16x32_bf16(Bt[n][k], At[m][k], acc[ai][bj][m][n], 0, 0, 0); __builtin_amdgcn_s_setprio(0); } while (0)
; #define PG8_WAIT_V(n) asm volatile("s_waitcnt vmcnt(" #n ")" ::: "memory")
; #define PG8_WAIT_L(n) asm volatile("s_waitcnt lgkmcnt(" #n ")" ::: "memory")
; #define PG8_BAR __builtin_amdgcn_s_barrier()
; #define PG8_SCHED __builtin_amdgcn_sched_barrier(0)
; template <class Epi, class Sched, bool ALIGN_EPI = false, bool SP2 = false>
; __device__ __forceinline__ void gemm_phase(PG8_LAS unsigned char* lds, const Gemm g, const Sched& S, const Epi& E, const int wid) {
;     ...
;             PG8_WAIT_V(8); PG8_WAIT_L(0); PG8_BAR; PG8_MMA(1, 0, At, B0); PG8_MMA(1, 1, At, B1); PG8_BAR; PG8_SCHED;
;             PG8_LDB(B0, 1, 0); PG8_LDB(B1, 1, 1); PG8_SCHED; PG8_LDA(At, 1, 0); PG8_STAGE(PG8_SA(0, 1), a2 + hstepA, voffA);
;             PG8_WAIT_V(8); PG8_WAIT_L(0); PG8_BAR; PG8_MMA(0, 0, At, B0); PG8_MMA(0, 1, At, B1); PG8_BAR; PG8_SCHED;
	v_mfma_f32_16x16x32_bf16 v[60:63], v[144:147], v[184:187], v[60:63]
	v_mfma_f32_16x16x32_bf16 v[56:59], v[158:161], v[184:187], v[56:59]
	v_mfma_f32_16x16x32_bf16 v[44:47], v[144:147], v[192:195], v[44:47]
	v_mfma_f32_16x16x32_bf16 v[40:43], v[158:161], v[192:195], v[40:43]
	v_mfma_f32_16x16x32_bf16 v[28:31], v[144:147], v[200:203], v[28:31]
	v_mfma_f32_16x16x32_bf16 v[24:27], v[158:161], v[200:203], v[24:27]
	v_mfma_f32_16x16x32_bf16 v[12:15], v[144:147], v[208:211], v[12:15]
	v_mfma_f32_16x16x32_bf16 v[8:11], v[158:161], v[208:211], v[8:11]
	v_mfma_f32_16x16x32_bf16 v[60:63], v[148:151], v[188:191], v[60:63]
	v_mfma_f32_16x16x32_bf16 v[56:59], v[162:165], v[188:191], v[56:59]
	v_mfma_f32_16x16x32_bf16 v[44:47], v[148:151], v[196:199], v[44:47]
	v_mfma_f32_16x16x32_bf16 v[40:43], v[162:165], v[196:199], v[40:43]
	v_mfma_f32_16x16x32_bf16 v[28:31], v[148:151], v[204:207], v[28:31]
	v_mfma_f32_16x16x32_bf16 v[24:27], v[162:165], v[204:207], v[24:27]
	v_mfma_f32_16x16x32_bf16 v[12:15], v[148:151], v[212:215], v[12:15]
	v_mfma_f32_16x16x32_bf16 v[8:11], v[162:165], v[212:215], v[8:11]
	s_setprio 0
	s_setprio 1
	v_mfma_f32_16x16x32_bf16 v[52:55], v[166:169], v[184:187], v[52:55]
	v_mfma_f32_16x16x32_bf16 v[48:51], v[174:177], v[184:187], v[48:51]
	v_mfma_f32_16x16x32_bf16 v[36:39], v[166:169], v[192:195], v[36:39]
	v_mfma_f32_16x16x32_bf16 v[32:35], v[174:177], v[192:195], v[32:35]
	v_mfma_f32_16x16x32_bf16 v[20:23], v[166:169], v[200:203], v[20:23]
	v_mfma_f32_16x16x32_bf16 v[16:19], v[174:177], v[200:203], v[16:19]
	v_mfma_f32_16x16x32_bf16 v[4:7], v[166:169], v[208:211], v[4:7]
	v_mfma_f32_16x16x32_bf16 v[0:3], v[174:177], v[208:211], v[0:3]
	v_mfma_f32_16x16x32_bf16 v[52:55], v[170:173], v[188:191], v[52:55]
	v_mfma_f32_16x16x32_bf16 v[48:51], v[180:183], v[188:191], v[48:51]
	v_mfma_f32_16x16x32_bf16 v[36:39], v[170:173], v[196:199], v[36:39]
	v_mfma_f32_16x16x32_bf16 v[32:35], v[180:183], v[196:199], v[32:35]
	v_mfma_f32_16x16x32_bf16 v[20:23], v[170:173], v[204:207], v[20:23]
	v_mfma_f32_16x16x32_bf16 v[16:19], v[180:183], v[204:207], v[16:19]
	v_mfma_f32_16x16x32_bf16 v[4:7], v[170:173], v[212:215], v[4:7]
	v_mfma_f32_16x16x32_bf16 v[0:3], v[180:183], v[212:215], v[0:3]
	s_barrier
	s_setprio 0
	s_add_i32 s35, 0, 0x18000
	s_add_i32 s71, 0, 0x1c000
	v_add_u32_e32 v162, s35, v153
	v_add_u32_e32 v179, s71, v153
	ds_read_b128 v[144:147], v162
	ds_read_b128 v[148:151], v162 offset:1024
	ds_read_b128 v[158:161], v162 offset:2048
	ds_read_b128 v[162:165], v162 offset:3072
	ds_read_b128 v[166:169], v179
	ds_read_b128 v[170:173], v179 offset:1024
	ds_read_b128 v[174:177], v179 offset:2048
	ds_read_b128 v[180:183], v179 offset:3072
	s_add_u32 s48, s48, 0x40000
	s_addc_u32 s49, s49, 0
	s_mov_b32 m0, s60
	v_lshl_add_u64 v[224:225], s[48:49], 0, v[128:129]
	ds_read_b128 v[184:187], v157 offset:32768
	ds_read_b128 v[188:191], v157 offset:33792
	ds_read_b128 v[192:195], v157 offset:34816
	ds_read_b128 v[196:199], v157 offset:35840
	ds_read_b128 v[200:203], v157 offset:36864
	ds_read_b128 v[204:207], v157 offset:37888
	ds_read_b128 v[208:211], v157 offset:38912
	ds_read_b128 v[212:215], v157 offset:39936
	global_load_lds_dwordx4 v[224:225], off
	v_lshl_add_u64 v[224:225], s[48:49], 0, v[132:133]
	s_mov_b32 m0, s61
	s_nop 0
	global_load_lds_dwordx4 v[224:225], off
	s_waitcnt vmcnt(8)
	s_waitcnt lgkmcnt(0)
	s_setprio 1
	s_barrier
	v_mfma_f32_16x16x32_bf16 v[124:127], v[144:147], v[184:187], v[124:127]
	v_mfma_f32_16x16x32_bf16 v[120:123], v[158:161], v[184:187], v[120:123]
	v_mfma_f32_16x16x32_bf16 v[108:111], v[144:147], v[192:195], v[108:111]
	v_mfma_f32_16x16x32_bf16 v[104:107], v[158:161], v[192:195], v[104:107]
	v_mfma_f32_16x16x32_bf16 v[92:95], v[144:147], v[200:203], v[92:95]
	v_mfma_f32_16x16x32_bf16 v[88:91], v[158:161], v[200:203], v[88:91]
	v_mfma_f32_16x16x32_bf16 v[76:79], v[144:147], v[208:211], v[76:79]
	v_mfma_f32_16x16x32_bf16 v[72:75], v[158:161], v[208:211], v[72:75]
	v_mfma_f32_16x16x32_bf16 v[124:127], v[148:151], v[188:191], v[124:127]
	v_mfma_f32_16x16x32_bf16 v[120:123], v[162:165], v[188:191], v[120:123]
	v_mfma_f32_16x16x32_bf16 v[108:111], v[148:151], v[196:199], v[108:111]
	v_mfma_f32_16x16x32_bf16 v[104:107], v[162:165], v[196:199], v[104:107]
	v_mfma_f32_16x16x32_bf16 v[92:95], v[148:151], v[204:207], v[92:95]
	v_mfma_f32_16x16x32_bf16 v[88:91], v[162:165], v[204:207], v[88:91]
	v_mfma_f32_16x16x32_bf16 v[76:79], v[148:151], v[212:215], v[76:79]
	v_mfma_f32_16x16x32_bf16 v[72:75], v[162:165], v[212:215], v[72:75]
	s_setprio 0
	s_setprio 1
	v_mfma_f32_16x16x32_bf16 v[116:119], v[166:169], v[184:187], v[116:119]
	v_mfma_f32_16x16x32_bf16 v[112:115], v[174:177], v[184:187], v[112:115]
	v_mfma_f32_16x16x32_bf16 v[100:103], v[166:169], v[192:195], v[100:103]
	v_mfma_f32_16x16x32_bf16 v[96:99], v[174:177], v[192:195], v[96:99]
	v_mfma_f32_16x16x32_bf16 v[84:87], v[166:169], v[200:203], v[84:87]
	v_mfma_f32_16x16x32_bf16 v[80:83], v[174:177], v[200:203], v[80:83]
	v_mfma_f32_16x16x32_bf16 v[68:71], v[166:169], v[208:211], v[68:71]
	v_mfma_f32_16x16x32_bf16 v[64:67], v[174:177], v[208:211], v[64:67]
	v_mfma_f32_16x16x32_bf16 v[116:119], v[170:173], v[188:191], v[116:119]
	v_mfma_f32_16x16x32_bf16 v[112:115], v[180:183], v[188:191], v[112:115]
	v_mfma_f32_16x16x32_bf16 v[100:103], v[170:173], v[196:199], v[100:103]
	v_mfma_f32_16x16x32_bf16 v[96:99], v[180:183], v[196:199], v[96:99]
	v_mfma_f32_16x16x32_bf16 v[84:87], v[170:173], v[204:207], v[84:87]
	v_mfma_f32_16x16x32_bf16 v[80:83], v[180:183], v[204:207], v[80:83]
	v_mfma_f32_16x16x32_bf16 v[68:71], v[170:173], v[212:215], v[68:71]
	v_mfma_f32_16x16x32_bf16 v[64:67], v[180:183], v[212:215], v[64:67]
	s_barrier
; #define PG8_STAGE(bufoff, gbase, voff) do { _Pragma("unroll") for (int _i = 0; _i < 2; ++_i) \
;         __builtin_amdgcn_global_load_lds((const unsigned*)((const char*)(gbase) + (voff)[_i]), (PG8_LAS unsigned*)(lds + (bufoff) + ldsw + _i * 8192), 16, 0, 0); } while (0)
; #define PG8_LDA(dst, b, h) do { _Pragma("unroll") for (int m = 0; m < 4; ++m) _Pragma("unroll") for (int k = 0; k < 2; ++k) dst[m][k] = *(const PG8_LAS bf16x8*)(lds + PG8_SA(b, h) + aoff + m * 2048 + k * 1024); } while (0)
; #define PG8_MMA(ai, bj, At, Bt) do { __builtin_amdgcn_s_setprio(1); _Pragma("unroll") for (int m = 0; m < 4; ++m) _Pragma("unroll") for (int n = 0; n < 2; ++n) _Pragma("unroll") for (int k = 0; k < 2; ++k) \
;         acc[ai][bj][m][n] = __builtin_amdgcn_mfma_f32_16x16x32_bf16(Bt[n][k], At[m][k], acc[ai][bj][m][n], 0, 0, 0); __builtin_amdgcn_s_setprio(0); } while (0)
; #define PG8_WAIT_V(n) asm volatile("s_waitcnt vmcnt(" #n ")" ::: "memory")
; #define PG8_WAIT_L(n) asm volatile("s_waitcnt lgkmcnt(" #n ")" ::: "memory")
; #define PG8_BAR __builtin_amdgcn_s_barrier()
; #define PG8_SCHED __builtin_amdgcn_sched_barrier(0)
; template <class Epi, class Sched, bool ALIGN_EPI = false, bool SP2 = false>
; __device__ __forceinline__ void gemm_phase(PG8_LAS unsigned char* lds, const Gemm g, const Sched& S, const Epi& E, const int wid) {
;     ...
;             PG8_LDA(At, 1, 1); PG8_STAGE(PG8_SB(1, 0), b3, voffB); PG8_STAGE(PG8_SB(1, 1), b3 + hstepB, voffB); PG8_STAGE(PG8_SA(1, 0), a3, voffA);
;             PG8_WAIT_V(8); PG8_WAIT_L(0); PG8_BAR; PG8_MMA(1, 0, At, B0); PG8_MMA(1, 1, At, B1); PG8_BAR; PG8_SCHED;
	s_setprio 0
	s_add_i32 s35, s35, s0
	v_lshl_add_u64 v[216:217], v[216:217], 0, s[12:13]
	s_mov_b32 m0, s35
	ds_read_b128 v[184:187], v157 offset:49152
	ds_read_b128 v[188:191], v157 offset:50176
	ds_read_b128 v[192:195], v157 offset:51200
	ds_read_b128 v[196:199], v157 offset:52224
	ds_read_b128 v[200:203], v157 offset:53248
	ds_read_b128 v[204:207], v157 offset:54272
	ds_read_b128 v[208:211], v157 offset:55296
	ds_read_b128 v[212:215], v157 offset:56320
	global_load_lds_dwordx4 v[216:217], off
	s_add_i32 m0, s35, 0x2000
	s_add_u32 s46, s46, 0x40080
	v_lshl_add_u64 v[216:217], v[218:219], 0, s[12:13]
	s_addc_u32 s47, s47, 0
	s_add_i32 s35, s71, s0
	global_load_lds_dwordx4 v[216:217], off
	v_lshl_add_u64 v[216:217], s[46:47], 0, v[130:131]
	s_mov_b32 m0, s35
	s_nop 0
	global_load_lds_dwordx4 v[216:217], off
	v_lshl_add_u64 v[216:217], s[46:47], 0, v[134:135]
	s_add_i32 m0, s35, 0x2000
	s_nop 0
	global_load_lds_dwordx4 v[216:217], off
	v_lshl_add_u64 v[216:217], v[220:221], 0, s[12:13]
	s_mov_b32 m0, s63
	s_nop 0
	global_load_lds_dwordx4 v[216:217], off
	v_lshl_add_u64 v[216:217], v[222:223], 0, s[12:13]
	s_mov_b32 m0, s64
	s_nop 0
	global_load_lds_dwordx4 v[216:217], off
	s_waitcnt vmcnt(8)
	s_waitcnt lgkmcnt(0)
	s_setprio 1
	s_barrier
	v_mfma_f32_16x16x32_bf16 v[60:63], v[144:147], v[184:187], v[60:63]
	v_mfma_f32_16x16x32_bf16 v[56:59], v[158:161], v[184:187], v[56:59]
	v_mfma_f32_16x16x32_bf16 v[44:47], v[144:147], v[192:195], v[44:47]
	v_mfma_f32_16x16x32_bf16 v[40:43], v[158:161], v[192:195], v[40:43]
	v_mfma_f32_16x16x32_bf16 v[28:31], v[144:147], v[200:203], v[28:31]
	v_mfma_f32_16x16x32_bf16 v[24:27], v[158:161], v[200:203], v[24:27]
	v_mfma_f32_16x16x32_bf16 v[12:15], v[144:147], v[208:211], v[12:15]
	v_mfma_f32_16x16x32_bf16 v[8:11], v[158:161], v[208:211], v[8:11]
	v_mfma_f32_16x16x32_bf16 v[60:63], v[148:151], v[188:191], v[60:63]
	v_mfma_f32_16x16x32_bf16 v[56:59], v[162:165], v[188:191], v[56:59]
	v_mfma_f32_16x16x32_bf16 v[44:47], v[148:151], v[196:199], v[44:47]
	v_mfma_f32_16x16x32_bf16 v[40:43], v[162:165], v[196:199], v[40:43]
	v_mfma_f32_16x16x32_bf16 v[28:31], v[148:151], v[204:207], v[28:31]
	v_mfma_f32_16x16x32_bf16 v[24:27], v[162:165], v[204:207], v[24:27]
	v_mfma_f32_16x16x32_bf16 v[12:15], v[148:151], v[212:215], v[12:15]
	v_mfma_f32_16x16x32_bf16 v[8:11], v[162:165], v[212:215], v[8:11]
	s_setprio 0
	s_setprio 1
	v_mfma_f32_16x16x32_bf16 v[52:55], v[166:169], v[184:187], v[52:55]
	v_mfma_f32_16x16x32_bf16 v[48:51], v[174:177], v[184:187], v[48:51]
	v_mfma_f32_16x16x32_bf16 v[36:39], v[166:169], v[192:195], v[36:39]
	v_mfma_f32_16x16x32_bf16 v[32:35], v[174:177], v[192:195], v[32:35]
	v_mfma_f32_16x16x32_bf16 v[20:23], v[166:169], v[200:203], v[20:23]
	v_mfma_f32_16x16x32_bf16 v[16:19], v[174:177], v[200:203], v[16:19]
	v_mfma_f32_16x16x32_bf16 v[4:7], v[166:169], v[208:211], v[4:7]
	v_mfma_f32_16x16x32_bf16 v[0:3], v[174:177], v[208:211], v[0:3]
	v_mfma_f32_16x16x32_bf16 v[52:55], v[170:173], v[188:191], v[52:55]
	v_mfma_f32_16x16x32_bf16 v[48:51], v[180:183], v[188:191], v[48:51]
	v_mfma_f32_16x16x32_bf16 v[36:39], v[170:173], v[196:199], v[36:39]
	v_mfma_f32_16x16x32_bf16 v[32:35], v[180:183], v[196:199], v[32:35]
	v_mfma_f32_16x16x32_bf16 v[20:23], v[170:173], v[204:207], v[20:23]
	v_mfma_f32_16x16x32_bf16 v[16:19], v[180:183], v[204:207], v[16:19]
	v_mfma_f32_16x16x32_bf16 v[4:7], v[170:173], v[212:215], v[4:7]
	v_mfma_f32_16x16x32_bf16 v[0:3], v[180:183], v[212:215], v[0:3]
	s_barrier
	s_setprio 0
	s_add_u32 s44, s44, 0x100
	s_addc_u32 s45, s45, 0
	s_add_u32 s7, s7, 0x100
	s_addc_u32 s31, s31, 0
	s_cmp_ge_i32 s41, s55
	s_mov_b32 s35, s41
	s_cbranch_scc0 .LBB0_119
	v_readlane_b32 s72, v250, 29
	s_and_b64 vcc, exec, s[24:25]
	s_cbranch_vccz .LBB0_122

; #define PG8_STAGE(bufoff, gbase, voff) do { _Pragma("unroll") for (int _i = 0; _i < 2; ++_i) \
;         __builtin_amdgcn_global_load_lds((const unsigned*)((const char*)(gbase) + (voff)[_i]), (PG8_LAS unsigned*)(lds + (bufoff) + ldsw + _i * 8192), 16, 0, 0); } while (0)
; #define PG8_WAIT_V(n) asm volatile("s_waitcnt vmcnt(" #n ")" ::: "memory")
; #define PG8_BAR __builtin_amdgcn_s_barrier()
; template <class Epi, class Sched, bool ALIGN_EPI = false, bool SP2 = false>
; __device__ __forceinline__ void gemm_phase(PG8_LAS unsigned char* lds, const Gemm g, const Sched& S, const Epi& E, const int wid) {
;     ...
;     const int aoff = lds_byte(wr * 64 + fr, fq * 8), boff = lds_byte(wc * 32 + fr, fq * 8);
;     ...
;         PG8_STAGE(PG8_SB(1, 0), cB + kstep, voffB); PG8_STAGE(PG8_SA(1, 0), cA + kstep, voffA); PG8_STAGE(PG8_SB(1, 1), cB + hstepB + kstep, voffB);
;         PG8_WAIT_V(6); PG8_BAR;
.LBB0_257:
	s_ashr_i32 s67, s4, 3
	s_add_u32 s10, s90, 0x3900000
	s_mov_b64 s[22:23], 0x80
	s_addc_u32 s11, s91, 0
	s_add_i32 m0, s41, 0x18000
	v_lshl_add_u64 v[6:7], v[6:7], 0, s[22:23]
	global_load_lds_dwordx4 v[6:7], off
	v_lshl_add_u64 v[4:5], v[4:5], 0, s[22:23]
	s_add_i32 m0, s41, 0x1a000
	s_add_i32 s61, s41, 0x8000
	s_add_i32 s62, s41, 0xa000
	global_load_lds_dwordx4 v[4:5], off
	v_lshl_add_u64 v[0:1], v[0:1], 0, s[22:23]
	s_mov_b32 m0, s61
	s_add_u32 s4, s46, 0x10080
	global_load_lds_dwordx4 v[0:1], off
	v_lshl_add_u64 v[0:1], v[2:3], 0, s[22:23]
	s_mov_b32 m0, s62
	s_addc_u32 s5, s47, 0
	global_load_lds_dwordx4 v[0:1], off
	s_add_i32 m0, s41, 0x1c000
	v_lshl_add_u64 v[0:1], s[4:5], 0, v[154:155]
	global_load_lds_dwordx4 v[0:1], off
	v_lshl_add_u64 v[0:1], s[4:5], 0, v[158:159]
	s_add_i32 m0, s41, 0x1e000
	v_and_b32_e32 v5, 48, v8
	global_load_lds_dwordx4 v[0:1], off
	s_waitcnt vmcnt(8)
	s_barrier
	v_and_b32_e32 v0, 15, v8
	v_or_b32_e32 v1, s72, v0
	v_lshlrev_b32_e32 v4, 6, v1
	s_movk_i32 s4, 0x3c0
	v_ashrrev_i32_e32 v3, 6, v8
	v_and_or_b32 v4, v4, s4, v5
	v_readlane_b32 s4, v250, 27
	v_lshl_or_b32 v0, v0, 6, v5
	v_lshlrev_b32_e32 v5, 2, v8
	v_lshl_add_u32 v6, v3, 10, s4
	v_readlane_b32 s4, v250, 28
	v_and_b32_e32 v5, 32, v5
	v_lshlrev_b32_e32 v7, 2, v1
	v_add_lshl_u32 v3, v3, s4, 10
	v_bitop3_b32 v179, v0, v3, v5 bitop3:0xde
	v_lshlrev_b32_e32 v0, 14, v9
	v_and_b32_e32 v0, 0xffff8000, v0
	v_lshlrev_b32_e32 v181, 10, v1
	v_lshl_add_u32 v0, v10, 11, v0
	v_and_b32_e32 v1, 1, v9
	v_lshl_or_b32 v0, v1, 6, v0
	s_cmp_gt_i32 s54, 0
	v_lshl_add_u32 v162, v11, 1, v0
	v_lshlrev_b32_e32 v0, 14, v12
	s_cselect_b64 s[24:25], -1, 0
	s_add_i32 s63, s54, -2
	v_readlane_b32 s4, v250, 18
	v_and_b32_e32 v0, 0xffff8000, v0
	v_ashrrev_i32_e32 v2, 1, v8
	v_and_b32_e32 v7, 32, v7
	s_waitcnt vmcnt(6)
	s_cmpk_lt_u32 s4, 0x100
	v_lshl_add_u32 v0, v13, 11, v0
	v_and_b32_e32 v1, 1, v12
	v_and_b32_e32 v2, -8, v2
	v_bitop3_b32 v4, v4, v6, v7 bitop3:0xde
	s_cselect_b64 s[30:31], -1, 0
	v_readlane_b32 s4, v250, 21
	v_lshl_or_b32 v0, v1, 6, v0
	s_add_i32 s64, 0, 0x10000
	s_add_i32 s65, 0, 0x14000
	v_add_u32_e32 v180, s4, v2
	s_ashr_i32 s21, s42, 31
	s_mov_b32 s20, s42
	v_mov_b32_e32 v163, v161
	v_lshl_add_u32 v164, v14, 1, v0
	v_mov_b32_e32 v165, v161
	v_mov_b64_e32 v[166:167], 0x200
	v_mov_b64_e32 v[168:169], 0x1ff
	v_add_u32_e32 v182, s64, v179
	v_add_u32_e32 v183, s65, v179
	v_add_u32_e32 v184, 0, v4
	v_mov_b32_e32 v185, 0x3e2aaaab
	s_mov_b32 s66, 0xbd75c28f
	v_mov_b32_e32 v170, 0x44b8aa3b
	s_barrier
	s_branch .LBB0_260

; #define PG8_STAGE(bufoff, gbase, voff) do { _Pragma("unroll") for (int _i = 0; _i < 2; ++_i) \
;         __builtin_amdgcn_global_load_lds((const unsigned*)((const char*)(gbase) + (voff)[_i]), (PG8_LAS unsigned*)(lds + (bufoff) + ldsw + _i * 8192), 16, 0, 0); } while (0)
; #define PG8_LDA(dst, b, h) do { _Pragma("unroll") for (int m = 0; m < 4; ++m) _Pragma("unroll") for (int k = 0; k < 2; ++k) dst[m][k] = *(const PG8_LAS bf16x8*)(lds + PG8_SA(b, h) + aoff + m * 2048 + k * 1024); } while (0)
; #define PG8_LDB(dst, b, h) do { _Pragma("unroll") for (int n = 0; n < 2; ++n) _Pragma("unroll") for (int k = 0; k < 2; ++k) dst[n][k] = *(const PG8_LAS bf16x8*)(lds + PG8_SB(b, h) + boff + n * 2048 + k * 1024); } while (0)
; #define PG8_MMA(ai, bj, At, Bt) do { __builtin_amdgcn_s_setprio(1); _Pragma("unroll") for (int m = 0; m < 4; ++m) _Pragma("unroll") for (int n = 0; n < 2; ++n) _Pragma("unroll") for (int k = 0; k < 2; ++k) \
;         acc[ai][bj][m][n] = __builtin_amdgcn_mfma_f32_16x16x32_bf16(Bt[n][k], At[m][k], acc[ai][bj][m][n], 0, 0, 0); __builtin_amdgcn_s_setprio(0); } while (0)
; #define PG8_WAIT_V(n) asm volatile("s_waitcnt vmcnt(" #n ")" ::: "memory")
; #define PG8_WAIT_L(n) asm volatile("s_waitcnt lgkmcnt(" #n ")" ::: "memory")
; template <class Epi, class Sched, bool ALIGN_EPI = false, bool SP2 = false>
; __device__ __forceinline__ void gemm_phase(PG8_LAS unsigned char* lds, const Gemm g, const Sched& S, const Epi& E, const int wid) {
;     ...
;             const bool last = (t == nt - 2);
;             const char* a1 = cA + (size_t)(t + 1) * kstep;
;             const char* a2 = last ? nA : cA + (size_t)(t + 2) * kstep; const char* b2 = last ? nB : cB + (size_t)(t + 2) * kstep;
;             const char* a3 = a2 + kstep; const char* b3 = b2 + kstep;
;             if (last && has_next) S.a_ready(nxt);
;             if constexpr (SP2) {
;             PG8_LDB(B0, 0, 0); PG8_LDB(B1, 0, 1); PG8_SCHED; PG8_LDA(At, 0, 0); PG8_STAGE(PG8_SA(1, 1), a1 + hstepA, voffA);
;             PG8_WAIT_V(8); PG8_WAIT_L(0); PG8_BAR; PG8_MMA(0, 0, At, B0); PG8_MMA(0, 1, At, B1); PG8_BAR; PG8_SCHED;
;             PG8_LDA(At, 0, 1); PG8_STAGE(PG8_SB(0, 0), b2, voffB); PG8_STAGE(PG8_SB(0, 1), b2 + hstepB, voffB); PG8_STAGE(PG8_SA(0, 0), a2, voffA);
;             PG8_WAIT_V(8); PG8_WAIT_L(0); PG8_BAR; PG8_MMA(1, 0, At, B0); PG8_MMA(1, 1, At, B1); PG8_BAR; PG8_SCHED;
.LBB0_270:
	ds_read_b128 v[60:63], v182
	ds_read_b128 v[68:71], v182 offset:1024
	ds_read_b128 v[72:75], v182 offset:2048
	ds_read_b128 v[76:79], v182 offset:3072
	ds_read_b128 v[80:83], v183
	ds_read_b128 v[84:87], v183 offset:1024
	ds_read_b128 v[172:175], v183 offset:2048
	ds_read_b128 v[186:189], v183 offset:3072
	s_add_i32 s68, s46, 2
	s_add_u32 s47, s44, 0xfffc0080
	s_addc_u32 s48, s45, -1
	s_cmp_eq_u32 s63, s46
	s_cselect_b32 s46, s6, s35
	s_cselect_b32 s49, s39, s48
	s_cselect_b32 s48, s38, s47
	s_cselect_b32 s47, s7, s37
	v_lshl_add_u64 v[176:177], s[44:45], 0, v[162:163]
	s_add_i32 m0, s41, 0xc000
	ds_read_b128 v[190:193], v184
	ds_read_b128 v[194:197], v184 offset:1024
	ds_read_b128 v[198:201], v184 offset:2048
	ds_read_b128 v[202:205], v184 offset:3072
	ds_read_b128 v[206:209], v184 offset:4096
	ds_read_b128 v[210:213], v184 offset:5120
	ds_read_b128 v[214:217], v184 offset:6144
	ds_read_b128 v[218:221], v184 offset:7168
	global_load_lds_dwordx4 v[176:177], off
	v_lshl_add_u64 v[176:177], s[44:45], 0, v[164:165]
	s_add_i32 m0, s41, 0xe000
	s_nop 0
	global_load_lds_dwordx4 v[176:177], off
	s_waitcnt vmcnt(8)
	s_waitcnt lgkmcnt(0)
	s_setprio 1
	s_barrier
	v_mfma_f32_16x16x32_bf16 v[148:151], v[60:63], v[190:193], v[148:151]
	v_mfma_f32_16x16x32_bf16 v[140:143], v[72:75], v[190:193], v[140:143]
	v_mfma_f32_16x16x32_bf16 v[132:135], v[60:63], v[198:201], v[132:135]
	v_mfma_f32_16x16x32_bf16 v[124:127], v[72:75], v[198:201], v[124:127]
	v_mfma_f32_16x16x32_bf16 v[116:119], v[60:63], v[206:209], v[116:119]
	v_mfma_f32_16x16x32_bf16 v[108:111], v[72:75], v[206:209], v[108:111]
	v_mfma_f32_16x16x32_bf16 v[100:103], v[60:63], v[214:217], v[100:103]
	v_mfma_f32_16x16x32_bf16 v[92:95], v[72:75], v[214:217], v[92:95]
	v_mfma_f32_16x16x32_bf16 v[148:151], v[68:71], v[194:197], v[148:151]
	v_mfma_f32_16x16x32_bf16 v[140:143], v[76:79], v[194:197], v[140:143]
	v_mfma_f32_16x16x32_bf16 v[132:135], v[68:71], v[202:205], v[132:135]
	v_mfma_f32_16x16x32_bf16 v[124:127], v[76:79], v[202:205], v[124:127]
	v_mfma_f32_16x16x32_bf16 v[116:119], v[68:71], v[210:213], v[116:119]
	v_mfma_f32_16x16x32_bf16 v[108:111], v[76:79], v[210:213], v[108:111]
	v_mfma_f32_16x16x32_bf16 v[100:103], v[68:71], v[218:221], v[100:103]
	v_mfma_f32_16x16x32_bf16 v[92:95], v[76:79], v[218:221], v[92:95]
	s_setprio 0
	s_setprio 1
	v_mfma_f32_16x16x32_bf16 v[144:147], v[80:83], v[190:193], v[144:147]
	v_mfma_f32_16x16x32_bf16 v[136:139], v[172:175], v[190:193], v[136:139]
	v_mfma_f32_16x16x32_bf16 v[128:131], v[80:83], v[198:201], v[128:131]
	v_mfma_f32_16x16x32_bf16 v[120:123], v[172:175], v[198:201], v[120:123]
	v_mfma_f32_16x16x32_bf16 v[112:115], v[80:83], v[206:209], v[112:115]
	v_mfma_f32_16x16x32_bf16 v[104:107], v[172:175], v[206:209], v[104:107]
	v_mfma_f32_16x16x32_bf16 v[96:99], v[80:83], v[214:217], v[96:99]
	v_mfma_f32_16x16x32_bf16 v[88:91], v[172:175], v[214:217], v[88:91]
	v_mfma_f32_16x16x32_bf16 v[144:147], v[84:87], v[194:197], v[144:147]
	v_mfma_f32_16x16x32_bf16 v[136:139], v[186:189], v[194:197], v[136:139]
	v_mfma_f32_16x16x32_bf16 v[128:131], v[84:87], v[202:205], v[128:131]
	v_mfma_f32_16x16x32_bf16 v[120:123], v[186:189], v[202:205], v[120:123]
	v_mfma_f32_16x16x32_bf16 v[112:115], v[84:87], v[210:213], v[112:115]
	v_mfma_f32_16x16x32_bf16 v[104:107], v[186:189], v[210:213], v[104:107]
	v_mfma_f32_16x16x32_bf16 v[96:99], v[84:87], v[218:221], v[96:99]
	v_mfma_f32_16x16x32_bf16 v[88:91], v[186:189], v[218:221], v[88:91]
	s_barrier
	s_setprio 0
	s_add_i32 s69, s64, s0
	v_lshl_add_u64 v[176:177], s[46:47], 0, v[154:155]
	s_mov_b32 m0, s69
	ds_read_b128 v[190:193], v184 offset:16384
	ds_read_b128 v[194:197], v184 offset:17408
	ds_read_b128 v[198:201], v184 offset:18432
	ds_read_b128 v[202:205], v184 offset:19456
	ds_read_b128 v[206:209], v184 offset:20480
	ds_read_b128 v[210:213], v184 offset:21504
	ds_read_b128 v[214:217], v184 offset:22528
	ds_read_b128 v[218:221], v184 offset:23552
	global_load_lds_dwordx4 v[176:177], off
	s_add_i32 m0, s69, 0x2000
	s_add_u32 s70, s46, 0x10000
	v_lshl_add_u64 v[222:223], s[46:47], 0, v[158:159]
	s_addc_u32 s71, s47, 0
	s_add_i32 s69, s65, s0
	global_load_lds_dwordx4 v[222:223], off
	v_lshl_add_u64 v[224:225], s[70:71], 0, v[154:155]
	s_mov_b32 m0, s69
	v_lshl_add_u64 v[226:227], s[48:49], 0, v[156:157]
	global_load_lds_dwordx4 v[224:225], off
	v_lshl_add_u64 v[224:225], s[70:71], 0, v[158:159]
	s_add_i32 m0, s69, 0x2000
	s_nop 0
	global_load_lds_dwordx4 v[224:225], off
	v_lshl_add_u64 v[224:225], s[48:49], 0, v[152:153]
	s_mov_b32 m0, s41
	s_nop 0
	global_load_lds_dwordx4 v[224:225], off
	s_mov_b32 m0, s57
	s_nop 0
	global_load_lds_dwordx4 v[226:227], off
	s_waitcnt vmcnt(8)
	s_waitcnt lgkmcnt(0)
	s_setprio 1
	s_barrier
; #define PG8_STAGE(bufoff, gbase, voff) do { _Pragma("unroll") for (int _i = 0; _i < 2; ++_i) \
;         __builtin_amdgcn_global_load_lds((const unsigned*)((const char*)(gbase) + (voff)[_i]), (PG8_LAS unsigned*)(lds + (bufoff) + ldsw + _i * 8192), 16, 0, 0); } while (0)
; #define PG8_LDA(dst, b, h) do { _Pragma("unroll") for (int m = 0; m < 4; ++m) _Pragma("unroll") for (int k = 0; k < 2; ++k) dst[m][k] = *(const PG8_LAS bf16x8*)(lds + PG8_SA(b, h) + aoff + m * 2048 + k * 1024); } while (0)
; #define PG8_LDB(dst, b, h) do { _Pragma("unroll") for (int n = 0; n < 2; ++n) _Pragma("unroll") for (int k = 0; k < 2; ++k) dst[n][k] = *(const PG8_LAS bf16x8*)(lds + PG8_SB(b, h) + boff + n * 2048 + k * 1024); } while (0)
; #define PG8_MMA(ai, bj, At, Bt) do { __builtin_amdgcn_s_setprio(1); _Pragma("unroll") for (int m = 0; m < 4; ++m) _Pragma("unroll") for (int n = 0; n < 2; ++n) _Pragma("unroll") for (int k = 0; k < 2; ++k) \
;         acc[ai][bj][m][n] = __builtin_amdgcn_mfma_f32_16x16x32_bf16(Bt[n][k], At[m][k], acc[ai][bj][m][n], 0, 0, 0); __builtin_amdgcn_s_setprio(0); } while (0)
; #define PG8_WAIT_V(n) asm volatile("s_waitcnt vmcnt(" #n ")" ::: "memory")
; #define PG8_WAIT_L(n) asm volatile("s_waitcnt lgkmcnt(" #n ")" ::: "memory")
; #define PG8_BAR __builtin_amdgcn_s_barrier()
; #define PG8_SCHED __builtin_amdgcn_sched_barrier(0)
; template <class Epi, class Sched, bool ALIGN_EPI = false, bool SP2 = false>
; __device__ __forceinline__ void gemm_phase(PG8_LAS unsigned char* lds, const Gemm g, const Sched& S, const Epi& E, const int wid) {
;     ...
;             PG8_WAIT_V(8); PG8_WAIT_L(0); PG8_BAR; PG8_MMA(1, 0, At, B0); PG8_MMA(1, 1, At, B1); PG8_BAR; PG8_SCHED;
;             PG8_LDB(B0, 1, 0); PG8_LDB(B1, 1, 1); PG8_SCHED; PG8_LDA(At, 1, 0); PG8_STAGE(PG8_SA(0, 1), a2 + hstepA, voffA);
;             PG8_WAIT_V(8); PG8_WAIT_L(0); PG8_BAR; PG8_MMA(0, 0, At, B0); PG8_MMA(0, 1, At, B1); PG8_BAR; PG8_SCHED;
	v_mfma_f32_16x16x32_bf16 v[64:67], v[60:63], v[190:193], v[64:67]
	v_mfma_f32_16x16x32_bf16 v[52:55], v[72:75], v[190:193], v[52:55]
	v_mfma_f32_16x16x32_bf16 v[44:47], v[60:63], v[198:201], v[44:47]
	v_mfma_f32_16x16x32_bf16 v[36:39], v[72:75], v[198:201], v[36:39]
	v_mfma_f32_16x16x32_bf16 v[28:31], v[60:63], v[206:209], v[28:31]
	v_mfma_f32_16x16x32_bf16 v[20:23], v[72:75], v[206:209], v[20:23]
	v_mfma_f32_16x16x32_bf16 v[12:15], v[60:63], v[214:217], v[12:15]
	v_mfma_f32_16x16x32_bf16 v[4:7], v[72:75], v[214:217], v[4:7]
	v_mfma_f32_16x16x32_bf16 v[64:67], v[68:71], v[194:197], v[64:67]
	v_mfma_f32_16x16x32_bf16 v[52:55], v[76:79], v[194:197], v[52:55]
	v_mfma_f32_16x16x32_bf16 v[44:47], v[68:71], v[202:205], v[44:47]
	v_mfma_f32_16x16x32_bf16 v[36:39], v[76:79], v[202:205], v[36:39]
	v_mfma_f32_16x16x32_bf16 v[28:31], v[68:71], v[210:213], v[28:31]
	v_mfma_f32_16x16x32_bf16 v[20:23], v[76:79], v[210:213], v[20:23]
	v_mfma_f32_16x16x32_bf16 v[12:15], v[68:71], v[218:221], v[12:15]
	v_mfma_f32_16x16x32_bf16 v[4:7], v[76:79], v[218:221], v[4:7]
	s_setprio 0
	s_setprio 1
	v_mfma_f32_16x16x32_bf16 v[56:59], v[80:83], v[190:193], v[56:59]
	v_mfma_f32_16x16x32_bf16 v[48:51], v[172:175], v[190:193], v[48:51]
	v_mfma_f32_16x16x32_bf16 v[40:43], v[80:83], v[198:201], v[40:43]
	v_mfma_f32_16x16x32_bf16 v[32:35], v[172:175], v[198:201], v[32:35]
	v_mfma_f32_16x16x32_bf16 v[24:27], v[80:83], v[206:209], v[24:27]
	v_mfma_f32_16x16x32_bf16 v[16:19], v[172:175], v[206:209], v[16:19]
	v_mfma_f32_16x16x32_bf16 v[8:11], v[80:83], v[214:217], v[8:11]
	v_mfma_f32_16x16x32_bf16 v[0:3], v[172:175], v[214:217], v[0:3]
	v_mfma_f32_16x16x32_bf16 v[56:59], v[84:87], v[194:197], v[56:59]
	v_mfma_f32_16x16x32_bf16 v[48:51], v[186:189], v[194:197], v[48:51]
	v_mfma_f32_16x16x32_bf16 v[40:43], v[84:87], v[202:205], v[40:43]
	v_mfma_f32_16x16x32_bf16 v[32:35], v[186:189], v[202:205], v[32:35]
	v_mfma_f32_16x16x32_bf16 v[24:27], v[84:87], v[210:213], v[24:27]
	v_mfma_f32_16x16x32_bf16 v[16:19], v[186:189], v[210:213], v[16:19]
	v_mfma_f32_16x16x32_bf16 v[8:11], v[84:87], v[218:221], v[8:11]
	v_mfma_f32_16x16x32_bf16 v[0:3], v[186:189], v[218:221], v[0:3]
	s_barrier
	s_setprio 0
	s_add_i32 s69, 0, 0x18000
	s_add_i32 s70, 0, 0x1c000
	v_add_u32_e32 v76, s69, v179
	v_add_u32_e32 v160, s70, v179
	ds_read_b128 v[60:63], v76
	ds_read_b128 v[68:71], v76 offset:1024
	ds_read_b128 v[72:75], v76 offset:2048
	ds_read_b128 v[76:79], v76 offset:3072
	ds_read_b128 v[80:83], v160
	ds_read_b128 v[84:87], v160 offset:1024
	ds_read_b128 v[172:175], v160 offset:2048
	ds_read_b128 v[186:189], v160 offset:3072
	s_add_u32 s48, s48, 0x40000
	s_addc_u32 s49, s49, 0
	s_mov_b32 m0, s58
	v_lshl_add_u64 v[228:229], s[48:49], 0, v[152:153]
	ds_read_b128 v[190:193], v184 offset:32768
	ds_read_b128 v[194:197], v184 offset:33792
	ds_read_b128 v[198:201], v184 offset:34816
	ds_read_b128 v[202:205], v184 offset:35840
	ds_read_b128 v[206:209], v184 offset:36864
	ds_read_b128 v[210:213], v184 offset:37888
	ds_read_b128 v[214:217], v184 offset:38912
	ds_read_b128 v[218:221], v184 offset:39936
	global_load_lds_dwordx4 v[228:229], off
	v_lshl_add_u64 v[228:229], s[48:49], 0, v[156:157]
	s_mov_b32 m0, s59
	s_nop 0
	global_load_lds_dwordx4 v[228:229], off
	s_waitcnt vmcnt(8)
	s_waitcnt lgkmcnt(0)
	s_setprio 1
	s_barrier
	v_mfma_f32_16x16x32_bf16 v[148:151], v[60:63], v[190:193], v[148:151]
	v_mfma_f32_16x16x32_bf16 v[140:143], v[72:75], v[190:193], v[140:143]
	v_mfma_f32_16x16x32_bf16 v[132:135], v[60:63], v[198:201], v[132:135]
	v_mfma_f32_16x16x32_bf16 v[124:127], v[72:75], v[198:201], v[124:127]
	v_mfma_f32_16x16x32_bf16 v[116:119], v[60:63], v[206:209], v[116:119]
	v_mfma_f32_16x16x32_bf16 v[108:111], v[72:75], v[206:209], v[108:111]
	v_mfma_f32_16x16x32_bf16 v[100:103], v[60:63], v[214:217], v[100:103]
	v_mfma_f32_16x16x32_bf16 v[92:95], v[72:75], v[214:217], v[92:95]
	v_mfma_f32_16x16x32_bf16 v[148:151], v[68:71], v[194:197], v[148:151]
	v_mfma_f32_16x16x32_bf16 v[140:143], v[76:79], v[194:197], v[140:143]
	v_mfma_f32_16x16x32_bf16 v[132:135], v[68:71], v[202:205], v[132:135]
	v_mfma_f32_16x16x32_bf16 v[124:127], v[76:79], v[202:205], v[124:127]
	v_mfma_f32_16x16x32_bf16 v[116:119], v[68:71], v[210:213], v[116:119]
	v_mfma_f32_16x16x32_bf16 v[108:111], v[76:79], v[210:213], v[108:111]
	v_mfma_f32_16x16x32_bf16 v[100:103], v[68:71], v[218:221], v[100:103]
	v_mfma_f32_16x16x32_bf16 v[92:95], v[76:79], v[218:221], v[92:95]
	s_setprio 0
	s_setprio 1
	v_mfma_f32_16x16x32_bf16 v[144:147], v[80:83], v[190:193], v[144:147]
	v_mfma_f32_16x16x32_bf16 v[136:139], v[172:175], v[190:193], v[136:139]
	v_mfma_f32_16x16x32_bf16 v[128:131], v[80:83], v[198:201], v[128:131]
	v_mfma_f32_16x16x32_bf16 v[120:123], v[172:175], v[198:201], v[120:123]
	v_mfma_f32_16x16x32_bf16 v[112:115], v[80:83], v[206:209], v[112:115]
	v_mfma_f32_16x16x32_bf16 v[104:107], v[172:175], v[206:209], v[104:107]
	v_mfma_f32_16x16x32_bf16 v[96:99], v[80:83], v[214:217], v[96:99]
	v_mfma_f32_16x16x32_bf16 v[88:91], v[172:175], v[214:217], v[88:91]
	v_mfma_f32_16x16x32_bf16 v[144:147], v[84:87], v[194:197], v[144:147]
	v_mfma_f32_16x16x32_bf16 v[136:139], v[186:189], v[194:197], v[136:139]
	v_mfma_f32_16x16x32_bf16 v[128:131], v[84:87], v[202:205], v[128:131]
	v_mfma_f32_16x16x32_bf16 v[120:123], v[186:189], v[202:205], v[120:123]
	v_mfma_f32_16x16x32_bf16 v[112:115], v[84:87], v[210:213], v[112:115]
	v_mfma_f32_16x16x32_bf16 v[104:107], v[186:189], v[210:213], v[104:107]
	v_mfma_f32_16x16x32_bf16 v[96:99], v[84:87], v[218:221], v[96:99]
	v_mfma_f32_16x16x32_bf16 v[88:91], v[186:189], v[218:221], v[88:91]
	s_barrier
; #define PG8_STAGE(bufoff, gbase, voff) do { _Pragma("unroll") for (int _i = 0; _i < 2; ++_i) \
;         __builtin_amdgcn_global_load_lds((const unsigned*)((const char*)(gbase) + (voff)[_i]), (PG8_LAS unsigned*)(lds + (bufoff) + ldsw + _i * 8192), 16, 0, 0); } while (0)
; #define PG8_LDA(dst, b, h) do { _Pragma("unroll") for (int m = 0; m < 4; ++m) _Pragma("unroll") for (int k = 0; k < 2; ++k) dst[m][k] = *(const PG8_LAS bf16x8*)(lds + PG8_SA(b, h) + aoff + m * 2048 + k * 1024); } while (0)
; #define PG8_MMA(ai, bj, At, Bt) do { __builtin_amdgcn_s_setprio(1); _Pragma("unroll") for (int m = 0; m < 4; ++m) _Pragma("unroll") for (int n = 0; n < 2; ++n) _Pragma("unroll") for (int k = 0; k < 2; ++k) \
;         acc[ai][bj][m][n] = __builtin_amdgcn_mfma_f32_16x16x32_bf16(Bt[n][k], At[m][k], acc[ai][bj][m][n], 0, 0, 0); __builtin_amdgcn_s_setprio(0); } while (0)
; #define PG8_WAIT_V(n) asm volatile("s_waitcnt vmcnt(" #n ")" ::: "memory")
; #define PG8_WAIT_L(n) asm volatile("s_waitcnt lgkmcnt(" #n ")" ::: "memory")
; #define PG8_BAR __builtin_amdgcn_s_barrier()
; #define PG8_SCHED __builtin_amdgcn_sched_barrier(0)
; template <class Epi, class Sched, bool ALIGN_EPI = false, bool SP2 = false>
; __device__ __forceinline__ void gemm_phase(PG8_LAS unsigned char* lds, const Gemm g, const Sched& S, const Epi& E, const int wid) {
;     ...
;             PG8_LDA(At, 1, 1); PG8_STAGE(PG8_SB(1, 0), b3, voffB); PG8_STAGE(PG8_SB(1, 1), b3 + hstepB, voffB); PG8_STAGE(PG8_SA(1, 0), a3, voffA);
;             PG8_WAIT_V(8); PG8_WAIT_L(0); PG8_BAR; PG8_MMA(1, 0, At, B0); PG8_MMA(1, 1, At, B1); PG8_BAR; PG8_SCHED;
	s_setprio 0
	s_add_i32 s48, s69, s0
	v_lshl_add_u64 v[176:177], v[176:177], 0, s[22:23]
	s_mov_b32 m0, s48
	ds_read_b128 v[190:193], v184 offset:49152
	ds_read_b128 v[194:197], v184 offset:50176
	ds_read_b128 v[198:201], v184 offset:51200
	ds_read_b128 v[202:205], v184 offset:52224
	ds_read_b128 v[206:209], v184 offset:53248
	ds_read_b128 v[210:213], v184 offset:54272
	ds_read_b128 v[214:217], v184 offset:55296
	ds_read_b128 v[218:221], v184 offset:56320
	global_load_lds_dwordx4 v[176:177], off
	s_add_i32 m0, s48, 0x2000
	s_add_u32 s46, s46, 0x10080
	v_lshl_add_u64 v[176:177], v[222:223], 0, s[22:23]
	s_addc_u32 s47, s47, 0
	s_add_i32 s48, s70, s0
	global_load_lds_dwordx4 v[176:177], off
	v_lshl_add_u64 v[176:177], s[46:47], 0, v[154:155]
	s_mov_b32 m0, s48
	s_nop 0
	global_load_lds_dwordx4 v[176:177], off
	v_lshl_add_u64 v[176:177], s[46:47], 0, v[158:159]
	s_add_i32 m0, s48, 0x2000
	s_nop 0
	global_load_lds_dwordx4 v[176:177], off
	v_lshl_add_u64 v[176:177], v[224:225], 0, s[22:23]
	s_mov_b32 m0, s61
	s_nop 0
	global_load_lds_dwordx4 v[176:177], off
	v_lshl_add_u64 v[176:177], v[226:227], 0, s[22:23]
	s_mov_b32 m0, s62
	s_nop 0
	global_load_lds_dwordx4 v[176:177], off
	s_waitcnt vmcnt(8)
	s_waitcnt lgkmcnt(0)
	s_setprio 1
	s_barrier
	v_mfma_f32_16x16x32_bf16 v[64:67], v[60:63], v[190:193], v[64:67]
	v_mfma_f32_16x16x32_bf16 v[52:55], v[72:75], v[190:193], v[52:55]
	v_mfma_f32_16x16x32_bf16 v[44:47], v[60:63], v[198:201], v[44:47]
	v_mfma_f32_16x16x32_bf16 v[36:39], v[72:75], v[198:201], v[36:39]
	v_mfma_f32_16x16x32_bf16 v[28:31], v[60:63], v[206:209], v[28:31]
	v_mfma_f32_16x16x32_bf16 v[20:23], v[72:75], v[206:209], v[20:23]
	v_mfma_f32_16x16x32_bf16 v[12:15], v[60:63], v[214:217], v[12:15]
	v_mfma_f32_16x16x32_bf16 v[4:7], v[72:75], v[214:217], v[4:7]
	v_mfma_f32_16x16x32_bf16 v[64:67], v[68:71], v[194:197], v[64:67]
	v_mfma_f32_16x16x32_bf16 v[52:55], v[76:79], v[194:197], v[52:55]
	v_mfma_f32_16x16x32_bf16 v[44:47], v[68:71], v[202:205], v[44:47]
	v_mfma_f32_16x16x32_bf16 v[36:39], v[76:79], v[202:205], v[36:39]
	v_mfma_f32_16x16x32_bf16 v[28:31], v[68:71], v[210:213], v[28:31]
	v_mfma_f32_16x16x32_bf16 v[20:23], v[76:79], v[210:213], v[20:23]
	v_mfma_f32_16x16x32_bf16 v[12:15], v[68:71], v[218:221], v[12:15]
	v_mfma_f32_16x16x32_bf16 v[4:7], v[76:79], v[218:221], v[4:7]
	s_setprio 0
	s_setprio 1
	v_mfma_f32_16x16x32_bf16 v[56:59], v[80:83], v[190:193], v[56:59]
	v_mfma_f32_16x16x32_bf16 v[48:51], v[172:175], v[190:193], v[48:51]
	v_mfma_f32_16x16x32_bf16 v[40:43], v[80:83], v[198:201], v[40:43]
	v_mfma_f32_16x16x32_bf16 v[32:35], v[172:175], v[198:201], v[32:35]
	v_mfma_f32_16x16x32_bf16 v[24:27], v[80:83], v[206:209], v[24:27]
	v_mfma_f32_16x16x32_bf16 v[16:19], v[172:175], v[206:209], v[16:19]
	v_mfma_f32_16x16x32_bf16 v[8:11], v[80:83], v[214:217], v[8:11]
	v_mfma_f32_16x16x32_bf16 v[0:3], v[172:175], v[214:217], v[0:3]
	v_mfma_f32_16x16x32_bf16 v[56:59], v[84:87], v[194:197], v[56:59]
	v_mfma_f32_16x16x32_bf16 v[48:51], v[186:189], v[194:197], v[48:51]
	v_mfma_f32_16x16x32_bf16 v[40:43], v[84:87], v[202:205], v[40:43]
	v_mfma_f32_16x16x32_bf16 v[32:35], v[186:189], v[202:205], v[32:35]
	v_mfma_f32_16x16x32_bf16 v[24:27], v[84:87], v[210:213], v[24:27]
	v_mfma_f32_16x16x32_bf16 v[16:19], v[186:189], v[210:213], v[16:19]
	v_mfma_f32_16x16x32_bf16 v[8:11], v[84:87], v[218:221], v[8:11]
	v_mfma_f32_16x16x32_bf16 v[0:3], v[186:189], v[218:221], v[0:3]
	s_barrier
	s_setprio 0
	s_add_u32 s44, s44, 0x100
	s_addc_u32 s45, s45, 0
	s_add_u32 s35, s35, 0x100
	s_addc_u32 s37, s37, 0
	s_cmp_ge_i32 s68, s54
	s_mov_b32 s46, s68
	s_cbranch_scc0 .LBB0_270
	s_and_b64 vcc, exec, s[30:31]
	s_cbranch_vccz .LBB0_273

; #define PG8_STAGE(bufoff, gbase, voff) do { _Pragma("unroll") for (int _i = 0; _i < 2; ++_i) \
;         __builtin_amdgcn_global_load_lds((const unsigned*)((const char*)(gbase) + (voff)[_i]), (PG8_LAS unsigned*)(lds + (bufoff) + ldsw + _i * 8192), 16, 0, 0); } while (0)
; #define PG8_LDA(dst, b, h) do { _Pragma("unroll") for (int m = 0; m < 4; ++m) _Pragma("unroll") for (int k = 0; k < 2; ++k) dst[m][k] = *(const PG8_LAS bf16x8*)(lds + PG8_SA(b, h) + aoff + m * 2048 + k * 1024); } while (0)
; #define PG8_LDB(dst, b, h) do { _Pragma("unroll") for (int n = 0; n < 2; ++n) _Pragma("unroll") for (int k = 0; k < 2; ++k) dst[n][k] = *(const PG8_LAS bf16x8*)(lds + PG8_SB(b, h) + boff + n * 2048 + k * 1024); } while (0)
; #define PG8_MMA(ai, bj, At, Bt) do { __builtin_amdgcn_s_setprio(1); _Pragma("unroll") for (int m = 0; m < 4; ++m) _Pragma("unroll") for (int n = 0; n < 2; ++n) _Pragma("unroll") for (int k = 0; k < 2; ++k) \
;         acc[ai][bj][m][n] = __builtin_amdgcn_mfma_f32_16x16x32_bf16(Bt[n][k], At[m][k], acc[ai][bj][m][n], 0, 0, 0); __builtin_amdgcn_s_setprio(0); } while (0)
; #define PG8_WAIT_V(n) asm volatile("s_waitcnt vmcnt(" #n ")" ::: "memory")
; #define PG8_WAIT_L(n) asm volatile("s_waitcnt lgkmcnt(" #n ")" ::: "memory")
; template <class Epi, class Sched, bool ALIGN_EPI = false, bool SP2 = false>
; __device__ __forceinline__ void gemm_phase(PG8_LAS unsigned char* lds, const Gemm g, const Sched& S, const Epi& E, const int wid) {
;     ...
;             const bool last = (t == nt - 2);
;             const char* a1 = cA + (size_t)(t + 1) * kstep;
;             const char* a2 = last ? nA : cA + (size_t)(t + 2) * kstep; const char* b2 = last ? nB : cB + (size_t)(t + 2) * kstep;
;             const char* a3 = a2 + kstep; const char* b3 = b2 + kstep;
;             if (last && has_next) S.a_ready(nxt);
;             if constexpr (SP2) {
;             PG8_LDB(B0, 0, 0); PG8_LDB(B1, 0, 1); PG8_SCHED; PG8_LDA(At, 0, 0); PG8_STAGE(PG8_SA(1, 1), a1 + hstepA, voffA);
;             PG8_WAIT_V(8); PG8_WAIT_L(0); PG8_BAR; PG8_MMA(0, 0, At, B0); PG8_MMA(0, 1, At, B1); PG8_BAR; PG8_SCHED;
;             PG8_LDA(At, 0, 1); PG8_STAGE(PG8_SB(0, 0), b2, voffB); PG8_STAGE(PG8_SB(0, 1), b2 + hstepB, voffB); PG8_STAGE(PG8_SA(0, 0), a2, voffA);
;             PG8_WAIT_V(8); PG8_WAIT_L(0); PG8_BAR; PG8_MMA(1, 0, At, B0); PG8_MMA(1, 1, At, B1); PG8_BAR; PG8_SCHED;
.LBB0_405:
	v_add_u32_e32 v162, s62, v148
	v_add_u32_e32 v179, s63, v148
	ds_read_b128 v[150:153], v162
	ds_read_b128 v[154:157], v162 offset:1024
	ds_read_b128 v[158:161], v162 offset:2048
	ds_read_b128 v[162:165], v162 offset:3072
	ds_read_b128 v[166:169], v179
	ds_read_b128 v[170:173], v179 offset:1024
	ds_read_b128 v[174:177], v179 offset:2048
	ds_read_b128 v[180:183], v179 offset:3072
	s_add_i32 s65, s44, 2
	s_add_u32 s45, s40, 0xfffc0080
	s_addc_u32 s46, s41, -1
	s_cmp_eq_u32 s61, s44
	s_cselect_b32 s44, s38, s31
	s_cselect_b32 s47, s37, s46
	s_cselect_b32 s46, s36, s45
	s_cselect_b32 s45, s39, s35
	v_lshl_add_u64 v[216:217], s[40:41], 0, v[136:137]
	s_add_i32 m0, s11, 0xc000
	ds_read_b128 v[184:187], v149
	ds_read_b128 v[188:191], v149 offset:1024
	ds_read_b128 v[192:195], v149 offset:2048
	ds_read_b128 v[196:199], v149 offset:3072
	ds_read_b128 v[200:203], v149 offset:4096
	ds_read_b128 v[204:207], v149 offset:5120
	ds_read_b128 v[208:211], v149 offset:6144
	ds_read_b128 v[212:215], v149 offset:7168
	global_load_lds_dwordx4 v[216:217], off
	v_lshl_add_u64 v[216:217], s[40:41], 0, v[138:139]
	s_add_i32 m0, s11, 0xe000
	s_nop 0
	global_load_lds_dwordx4 v[216:217], off
	s_waitcnt vmcnt(8)
	s_waitcnt lgkmcnt(0)
	s_setprio 1
	s_barrier
	v_mfma_f32_16x16x32_bf16 v[124:127], v[150:153], v[184:187], v[124:127]
	v_mfma_f32_16x16x32_bf16 v[120:123], v[158:161], v[184:187], v[120:123]
	v_mfma_f32_16x16x32_bf16 v[108:111], v[150:153], v[192:195], v[108:111]
	v_mfma_f32_16x16x32_bf16 v[104:107], v[158:161], v[192:195], v[104:107]
	v_mfma_f32_16x16x32_bf16 v[100:103], v[150:153], v[200:203], v[100:103]
	v_mfma_f32_16x16x32_bf16 v[92:95], v[158:161], v[200:203], v[92:95]
	v_mfma_f32_16x16x32_bf16 v[84:87], v[150:153], v[208:211], v[84:87]
	v_mfma_f32_16x16x32_bf16 v[76:79], v[158:161], v[208:211], v[76:79]
	v_mfma_f32_16x16x32_bf16 v[124:127], v[154:157], v[188:191], v[124:127]
	v_mfma_f32_16x16x32_bf16 v[120:123], v[162:165], v[188:191], v[120:123]
	v_mfma_f32_16x16x32_bf16 v[108:111], v[154:157], v[196:199], v[108:111]
	v_mfma_f32_16x16x32_bf16 v[104:107], v[162:165], v[196:199], v[104:107]
	v_mfma_f32_16x16x32_bf16 v[100:103], v[154:157], v[204:207], v[100:103]
	v_mfma_f32_16x16x32_bf16 v[92:95], v[162:165], v[204:207], v[92:95]
	v_mfma_f32_16x16x32_bf16 v[84:87], v[154:157], v[212:215], v[84:87]
	v_mfma_f32_16x16x32_bf16 v[76:79], v[162:165], v[212:215], v[76:79]
	s_setprio 0
	s_setprio 1
	v_mfma_f32_16x16x32_bf16 v[116:119], v[166:169], v[184:187], v[116:119]
	v_mfma_f32_16x16x32_bf16 v[112:115], v[174:177], v[184:187], v[112:115]
	v_mfma_f32_16x16x32_bf16 v[96:99], v[166:169], v[192:195], v[96:99]
	v_mfma_f32_16x16x32_bf16 v[88:91], v[174:177], v[192:195], v[88:91]
	v_mfma_f32_16x16x32_bf16 v[80:83], v[166:169], v[200:203], v[80:83]
	v_mfma_f32_16x16x32_bf16 v[72:75], v[174:177], v[200:203], v[72:75]
	v_mfma_f32_16x16x32_bf16 v[68:71], v[166:169], v[208:211], v[68:71]
	v_mfma_f32_16x16x32_bf16 v[64:67], v[174:177], v[208:211], v[64:67]
	v_mfma_f32_16x16x32_bf16 v[116:119], v[170:173], v[188:191], v[116:119]
	v_mfma_f32_16x16x32_bf16 v[112:115], v[180:183], v[188:191], v[112:115]
	v_mfma_f32_16x16x32_bf16 v[96:99], v[170:173], v[196:199], v[96:99]
	v_mfma_f32_16x16x32_bf16 v[88:91], v[180:183], v[196:199], v[88:91]
	v_mfma_f32_16x16x32_bf16 v[80:83], v[170:173], v[204:207], v[80:83]
	v_mfma_f32_16x16x32_bf16 v[72:75], v[180:183], v[204:207], v[72:75]
	v_mfma_f32_16x16x32_bf16 v[68:71], v[170:173], v[212:215], v[68:71]
	v_mfma_f32_16x16x32_bf16 v[64:67], v[180:183], v[212:215], v[64:67]
	s_barrier
	s_setprio 0
	s_add_i32 s66, s62, s0
	v_lshl_add_u64 v[216:217], s[44:45], 0, v[134:135]
	s_mov_b32 m0, s66
	ds_read_b128 v[184:187], v149 offset:16384
	ds_read_b128 v[188:191], v149 offset:17408
	ds_read_b128 v[192:195], v149 offset:18432
	ds_read_b128 v[196:199], v149 offset:19456
	ds_read_b128 v[200:203], v149 offset:20480
	ds_read_b128 v[204:207], v149 offset:21504
	ds_read_b128 v[208:211], v149 offset:22528
	ds_read_b128 v[212:215], v149 offset:23552
	global_load_lds_dwordx4 v[216:217], off
	s_add_i32 m0, s66, 0x2000
	s_add_u32 s66, s44, 0x40000
	v_lshl_add_u64 v[218:219], s[44:45], 0, v[132:133]
	s_addc_u32 s67, s45, 0
	s_add_i32 s68, s63, s0
	global_load_lds_dwordx4 v[218:219], off
	v_lshl_add_u64 v[220:221], s[66:67], 0, v[134:135]
	s_mov_b32 m0, s68
	v_lshl_add_u64 v[222:223], s[46:47], 0, v[130:131]
	global_load_lds_dwordx4 v[220:221], off
	v_lshl_add_u64 v[220:221], s[66:67], 0, v[132:133]
	s_add_i32 m0, s68, 0x2000
	s_nop 0
	global_load_lds_dwordx4 v[220:221], off
	v_lshl_add_u64 v[220:221], s[46:47], 0, v[128:129]
	s_mov_b32 m0, s11
	s_nop 0
	global_load_lds_dwordx4 v[220:221], off
	s_mov_b32 m0, s55
	s_nop 0
	global_load_lds_dwordx4 v[222:223], off
	s_waitcnt vmcnt(8)
	s_waitcnt lgkmcnt(0)
	s_setprio 1
	s_barrier
; #define PG8_STAGE(bufoff, gbase, voff) do { _Pragma("unroll") for (int _i = 0; _i < 2; ++_i) \
;         __builtin_amdgcn_global_load_lds((const unsigned*)((const char*)(gbase) + (voff)[_i]), (PG8_LAS unsigned*)(lds + (bufoff) + ldsw + _i * 8192), 16, 0, 0); } while (0)
; #define PG8_LDA(dst, b, h) do { _Pragma("unroll") for (int m = 0; m < 4; ++m) _Pragma("unroll") for (int k = 0; k < 2; ++k) dst[m][k] = *(const PG8_LAS bf16x8*)(lds + PG8_SA(b, h) + aoff + m * 2048 + k * 1024); } while (0)
; #define PG8_LDB(dst, b, h) do { _Pragma("unroll") for (int n = 0; n < 2; ++n) _Pragma("unroll") for (int k = 0; k < 2; ++k) dst[n][k] = *(const PG8_LAS bf16x8*)(lds + PG8_SB(b, h) + boff + n * 2048 + k * 1024); } while (0)
; #define PG8_MMA(ai, bj, At, Bt) do { __builtin_amdgcn_s_setprio(1); _Pragma("unroll") for (int m = 0; m < 4; ++m) _Pragma("unroll") for (int n = 0; n < 2; ++n) _Pragma("unroll") for (int k = 0; k < 2; ++k) \
;         acc[ai][bj][m][n] = __builtin_amdgcn_mfma_f32_16x16x32_bf16(Bt[n][k], At[m][k], acc[ai][bj][m][n], 0, 0, 0); __builtin_amdgcn_s_setprio(0); } while (0)
; #define PG8_WAIT_V(n) asm volatile("s_waitcnt vmcnt(" #n ")" ::: "memory")
; #define PG8_WAIT_L(n) asm volatile("s_waitcnt lgkmcnt(" #n ")" ::: "memory")
; #define PG8_BAR __builtin_amdgcn_s_barrier()
; #define PG8_SCHED __builtin_amdgcn_sched_barrier(0)
; template <class Epi, class Sched, bool ALIGN_EPI = false, bool SP2 = false>
; __device__ __forceinline__ void gemm_phase(PG8_LAS unsigned char* lds, const Gemm g, const Sched& S, const Epi& E, const int wid) {
;     ...
;             PG8_WAIT_V(8); PG8_WAIT_L(0); PG8_BAR; PG8_MMA(1, 0, At, B0); PG8_MMA(1, 1, At, B1); PG8_BAR; PG8_SCHED;
;             PG8_LDB(B0, 1, 0); PG8_LDB(B1, 1, 1); PG8_SCHED; PG8_LDA(At, 1, 0); PG8_STAGE(PG8_SA(0, 1), a2 + hstepA, voffA);
;             PG8_WAIT_V(8); PG8_WAIT_L(0); PG8_BAR; PG8_MMA(0, 0, At, B0); PG8_MMA(0, 1, At, B1); PG8_BAR; PG8_SCHED;
	v_mfma_f32_16x16x32_bf16 v[52:55], v[150:153], v[184:187], v[52:55]
	v_mfma_f32_16x16x32_bf16 v[40:43], v[158:161], v[184:187], v[40:43]
	v_mfma_f32_16x16x32_bf16 v[28:31], v[150:153], v[192:195], v[28:31]
	v_mfma_f32_16x16x32_bf16 v[12:15], v[158:161], v[192:195], v[12:15]
	v_mfma_f32_16x16x32_bf16 v[60:63], v[150:153], v[200:203], v[60:63]
	v_mfma_f32_16x16x32_bf16 v[48:51], v[158:161], v[200:203], v[48:51]
	v_mfma_f32_16x16x32_bf16 v[36:39], v[150:153], v[208:211], v[36:39]
	v_mfma_f32_16x16x32_bf16 v[24:27], v[158:161], v[208:211], v[24:27]
	v_mfma_f32_16x16x32_bf16 v[52:55], v[154:157], v[188:191], v[52:55]
	v_mfma_f32_16x16x32_bf16 v[40:43], v[162:165], v[188:191], v[40:43]
	v_mfma_f32_16x16x32_bf16 v[28:31], v[154:157], v[196:199], v[28:31]
	v_mfma_f32_16x16x32_bf16 v[12:15], v[162:165], v[196:199], v[12:15]
	v_mfma_f32_16x16x32_bf16 v[60:63], v[154:157], v[204:207], v[60:63]
	v_mfma_f32_16x16x32_bf16 v[48:51], v[162:165], v[204:207], v[48:51]
	v_mfma_f32_16x16x32_bf16 v[36:39], v[154:157], v[212:215], v[36:39]
	v_mfma_f32_16x16x32_bf16 v[24:27], v[162:165], v[212:215], v[24:27]
	s_setprio 0
	s_setprio 1
	v_mfma_f32_16x16x32_bf16 v[20:23], v[166:169], v[184:187], v[20:23]
	v_mfma_f32_16x16x32_bf16 v[8:11], v[174:177], v[184:187], v[8:11]
	v_mfma_f32_16x16x32_bf16 v[56:59], v[166:169], v[192:195], v[56:59]
	v_mfma_f32_16x16x32_bf16 v[44:47], v[174:177], v[192:195], v[44:47]
	v_mfma_f32_16x16x32_bf16 v[32:35], v[166:169], v[200:203], v[32:35]
	v_mfma_f32_16x16x32_bf16 v[16:19], v[174:177], v[200:203], v[16:19]
	v_mfma_f32_16x16x32_bf16 v[4:7], v[166:169], v[208:211], v[4:7]
	v_mfma_f32_16x16x32_bf16 v[0:3], v[174:177], v[208:211], v[0:3]
	v_mfma_f32_16x16x32_bf16 v[20:23], v[170:173], v[188:191], v[20:23]
	v_mfma_f32_16x16x32_bf16 v[8:11], v[180:183], v[188:191], v[8:11]
	v_mfma_f32_16x16x32_bf16 v[56:59], v[170:173], v[196:199], v[56:59]
	v_mfma_f32_16x16x32_bf16 v[44:47], v[180:183], v[196:199], v[44:47]
	v_mfma_f32_16x16x32_bf16 v[32:35], v[170:173], v[204:207], v[32:35]
	v_mfma_f32_16x16x32_bf16 v[16:19], v[180:183], v[204:207], v[16:19]
	v_mfma_f32_16x16x32_bf16 v[4:7], v[170:173], v[212:215], v[4:7]
	v_mfma_f32_16x16x32_bf16 v[0:3], v[180:183], v[212:215], v[0:3]
	s_barrier
	s_setprio 0
	s_add_i32 s66, 0, 0x18000
	s_add_i32 s67, 0, 0x1c000
	v_add_u32_e32 v162, s66, v148
	v_add_u32_e32 v179, s67, v148
	ds_read_b128 v[150:153], v162
	ds_read_b128 v[154:157], v162 offset:1024
	ds_read_b128 v[158:161], v162 offset:2048
	ds_read_b128 v[162:165], v162 offset:3072
	ds_read_b128 v[166:169], v179
	ds_read_b128 v[170:173], v179 offset:1024
	ds_read_b128 v[174:177], v179 offset:2048
	ds_read_b128 v[180:183], v179 offset:3072
	s_add_u32 s46, s46, 0x40000
	s_addc_u32 s47, s47, 0
	s_mov_b32 m0, s56
	v_lshl_add_u64 v[224:225], s[46:47], 0, v[128:129]
	ds_read_b128 v[184:187], v149 offset:32768
	ds_read_b128 v[188:191], v149 offset:33792
	ds_read_b128 v[192:195], v149 offset:34816
	ds_read_b128 v[196:199], v149 offset:35840
	ds_read_b128 v[200:203], v149 offset:36864
	ds_read_b128 v[204:207], v149 offset:37888
	ds_read_b128 v[208:211], v149 offset:38912
	ds_read_b128 v[212:215], v149 offset:39936
	global_load_lds_dwordx4 v[224:225], off
	v_lshl_add_u64 v[224:225], s[46:47], 0, v[130:131]
	s_mov_b32 m0, s57
	s_nop 0
	global_load_lds_dwordx4 v[224:225], off
	s_waitcnt vmcnt(8)
	s_waitcnt lgkmcnt(0)
	s_setprio 1
	s_barrier
	v_mfma_f32_16x16x32_bf16 v[124:127], v[150:153], v[184:187], v[124:127]
	v_mfma_f32_16x16x32_bf16 v[120:123], v[158:161], v[184:187], v[120:123]
	v_mfma_f32_16x16x32_bf16 v[108:111], v[150:153], v[192:195], v[108:111]
	v_mfma_f32_16x16x32_bf16 v[104:107], v[158:161], v[192:195], v[104:107]
	v_mfma_f32_16x16x32_bf16 v[100:103], v[150:153], v[200:203], v[100:103]
	v_mfma_f32_16x16x32_bf16 v[92:95], v[158:161], v[200:203], v[92:95]
	v_mfma_f32_16x16x32_bf16 v[84:87], v[150:153], v[208:211], v[84:87]
	v_mfma_f32_16x16x32_bf16 v[76:79], v[158:161], v[208:211], v[76:79]
	v_mfma_f32_16x16x32_bf16 v[124:127], v[154:157], v[188:191], v[124:127]
	v_mfma_f32_16x16x32_bf16 v[120:123], v[162:165], v[188:191], v[120:123]
	v_mfma_f32_16x16x32_bf16 v[108:111], v[154:157], v[196:199], v[108:111]
	v_mfma_f32_16x16x32_bf16 v[104:107], v[162:165], v[196:199], v[104:107]
	v_mfma_f32_16x16x32_bf16 v[100:103], v[154:157], v[204:207], v[100:103]
	v_mfma_f32_16x16x32_bf16 v[92:95], v[162:165], v[204:207], v[92:95]
	v_mfma_f32_16x16x32_bf16 v[84:87], v[154:157], v[212:215], v[84:87]
	v_mfma_f32_16x16x32_bf16 v[76:79], v[162:165], v[212:215], v[76:79]
	s_setprio 0
	s_setprio 1
	v_mfma_f32_16x16x32_bf16 v[116:119], v[166:169], v[184:187], v[116:119]
	v_mfma_f32_16x16x32_bf16 v[112:115], v[174:177], v[184:187], v[112:115]
	v_mfma_f32_16x16x32_bf16 v[96:99], v[166:169], v[192:195], v[96:99]
	v_mfma_f32_16x16x32_bf16 v[88:91], v[174:177], v[192:195], v[88:91]
	v_mfma_f32_16x16x32_bf16 v[80:83], v[166:169], v[200:203], v[80:83]
	v_mfma_f32_16x16x32_bf16 v[72:75], v[174:177], v[200:203], v[72:75]
	v_mfma_f32_16x16x32_bf16 v[68:71], v[166:169], v[208:211], v[68:71]
	v_mfma_f32_16x16x32_bf16 v[64:67], v[174:177], v[208:211], v[64:67]
	v_mfma_f32_16x16x32_bf16 v[116:119], v[170:173], v[188:191], v[116:119]
	v_mfma_f32_16x16x32_bf16 v[112:115], v[180:183], v[188:191], v[112:115]
	v_mfma_f32_16x16x32_bf16 v[96:99], v[170:173], v[196:199], v[96:99]
	v_mfma_f32_16x16x32_bf16 v[88:91], v[180:183], v[196:199], v[88:91]
	v_mfma_f32_16x16x32_bf16 v[80:83], v[170:173], v[204:207], v[80:83]
	v_mfma_f32_16x16x32_bf16 v[72:75], v[180:183], v[204:207], v[72:75]
	v_mfma_f32_16x16x32_bf16 v[68:71], v[170:173], v[212:215], v[68:71]
	v_mfma_f32_16x16x32_bf16 v[64:67], v[180:183], v[212:215], v[64:67]
	s_barrier
; #define PG8_STAGE(bufoff, gbase, voff) do { _Pragma("unroll") for (int _i = 0; _i < 2; ++_i) \
;         __builtin_amdgcn_global_load_lds((const unsigned*)((const char*)(gbase) + (voff)[_i]), (PG8_LAS unsigned*)(lds + (bufoff) + ldsw + _i * 8192), 16, 0, 0); } while (0)
; #define PG8_LDA(dst, b, h) do { _Pragma("unroll") for (int m = 0; m < 4; ++m) _Pragma("unroll") for (int k = 0; k < 2; ++k) dst[m][k] = *(const PG8_LAS bf16x8*)(lds + PG8_SA(b, h) + aoff + m * 2048 + k * 1024); } while (0)
; #define PG8_MMA(ai, bj, At, Bt) do { __builtin_amdgcn_s_setprio(1); _Pragma("unroll") for (int m = 0; m < 4; ++m) _Pragma("unroll") for (int n = 0; n < 2; ++n) _Pragma("unroll") for (int k = 0; k < 2; ++k) \
;         acc[ai][bj][m][n] = __builtin_amdgcn_mfma_f32_16x16x32_bf16(Bt[n][k], At[m][k], acc[ai][bj][m][n], 0, 0, 0); __builtin_amdgcn_s_setprio(0); } while (0)
; #define PG8_WAIT_V(n) asm volatile("s_waitcnt vmcnt(" #n ")" ::: "memory")
; #define PG8_WAIT_L(n) asm volatile("s_waitcnt lgkmcnt(" #n ")" ::: "memory")
; #define PG8_BAR __builtin_amdgcn_s_barrier()
; #define PG8_SCHED __builtin_amdgcn_sched_barrier(0)
; template <class Epi, class Sched, bool ALIGN_EPI = false, bool SP2 = false>
; __device__ __forceinline__ void gemm_phase(PG8_LAS unsigned char* lds, const Gemm g, const Sched& S, const Epi& E, const int wid) {
;     ...
;             PG8_LDA(At, 1, 1); PG8_STAGE(PG8_SB(1, 0), b3, voffB); PG8_STAGE(PG8_SB(1, 1), b3 + hstepB, voffB); PG8_STAGE(PG8_SA(1, 0), a3, voffA);
;             PG8_WAIT_V(8); PG8_WAIT_L(0); PG8_BAR; PG8_MMA(1, 0, At, B0); PG8_MMA(1, 1, At, B1); PG8_BAR; PG8_SCHED;
	s_setprio 0
	s_add_i32 s46, s66, s0
	v_lshl_add_u64 v[216:217], v[216:217], 0, s[26:27]
	s_mov_b32 m0, s46
	ds_read_b128 v[184:187], v149 offset:49152
	ds_read_b128 v[188:191], v149 offset:50176
	ds_read_b128 v[192:195], v149 offset:51200
	ds_read_b128 v[196:199], v149 offset:52224
	ds_read_b128 v[200:203], v149 offset:53248
	ds_read_b128 v[204:207], v149 offset:54272
	ds_read_b128 v[208:211], v149 offset:55296
	ds_read_b128 v[212:215], v149 offset:56320
	global_load_lds_dwordx4 v[216:217], off
	s_add_i32 m0, s46, 0x2000
	s_add_u32 s44, s44, 0x40080
	v_lshl_add_u64 v[216:217], v[218:219], 0, s[26:27]
	s_addc_u32 s45, s45, 0
	s_add_i32 s46, s67, s0
	global_load_lds_dwordx4 v[216:217], off
	v_lshl_add_u64 v[216:217], s[44:45], 0, v[134:135]
	s_mov_b32 m0, s46
	s_nop 0
	global_load_lds_dwordx4 v[216:217], off
	v_lshl_add_u64 v[216:217], s[44:45], 0, v[132:133]
	s_add_i32 m0, s46, 0x2000
	s_nop 0
	global_load_lds_dwordx4 v[216:217], off
	v_lshl_add_u64 v[216:217], v[220:221], 0, s[26:27]
	s_mov_b32 m0, s59
	s_nop 0
	global_load_lds_dwordx4 v[216:217], off
	v_lshl_add_u64 v[216:217], v[222:223], 0, s[26:27]
	s_mov_b32 m0, s60
	s_nop 0
	global_load_lds_dwordx4 v[216:217], off
	s_waitcnt vmcnt(8)
	s_waitcnt lgkmcnt(0)
	s_setprio 1
	s_barrier
	v_mfma_f32_16x16x32_bf16 v[52:55], v[150:153], v[184:187], v[52:55]
	v_mfma_f32_16x16x32_bf16 v[40:43], v[158:161], v[184:187], v[40:43]
	v_mfma_f32_16x16x32_bf16 v[28:31], v[150:153], v[192:195], v[28:31]
	v_mfma_f32_16x16x32_bf16 v[12:15], v[158:161], v[192:195], v[12:15]
	v_mfma_f32_16x16x32_bf16 v[60:63], v[150:153], v[200:203], v[60:63]
	v_mfma_f32_16x16x32_bf16 v[48:51], v[158:161], v[200:203], v[48:51]
	v_mfma_f32_16x16x32_bf16 v[36:39], v[150:153], v[208:211], v[36:39]
	v_mfma_f32_16x16x32_bf16 v[24:27], v[158:161], v[208:211], v[24:27]
	v_mfma_f32_16x16x32_bf16 v[52:55], v[154:157], v[188:191], v[52:55]
	v_mfma_f32_16x16x32_bf16 v[40:43], v[162:165], v[188:191], v[40:43]
	v_mfma_f32_16x16x32_bf16 v[28:31], v[154:157], v[196:199], v[28:31]
	v_mfma_f32_16x16x32_bf16 v[12:15], v[162:165], v[196:199], v[12:15]
	v_mfma_f32_16x16x32_bf16 v[60:63], v[154:157], v[204:207], v[60:63]
	v_mfma_f32_16x16x32_bf16 v[48:51], v[162:165], v[204:207], v[48:51]
	v_mfma_f32_16x16x32_bf16 v[36:39], v[154:157], v[212:215], v[36:39]
	v_mfma_f32_16x16x32_bf16 v[24:27], v[162:165], v[212:215], v[24:27]
	s_setprio 0
	s_setprio 1
	v_mfma_f32_16x16x32_bf16 v[20:23], v[166:169], v[184:187], v[20:23]
	v_mfma_f32_16x16x32_bf16 v[8:11], v[174:177], v[184:187], v[8:11]
	v_mfma_f32_16x16x32_bf16 v[56:59], v[166:169], v[192:195], v[56:59]
	v_mfma_f32_16x16x32_bf16 v[44:47], v[174:177], v[192:195], v[44:47]
	v_mfma_f32_16x16x32_bf16 v[32:35], v[166:169], v[200:203], v[32:35]
	v_mfma_f32_16x16x32_bf16 v[16:19], v[174:177], v[200:203], v[16:19]
	v_mfma_f32_16x16x32_bf16 v[4:7], v[166:169], v[208:211], v[4:7]
	v_mfma_f32_16x16x32_bf16 v[0:3], v[174:177], v[208:211], v[0:3]
	v_mfma_f32_16x16x32_bf16 v[20:23], v[170:173], v[188:191], v[20:23]
	v_mfma_f32_16x16x32_bf16 v[8:11], v[180:183], v[188:191], v[8:11]
	v_mfma_f32_16x16x32_bf16 v[56:59], v[170:173], v[196:199], v[56:59]
	v_mfma_f32_16x16x32_bf16 v[44:47], v[180:183], v[196:199], v[44:47]
	v_mfma_f32_16x16x32_bf16 v[32:35], v[170:173], v[204:207], v[32:35]
	v_mfma_f32_16x16x32_bf16 v[16:19], v[180:183], v[204:207], v[16:19]
	v_mfma_f32_16x16x32_bf16 v[4:7], v[170:173], v[212:215], v[4:7]
	v_mfma_f32_16x16x32_bf16 v[0:3], v[180:183], v[212:215], v[0:3]
	s_barrier
	s_setprio 0
	s_add_u32 s40, s40, 0x100
	s_addc_u32 s41, s41, 0
	s_add_u32 s31, s31, 0x100
	s_addc_u32 s35, s35, 0
	s_cmp_ge_i32 s65, s49
	s_mov_b32 s44, s65
	s_cbranch_scc0 .LBB0_405

; #define PG8_STAGE(bufoff, gbase, voff) do { _Pragma("unroll") for (int _i = 0; _i < 2; ++_i) \
;         __builtin_amdgcn_global_load_lds((const unsigned*)((const char*)(gbase) + (voff)[_i]), (PG8_LAS unsigned*)(lds + (bufoff) + ldsw + _i * 8192), 16, 0, 0); } while (0)
; #define PG8_WAIT_V(n) asm volatile("s_waitcnt vmcnt(" #n ")" ::: "memory")
; #define PG8_BAR __builtin_amdgcn_s_barrier()
; template <class Epi, class Sched, bool ALIGN_EPI = false, bool SP2 = false>
; __device__ __forceinline__ void gemm_phase(PG8_LAS unsigned char* lds, const Gemm g, const Sched& S, const Epi& E, const int wid) {
;     ...
;     const int aoff = lds_byte(wr * 64 + fr, fq * 8), boff = lds_byte(wc * 32 + fr, fq * 8);
;     ...
;         PG8_STAGE(PG8_SB(1, 0), cB + kstep, voffB); PG8_STAGE(PG8_SA(1, 0), cA + kstep, voffA); PG8_STAGE(PG8_SB(1, 1), cB + hstepB + kstep, voffB);
;         PG8_WAIT_V(6); PG8_BAR;
.LBB0_480:
	v_readlane_b32 s56, v249, 25
	v_mov_b32_e32 v133, v147
	v_readlane_b32 s57, v249, 26
	v_lshl_add_u64 v[0:1], v[0:1], 0, s[80:81]
	s_add_i32 m0, s65, 0x18000
	v_lshl_add_u64 v[12:13], s[56:57], 0, v[132:133]
	v_mov_b32_e32 v131, v147
	global_load_lds_dwordx4 v[0:1], off
	v_lshl_add_u64 v[0:1], v[2:3], 0, s[80:81]
	s_add_i32 m0, s65, 0x1a000
	s_add_i32 s69, s65, 0x8000
	s_add_i32 s70, s65, 0xa000
	v_lshl_add_u64 v[14:15], s[56:57], 0, v[130:131]
	global_load_lds_dwordx4 v[0:1], off
	v_lshl_add_u64 v[0:1], v[12:13], 0, s[80:81]
	s_mov_b32 m0, s69
	s_add_u32 s4, s58, 0x40080
	global_load_lds_dwordx4 v[0:1], off
	v_lshl_add_u64 v[0:1], v[14:15], 0, s[80:81]
	s_mov_b32 m0, s70
	s_addc_u32 s5, s59, 0
	global_load_lds_dwordx4 v[0:1], off
	v_lshl_add_u64 v[0:1], s[4:5], 0, v[146:147]
	s_add_i32 m0, s65, 0x1c000
	v_and_b32_e32 v11, 48, v7
	global_load_lds_dwordx4 v[0:1], off
	v_lshl_add_u64 v[0:1], s[4:5], 0, v[128:129]
	s_add_i32 m0, s65, 0x1e000
	s_movk_i32 s4, 0x3c0
	global_load_lds_dwordx4 v[0:1], off
	s_waitcnt vmcnt(8)
	s_barrier
	v_and_b32_e32 v0, 15, v7
	v_or_b32_e32 v141, s72, v0
	v_lshlrev_b32_e32 v3, 6, v141
	v_ashrrev_i32_e32 v2, 6, v7
	v_and_or_b32 v3, v3, s4, v11
	v_readlane_b32 s4, v250, 27
	v_ashrrev_i32_e32 v1, 1, v7
	v_lshlrev_b32_e32 v7, 2, v7
	v_lshl_add_u32 v12, v2, 10, s4
	v_readlane_b32 s4, v250, 28
	v_lshl_or_b32 v0, v0, 6, v11
	v_and_b32_e32 v7, 32, v7
	v_add_lshl_u32 v2, v2, s4, 10
	v_bitop3_b32 v143, v0, v2, v7 bitop3:0xde
	v_lshlrev_b32_e32 v0, 14, v8
	v_and_b32_e32 v1, -8, v1
	v_readlane_b32 s8, v250, 21
	v_and_b32_e32 v0, 0xffff8000, v0
	v_lshl_add_u32 v0, v9, 11, v0
	v_add_u32_e32 v161, s8, v1
	v_and_b32_e32 v1, 1, v8
	v_lshl_or_b32 v0, v1, 6, v0
	v_lshl_add_u32 v134, v10, 1, v0
	v_lshlrev_b32_e32 v0, 14, v4
	v_lshlrev_b32_e32 v13, 2, v141
	v_and_b32_e32 v0, 0xffff8000, v0
	v_and_b32_e32 v13, 32, v13
	s_waitcnt vmcnt(6)
	v_lshl_add_u32 v0, v5, 11, v0
	v_and_b32_e32 v1, 1, v4
	v_bitop3_b32 v3, v3, v12, v13 bitop3:0xde
	s_cmp_gt_i32 s62, 0
	v_lshl_or_b32 v0, v1, 6, v0
	v_readlane_b32 s10, v249, 21
	s_mov_b32 s71, 0
	s_cselect_b64 s[4:5], -1, 0
	s_add_i32 s72, s62, -2
	v_mov_b32_e32 v135, v147
	v_lshl_add_u32 v136, v6, 1, v0
	v_mov_b32_e32 v137, v147
	v_add_u32_e32 v163, 0, v3
	v_readlane_b32 s8, v249, 20
	s_mov_b32 s73, s10
	s_barrier
	v_readlane_b32 s11, v249, 22
	s_branch .LBB0_483

; #define PG8_STAGE(bufoff, gbase, voff) do { _Pragma("unroll") for (int _i = 0; _i < 2; ++_i) \
;         __builtin_amdgcn_global_load_lds((const unsigned*)((const char*)(gbase) + (voff)[_i]), (PG8_LAS unsigned*)(lds + (bufoff) + ldsw + _i * 8192), 16, 0, 0); } while (0)
; #define PG8_LDA(dst, b, h) do { _Pragma("unroll") for (int m = 0; m < 4; ++m) _Pragma("unroll") for (int k = 0; k < 2; ++k) dst[m][k] = *(const PG8_LAS bf16x8*)(lds + PG8_SA(b, h) + aoff + m * 2048 + k * 1024); } while (0)
; #define PG8_LDB(dst, b, h) do { _Pragma("unroll") for (int n = 0; n < 2; ++n) _Pragma("unroll") for (int k = 0; k < 2; ++k) dst[n][k] = *(const PG8_LAS bf16x8*)(lds + PG8_SB(b, h) + boff + n * 2048 + k * 1024); } while (0)
; #define PG8_MMA(ai, bj, At, Bt) do { __builtin_amdgcn_s_setprio(1); _Pragma("unroll") for (int m = 0; m < 4; ++m) _Pragma("unroll") for (int n = 0; n < 2; ++n) _Pragma("unroll") for (int k = 0; k < 2; ++k) \
;         acc[ai][bj][m][n] = __builtin_amdgcn_mfma_f32_16x16x32_bf16(Bt[n][k], At[m][k], acc[ai][bj][m][n], 0, 0, 0); __builtin_amdgcn_s_setprio(0); } while (0)
; #define PG8_WAIT_V(n) asm volatile("s_waitcnt vmcnt(" #n ")" ::: "memory")
; #define PG8_WAIT_L(n) asm volatile("s_waitcnt lgkmcnt(" #n ")" ::: "memory")
; template <class Epi, class Sched, bool ALIGN_EPI = false, bool SP2 = false>
; __device__ __forceinline__ void gemm_phase(PG8_LAS unsigned char* lds, const Gemm g, const Sched& S, const Epi& E, const int wid) {
;     ...
;             const bool last = (t == nt - 2);
;             const char* a1 = cA + (size_t)(t + 1) * kstep;
;             const char* a2 = last ? nA : cA + (size_t)(t + 2) * kstep; const char* b2 = last ? nB : cB + (size_t)(t + 2) * kstep;
;             const char* a3 = a2 + kstep; const char* b3 = b2 + kstep;
;             if (last && has_next) S.a_ready(nxt);
;             if constexpr (SP2) {
;             PG8_LDB(B0, 0, 0); PG8_LDB(B1, 0, 1); PG8_SCHED; PG8_LDA(At, 0, 0); PG8_STAGE(PG8_SA(1, 1), a1 + hstepA, voffA);
;             PG8_WAIT_V(8); PG8_WAIT_L(0); PG8_BAR; PG8_MMA(0, 0, At, B0); PG8_MMA(0, 1, At, B1); PG8_BAR; PG8_SCHED;
;             PG8_LDA(At, 0, 1); PG8_STAGE(PG8_SB(0, 0), b2, voffB); PG8_STAGE(PG8_SB(0, 1), b2 + hstepB, voffB); PG8_STAGE(PG8_SA(0, 0), a2, voffA);
;             PG8_WAIT_V(8); PG8_WAIT_L(0); PG8_BAR; PG8_MMA(1, 0, At, B0); PG8_MMA(1, 1, At, B1); PG8_BAR; PG8_SCHED;
.LBB0_487:
	s_add_i32 s74, s58, 2
	s_add_u32 s59, s56, 0xfffc0080
	s_addc_u32 s60, s57, -1
	s_add_i32 s75, 0, 0x10000
	s_cmp_eq_u32 s72, s58
	s_cselect_b32 s61, s53, s60
	s_cselect_b32 s60, s52, s59
	v_add_u32_e32 v138, s75, v143
	s_cselect_b32 s59, s55, s51
	s_cselect_b32 s58, s54, s11
	s_add_i32 s76, 0, 0x14000
	ds_read_b128 v[170:173], v138
	ds_read_b128 v[174:177], v138 offset:1024
	ds_read_b128 v[178:181], v138 offset:2048
	ds_read_b128 v[182:185], v138 offset:3072
	v_add_u32_e32 v138, s76, v143
	ds_read_b128 v[186:189], v138
	ds_read_b128 v[190:193], v138 offset:1024
	ds_read_b128 v[194:197], v138 offset:2048
	ds_read_b128 v[198:201], v138 offset:3072
	v_lshl_add_u64 v[138:139], s[56:57], 0, v[134:135]
	s_add_i32 m0, s65, 0xc000
	ds_read_b128 v[202:205], v163
	ds_read_b128 v[206:209], v163 offset:1024
	ds_read_b128 v[210:213], v163 offset:2048
	ds_read_b128 v[214:217], v163 offset:3072
	ds_read_b128 v[218:221], v163 offset:4096
	ds_read_b128 v[222:225], v163 offset:5120
	ds_read_b128 v[226:229], v163 offset:6144
	ds_read_b128 v[230:233], v163 offset:7168
	global_load_lds_dwordx4 v[138:139], off
	v_lshl_add_u64 v[138:139], s[56:57], 0, v[136:137]
	s_add_i32 m0, s65, 0xe000
	s_nop 0
	global_load_lds_dwordx4 v[138:139], off
	s_waitcnt vmcnt(8)
	s_waitcnt lgkmcnt(0)
	s_setprio 1
	s_barrier
	v_mfma_f32_16x16x32_bf16 v[124:127], v[170:173], v[202:205], v[124:127]
	v_mfma_f32_16x16x32_bf16 v[116:119], v[178:181], v[202:205], v[116:119]
	v_mfma_f32_16x16x32_bf16 v[108:111], v[170:173], v[210:213], v[108:111]
	v_mfma_f32_16x16x32_bf16 v[100:103], v[178:181], v[210:213], v[100:103]
	v_mfma_f32_16x16x32_bf16 v[92:95], v[170:173], v[218:221], v[92:95]
	v_mfma_f32_16x16x32_bf16 v[84:87], v[178:181], v[218:221], v[84:87]
	v_mfma_f32_16x16x32_bf16 v[76:79], v[170:173], v[226:229], v[76:79]
	v_mfma_f32_16x16x32_bf16 v[68:71], v[178:181], v[226:229], v[68:71]
	v_mfma_f32_16x16x32_bf16 v[124:127], v[174:177], v[206:209], v[124:127]
	v_mfma_f32_16x16x32_bf16 v[116:119], v[182:185], v[206:209], v[116:119]
	v_mfma_f32_16x16x32_bf16 v[108:111], v[174:177], v[214:217], v[108:111]
	v_mfma_f32_16x16x32_bf16 v[100:103], v[182:185], v[214:217], v[100:103]
	v_mfma_f32_16x16x32_bf16 v[92:95], v[174:177], v[222:225], v[92:95]
	v_mfma_f32_16x16x32_bf16 v[84:87], v[182:185], v[222:225], v[84:87]
	v_mfma_f32_16x16x32_bf16 v[76:79], v[174:177], v[230:233], v[76:79]
	v_mfma_f32_16x16x32_bf16 v[68:71], v[182:185], v[230:233], v[68:71]
	s_setprio 0
	s_setprio 1
	v_mfma_f32_16x16x32_bf16 v[120:123], v[186:189], v[202:205], v[120:123]
	v_mfma_f32_16x16x32_bf16 v[112:115], v[194:197], v[202:205], v[112:115]
	v_mfma_f32_16x16x32_bf16 v[104:107], v[186:189], v[210:213], v[104:107]
	v_mfma_f32_16x16x32_bf16 v[96:99], v[194:197], v[210:213], v[96:99]
	v_mfma_f32_16x16x32_bf16 v[88:91], v[186:189], v[218:221], v[88:91]
	v_mfma_f32_16x16x32_bf16 v[80:83], v[194:197], v[218:221], v[80:83]
	v_mfma_f32_16x16x32_bf16 v[72:75], v[186:189], v[226:229], v[72:75]
	v_mfma_f32_16x16x32_bf16 v[64:67], v[194:197], v[226:229], v[64:67]
	v_mfma_f32_16x16x32_bf16 v[120:123], v[190:193], v[206:209], v[120:123]
	v_mfma_f32_16x16x32_bf16 v[112:115], v[198:201], v[206:209], v[112:115]
	v_mfma_f32_16x16x32_bf16 v[104:107], v[190:193], v[214:217], v[104:107]
	v_mfma_f32_16x16x32_bf16 v[96:99], v[198:201], v[214:217], v[96:99]
	v_mfma_f32_16x16x32_bf16 v[88:91], v[190:193], v[222:225], v[88:91]
	v_mfma_f32_16x16x32_bf16 v[80:83], v[198:201], v[222:225], v[80:83]
	v_mfma_f32_16x16x32_bf16 v[72:75], v[190:193], v[230:233], v[72:75]
	v_mfma_f32_16x16x32_bf16 v[64:67], v[198:201], v[230:233], v[64:67]
	s_barrier
	s_setprio 0
	s_add_i32 s75, s75, s0
	v_lshl_add_u64 v[138:139], s[58:59], 0, v[146:147]
	s_mov_b32 m0, s75
	ds_read_b128 v[202:205], v163 offset:16384
	ds_read_b128 v[206:209], v163 offset:17408
	ds_read_b128 v[210:213], v163 offset:18432
	ds_read_b128 v[214:217], v163 offset:19456
	ds_read_b128 v[218:221], v163 offset:20480
	ds_read_b128 v[222:225], v163 offset:21504
	ds_read_b128 v[226:229], v163 offset:22528
	ds_read_b128 v[230:233], v163 offset:23552
	global_load_lds_dwordx4 v[138:139], off
	s_add_i32 m0, s75, 0x2000
	s_add_u32 s82, s58, 0x40000
	v_lshl_add_u64 v[234:235], s[58:59], 0, v[128:129]
	s_addc_u32 s83, s59, 0
	s_add_i32 s75, s76, s0
	global_load_lds_dwordx4 v[234:235], off
	v_lshl_add_u64 v[236:237], s[82:83], 0, v[146:147]
	s_mov_b32 m0, s75
	v_lshl_add_u64 v[238:239], s[60:61], 0, v[130:131]
	global_load_lds_dwordx4 v[236:237], off
	v_lshl_add_u64 v[236:237], s[82:83], 0, v[128:129]
	s_add_i32 m0, s75, 0x2000
	s_nop 0
	global_load_lds_dwordx4 v[236:237], off
	v_lshl_add_u64 v[236:237], s[60:61], 0, v[132:133]
	s_mov_b32 m0, s65
	s_nop 0
	global_load_lds_dwordx4 v[236:237], off
	s_mov_b32 m0, s66
	s_nop 0
	global_load_lds_dwordx4 v[238:239], off
	s_waitcnt vmcnt(8)
	s_waitcnt lgkmcnt(0)
	s_setprio 1
	s_barrier
; #define PG8_STAGE(bufoff, gbase, voff) do { _Pragma("unroll") for (int _i = 0; _i < 2; ++_i) \
;         __builtin_amdgcn_global_load_lds((const unsigned*)((const char*)(gbase) + (voff)[_i]), (PG8_LAS unsigned*)(lds + (bufoff) + ldsw + _i * 8192), 16, 0, 0); } while (0)
; #define PG8_LDA(dst, b, h) do { _Pragma("unroll") for (int m = 0; m < 4; ++m) _Pragma("unroll") for (int k = 0; k < 2; ++k) dst[m][k] = *(const PG8_LAS bf16x8*)(lds + PG8_SA(b, h) + aoff + m * 2048 + k * 1024); } while (0)
; #define PG8_LDB(dst, b, h) do { _Pragma("unroll") for (int n = 0; n < 2; ++n) _Pragma("unroll") for (int k = 0; k < 2; ++k) dst[n][k] = *(const PG8_LAS bf16x8*)(lds + PG8_SB(b, h) + boff + n * 2048 + k * 1024); } while (0)
; #define PG8_MMA(ai, bj, At, Bt) do { __builtin_amdgcn_s_setprio(1); _Pragma("unroll") for (int m = 0; m < 4; ++m) _Pragma("unroll") for (int n = 0; n < 2; ++n) _Pragma("unroll") for (int k = 0; k < 2; ++k) \
;         acc[ai][bj][m][n] = __builtin_amdgcn_mfma_f32_16x16x32_bf16(Bt[n][k], At[m][k], acc[ai][bj][m][n], 0, 0, 0); __builtin_amdgcn_s_setprio(0); } while (0)
; #define PG8_WAIT_V(n) asm volatile("s_waitcnt vmcnt(" #n ")" ::: "memory")
; #define PG8_WAIT_L(n) asm volatile("s_waitcnt lgkmcnt(" #n ")" ::: "memory")
; #define PG8_BAR __builtin_amdgcn_s_barrier()
; #define PG8_SCHED __builtin_amdgcn_sched_barrier(0)
; template <class Epi, class Sched, bool ALIGN_EPI = false, bool SP2 = false>
; __device__ __forceinline__ void gemm_phase(PG8_LAS unsigned char* lds, const Gemm g, const Sched& S, const Epi& E, const int wid) {
;     ...
;             PG8_WAIT_V(8); PG8_WAIT_L(0); PG8_BAR; PG8_MMA(1, 0, At, B0); PG8_MMA(1, 1, At, B1); PG8_BAR; PG8_SCHED;
;             PG8_LDB(B0, 1, 0); PG8_LDB(B1, 1, 1); PG8_SCHED; PG8_LDA(At, 1, 0); PG8_STAGE(PG8_SA(0, 1), a2 + hstepA, voffA);
;             PG8_WAIT_V(8); PG8_WAIT_L(0); PG8_BAR; PG8_MMA(0, 0, At, B0); PG8_MMA(0, 1, At, B1); PG8_BAR; PG8_SCHED;
	v_mfma_f32_16x16x32_bf16 v[60:63], v[170:173], v[202:205], v[60:63]
	v_mfma_f32_16x16x32_bf16 v[52:55], v[178:181], v[202:205], v[52:55]
	v_mfma_f32_16x16x32_bf16 v[44:47], v[170:173], v[210:213], v[44:47]
	v_mfma_f32_16x16x32_bf16 v[36:39], v[178:181], v[210:213], v[36:39]
	v_mfma_f32_16x16x32_bf16 v[28:31], v[170:173], v[218:221], v[28:31]
	v_mfma_f32_16x16x32_bf16 v[20:23], v[178:181], v[218:221], v[20:23]
	v_mfma_f32_16x16x32_bf16 v[12:15], v[170:173], v[226:229], v[12:15]
	v_mfma_f32_16x16x32_bf16 v[4:7], v[178:181], v[226:229], v[4:7]
	v_mfma_f32_16x16x32_bf16 v[60:63], v[174:177], v[206:209], v[60:63]
	v_mfma_f32_16x16x32_bf16 v[52:55], v[182:185], v[206:209], v[52:55]
	v_mfma_f32_16x16x32_bf16 v[44:47], v[174:177], v[214:217], v[44:47]
	v_mfma_f32_16x16x32_bf16 v[36:39], v[182:185], v[214:217], v[36:39]
	v_mfma_f32_16x16x32_bf16 v[28:31], v[174:177], v[222:225], v[28:31]
	v_mfma_f32_16x16x32_bf16 v[20:23], v[182:185], v[222:225], v[20:23]
	v_mfma_f32_16x16x32_bf16 v[12:15], v[174:177], v[230:233], v[12:15]
	v_mfma_f32_16x16x32_bf16 v[4:7], v[182:185], v[230:233], v[4:7]
	s_setprio 0
	s_setprio 1
	v_mfma_f32_16x16x32_bf16 v[56:59], v[186:189], v[202:205], v[56:59]
	v_mfma_f32_16x16x32_bf16 v[48:51], v[194:197], v[202:205], v[48:51]
	v_mfma_f32_16x16x32_bf16 v[40:43], v[186:189], v[210:213], v[40:43]
	v_mfma_f32_16x16x32_bf16 v[32:35], v[194:197], v[210:213], v[32:35]
	v_mfma_f32_16x16x32_bf16 v[24:27], v[186:189], v[218:221], v[24:27]
	v_mfma_f32_16x16x32_bf16 v[16:19], v[194:197], v[218:221], v[16:19]
	v_mfma_f32_16x16x32_bf16 v[8:11], v[186:189], v[226:229], v[8:11]
	v_mfma_f32_16x16x32_bf16 v[0:3], v[194:197], v[226:229], v[0:3]
	v_mfma_f32_16x16x32_bf16 v[56:59], v[190:193], v[206:209], v[56:59]
	v_mfma_f32_16x16x32_bf16 v[48:51], v[198:201], v[206:209], v[48:51]
	v_mfma_f32_16x16x32_bf16 v[40:43], v[190:193], v[214:217], v[40:43]
	v_mfma_f32_16x16x32_bf16 v[32:35], v[198:201], v[214:217], v[32:35]
	v_mfma_f32_16x16x32_bf16 v[24:27], v[190:193], v[222:225], v[24:27]
	v_mfma_f32_16x16x32_bf16 v[16:19], v[198:201], v[222:225], v[16:19]
	v_mfma_f32_16x16x32_bf16 v[8:11], v[190:193], v[230:233], v[8:11]
	v_mfma_f32_16x16x32_bf16 v[0:3], v[198:201], v[230:233], v[0:3]
	s_barrier
	s_setprio 0
	s_add_i32 s75, 0, 0x18000
	v_add_u32_e32 v140, s75, v143
	s_add_i32 s76, 0, 0x1c000
	ds_read_b128 v[170:173], v140
	ds_read_b128 v[174:177], v140 offset:1024
	ds_read_b128 v[178:181], v140 offset:2048
	ds_read_b128 v[182:185], v140 offset:3072
	v_add_u32_e32 v140, s76, v143
	ds_read_b128 v[186:189], v140
	ds_read_b128 v[190:193], v140 offset:1024
	ds_read_b128 v[194:197], v140 offset:2048
	ds_read_b128 v[198:201], v140 offset:3072
	s_add_u32 s60, s60, 0x40000
	s_addc_u32 s61, s61, 0
	s_mov_b32 m0, s67
	v_lshl_add_u64 v[240:241], s[60:61], 0, v[132:133]
	ds_read_b128 v[202:205], v163 offset:32768
	ds_read_b128 v[206:209], v163 offset:33792
	ds_read_b128 v[210:213], v163 offset:34816
	ds_read_b128 v[214:217], v163 offset:35840
	ds_read_b128 v[218:221], v163 offset:36864
	ds_read_b128 v[222:225], v163 offset:37888
	ds_read_b128 v[226:229], v163 offset:38912
	ds_read_b128 v[230:233], v163 offset:39936
	global_load_lds_dwordx4 v[240:241], off
	v_lshl_add_u64 v[240:241], s[60:61], 0, v[130:131]
	s_mov_b32 m0, s68
	s_nop 0
	global_load_lds_dwordx4 v[240:241], off
	s_waitcnt vmcnt(8)
	s_waitcnt lgkmcnt(0)
	s_setprio 1
	s_barrier
	v_mfma_f32_16x16x32_bf16 v[124:127], v[170:173], v[202:205], v[124:127]
	v_mfma_f32_16x16x32_bf16 v[116:119], v[178:181], v[202:205], v[116:119]
	v_mfma_f32_16x16x32_bf16 v[108:111], v[170:173], v[210:213], v[108:111]
	v_mfma_f32_16x16x32_bf16 v[100:103], v[178:181], v[210:213], v[100:103]
	v_mfma_f32_16x16x32_bf16 v[92:95], v[170:173], v[218:221], v[92:95]
	v_mfma_f32_16x16x32_bf16 v[84:87], v[178:181], v[218:221], v[84:87]
	v_mfma_f32_16x16x32_bf16 v[76:79], v[170:173], v[226:229], v[76:79]
	v_mfma_f32_16x16x32_bf16 v[68:71], v[178:181], v[226:229], v[68:71]
	v_mfma_f32_16x16x32_bf16 v[124:127], v[174:177], v[206:209], v[124:127]
	v_mfma_f32_16x16x32_bf16 v[116:119], v[182:185], v[206:209], v[116:119]
	v_mfma_f32_16x16x32_bf16 v[108:111], v[174:177], v[214:217], v[108:111]
	v_mfma_f32_16x16x32_bf16 v[100:103], v[182:185], v[214:217], v[100:103]
	v_mfma_f32_16x16x32_bf16 v[92:95], v[174:177], v[222:225], v[92:95]
	v_mfma_f32_16x16x32_bf16 v[84:87], v[182:185], v[222:225], v[84:87]
	v_mfma_f32_16x16x32_bf16 v[76:79], v[174:177], v[230:233], v[76:79]
	v_mfma_f32_16x16x32_bf16 v[68:71], v[182:185], v[230:233], v[68:71]
	s_setprio 0
	s_setprio 1
	v_mfma_f32_16x16x32_bf16 v[120:123], v[186:189], v[202:205], v[120:123]
	v_mfma_f32_16x16x32_bf16 v[112:115], v[194:197], v[202:205], v[112:115]
	v_mfma_f32_16x16x32_bf16 v[104:107], v[186:189], v[210:213], v[104:107]
	v_mfma_f32_16x16x32_bf16 v[96:99], v[194:197], v[210:213], v[96:99]
	v_mfma_f32_16x16x32_bf16 v[88:91], v[186:189], v[218:221], v[88:91]
	v_mfma_f32_16x16x32_bf16 v[80:83], v[194:197], v[218:221], v[80:83]
	v_mfma_f32_16x16x32_bf16 v[72:75], v[186:189], v[226:229], v[72:75]
	v_mfma_f32_16x16x32_bf16 v[64:67], v[194:197], v[226:229], v[64:67]
	v_mfma_f32_16x16x32_bf16 v[120:123], v[190:193], v[206:209], v[120:123]
	v_mfma_f32_16x16x32_bf16 v[112:115], v[198:201], v[206:209], v[112:115]
	v_mfma_f32_16x16x32_bf16 v[104:107], v[190:193], v[214:217], v[104:107]
	v_mfma_f32_16x16x32_bf16 v[96:99], v[198:201], v[214:217], v[96:99]
	v_mfma_f32_16x16x32_bf16 v[88:91], v[190:193], v[222:225], v[88:91]
	v_mfma_f32_16x16x32_bf16 v[80:83], v[198:201], v[222:225], v[80:83]
	v_mfma_f32_16x16x32_bf16 v[72:75], v[190:193], v[230:233], v[72:75]
	v_mfma_f32_16x16x32_bf16 v[64:67], v[198:201], v[230:233], v[64:67]
	s_barrier
; #define PG8_STAGE(bufoff, gbase, voff) do { _Pragma("unroll") for (int _i = 0; _i < 2; ++_i) \
;         __builtin_amdgcn_global_load_lds((const unsigned*)((const char*)(gbase) + (voff)[_i]), (PG8_LAS unsigned*)(lds + (bufoff) + ldsw + _i * 8192), 16, 0, 0); } while (0)
; #define PG8_LDA(dst, b, h) do { _Pragma("unroll") for (int m = 0; m < 4; ++m) _Pragma("unroll") for (int k = 0; k < 2; ++k) dst[m][k] = *(const PG8_LAS bf16x8*)(lds + PG8_SA(b, h) + aoff + m * 2048 + k * 1024); } while (0)
; #define PG8_MMA(ai, bj, At, Bt) do { __builtin_amdgcn_s_setprio(1); _Pragma("unroll") for (int m = 0; m < 4; ++m) _Pragma("unroll") for (int n = 0; n < 2; ++n) _Pragma("unroll") for (int k = 0; k < 2; ++k) \
;         acc[ai][bj][m][n] = __builtin_amdgcn_mfma_f32_16x16x32_bf16(Bt[n][k], At[m][k], acc[ai][bj][m][n], 0, 0, 0); __builtin_amdgcn_s_setprio(0); } while (0)
; #define PG8_WAIT_V(n) asm volatile("s_waitcnt vmcnt(" #n ")" ::: "memory")
; #define PG8_WAIT_L(n) asm volatile("s_waitcnt lgkmcnt(" #n ")" ::: "memory")
; #define PG8_BAR __builtin_amdgcn_s_barrier()
; #define PG8_SCHED __builtin_amdgcn_sched_barrier(0)
; template <class Epi, class Sched, bool ALIGN_EPI = false, bool SP2 = false>
; __device__ __forceinline__ void gemm_phase(PG8_LAS unsigned char* lds, const Gemm g, const Sched& S, const Epi& E, const int wid) {
;     ...
;         for (int t = 0; t < nt; t += 2) {
;             const bool last = (t == nt - 2);
;             const char* a1 = cA + (size_t)(t + 1) * kstep;
;             const char* a2 = last ? nA : cA + (size_t)(t + 2) * kstep; const char* b2 = last ? nB : cB + (size_t)(t + 2) * kstep;
;             const char* a3 = a2 + kstep; const char* b3 = b2 + kstep;
;     ...
;             PG8_LDA(At, 1, 1); PG8_STAGE(PG8_SB(1, 0), b3, voffB); PG8_STAGE(PG8_SB(1, 1), b3 + hstepB, voffB); PG8_STAGE(PG8_SA(1, 0), a3, voffA);
;             PG8_WAIT_V(8); PG8_WAIT_L(0); PG8_BAR; PG8_MMA(1, 0, At, B0); PG8_MMA(1, 1, At, B1); PG8_BAR; PG8_SCHED;
	s_setprio 0
	s_add_i32 s60, s75, s0
	v_lshl_add_u64 v[138:139], v[138:139], 0, s[80:81]
	s_mov_b32 m0, s60
	ds_read_b128 v[202:205], v163 offset:49152
	ds_read_b128 v[206:209], v163 offset:50176
	ds_read_b128 v[210:213], v163 offset:51200
	ds_read_b128 v[214:217], v163 offset:52224
	ds_read_b128 v[218:221], v163 offset:53248
	ds_read_b128 v[222:225], v163 offset:54272
	ds_read_b128 v[226:229], v163 offset:55296
	ds_read_b128 v[230:233], v163 offset:56320
	global_load_lds_dwordx4 v[138:139], off
	s_add_i32 m0, s60, 0x2000
	s_add_u32 s58, s58, 0x40080
	v_lshl_add_u64 v[138:139], v[234:235], 0, s[80:81]
	s_addc_u32 s59, s59, 0
	s_add_i32 s60, s76, s0
	global_load_lds_dwordx4 v[138:139], off
	v_lshl_add_u64 v[138:139], s[58:59], 0, v[146:147]
	s_mov_b32 m0, s60
	s_nop 0
	global_load_lds_dwordx4 v[138:139], off
	v_lshl_add_u64 v[138:139], s[58:59], 0, v[128:129]
	s_add_i32 m0, s60, 0x2000
	s_nop 0
	global_load_lds_dwordx4 v[138:139], off
	v_lshl_add_u64 v[138:139], v[236:237], 0, s[80:81]
	s_mov_b32 m0, s69
	s_nop 0
	global_load_lds_dwordx4 v[138:139], off
	v_lshl_add_u64 v[138:139], v[238:239], 0, s[80:81]
	s_mov_b32 m0, s70
	s_nop 0
	global_load_lds_dwordx4 v[138:139], off
	s_waitcnt vmcnt(8)
	s_waitcnt lgkmcnt(0)
	s_setprio 1
	s_barrier
	v_mfma_f32_16x16x32_bf16 v[60:63], v[170:173], v[202:205], v[60:63]
	v_mfma_f32_16x16x32_bf16 v[52:55], v[178:181], v[202:205], v[52:55]
	v_mfma_f32_16x16x32_bf16 v[44:47], v[170:173], v[210:213], v[44:47]
	v_mfma_f32_16x16x32_bf16 v[36:39], v[178:181], v[210:213], v[36:39]
	v_mfma_f32_16x16x32_bf16 v[28:31], v[170:173], v[218:221], v[28:31]
	v_mfma_f32_16x16x32_bf16 v[20:23], v[178:181], v[218:221], v[20:23]
	v_mfma_f32_16x16x32_bf16 v[12:15], v[170:173], v[226:229], v[12:15]
	v_mfma_f32_16x16x32_bf16 v[4:7], v[178:181], v[226:229], v[4:7]
	v_mfma_f32_16x16x32_bf16 v[60:63], v[174:177], v[206:209], v[60:63]
	v_mfma_f32_16x16x32_bf16 v[52:55], v[182:185], v[206:209], v[52:55]
	v_mfma_f32_16x16x32_bf16 v[44:47], v[174:177], v[214:217], v[44:47]
	v_mfma_f32_16x16x32_bf16 v[36:39], v[182:185], v[214:217], v[36:39]
	v_mfma_f32_16x16x32_bf16 v[28:31], v[174:177], v[222:225], v[28:31]
	v_mfma_f32_16x16x32_bf16 v[20:23], v[182:185], v[222:225], v[20:23]
	v_mfma_f32_16x16x32_bf16 v[12:15], v[174:177], v[230:233], v[12:15]
	v_mfma_f32_16x16x32_bf16 v[4:7], v[182:185], v[230:233], v[4:7]
	s_setprio 0
	s_setprio 1
	v_mfma_f32_16x16x32_bf16 v[56:59], v[186:189], v[202:205], v[56:59]
	v_mfma_f32_16x16x32_bf16 v[48:51], v[194:197], v[202:205], v[48:51]
	v_mfma_f32_16x16x32_bf16 v[40:43], v[186:189], v[210:213], v[40:43]
	v_mfma_f32_16x16x32_bf16 v[32:35], v[194:197], v[210:213], v[32:35]
	v_mfma_f32_16x16x32_bf16 v[24:27], v[186:189], v[218:221], v[24:27]
	v_mfma_f32_16x16x32_bf16 v[16:19], v[194:197], v[218:221], v[16:19]
	v_mfma_f32_16x16x32_bf16 v[8:11], v[186:189], v[226:229], v[8:11]
	v_mfma_f32_16x16x32_bf16 v[0:3], v[194:197], v[226:229], v[0:3]
	v_mfma_f32_16x16x32_bf16 v[56:59], v[190:193], v[206:209], v[56:59]
	v_mfma_f32_16x16x32_bf16 v[48:51], v[198:201], v[206:209], v[48:51]
	v_mfma_f32_16x16x32_bf16 v[40:43], v[190:193], v[214:217], v[40:43]
	v_mfma_f32_16x16x32_bf16 v[32:35], v[198:201], v[214:217], v[32:35]
	v_mfma_f32_16x16x32_bf16 v[24:27], v[190:193], v[222:225], v[24:27]
	v_mfma_f32_16x16x32_bf16 v[16:19], v[198:201], v[222:225], v[16:19]
	v_mfma_f32_16x16x32_bf16 v[8:11], v[190:193], v[230:233], v[8:11]
	v_mfma_f32_16x16x32_bf16 v[0:3], v[198:201], v[230:233], v[0:3]
	s_barrier
	s_setprio 0
	s_add_u32 s56, s56, 0x100
	s_addc_u32 s57, s57, 0
	s_add_u32 s11, s11, 0x100
	s_addc_u32 s51, s51, 0
	s_cmp_ge_i32 s74, s62
	s_mov_b32 s58, s74
	s_cbranch_scc0 .LBB0_487
	s_mov_b32 s74, 0x1e000
	s_mov_b32 s75, 0xc000
	s_mov_b32 s82, 0x24000
	s_mov_b32 s83, 0x26000
	s_mov_b32 s61, 0x2c000
	s_mov_b32 s60, 0x32000
	s_mov_b32 s76, 0x38000
	s_mov_b32 s51, 0x2e000
	s_and_b64 vcc, exec, s[6:7]
	s_cbranch_vccz .LBB0_490

; #define PG8_STAGE(bufoff, gbase, voff) do { _Pragma("unroll") for (int _i = 0; _i < 2; ++_i) \
;         __builtin_amdgcn_global_load_lds((const unsigned*)((const char*)(gbase) + (voff)[_i]), (PG8_LAS unsigned*)(lds + (bufoff) + ldsw + _i * 8192), 16, 0, 0); } while (0)
; #define PG8_LDA(dst, b, h) do { _Pragma("unroll") for (int m = 0; m < 4; ++m) _Pragma("unroll") for (int k = 0; k < 2; ++k) dst[m][k] = *(const PG8_LAS bf16x8*)(lds + PG8_SA(b, h) + aoff + m * 2048 + k * 1024); } while (0)
; #define PG8_LDB(dst, b, h) do { _Pragma("unroll") for (int n = 0; n < 2; ++n) _Pragma("unroll") for (int k = 0; k < 2; ++k) dst[n][k] = *(const PG8_LAS bf16x8*)(lds + PG8_SB(b, h) + boff + n * 2048 + k * 1024); } while (0)
; #define PG8_MMA(ai, bj, At, Bt) do { __builtin_amdgcn_s_setprio(1); _Pragma("unroll") for (int m = 0; m < 4; ++m) _Pragma("unroll") for (int n = 0; n < 2; ++n) _Pragma("unroll") for (int k = 0; k < 2; ++k) \
;         acc[ai][bj][m][n] = __builtin_amdgcn_mfma_f32_16x16x32_bf16(Bt[n][k], At[m][k], acc[ai][bj][m][n], 0, 0, 0); __builtin_amdgcn_s_setprio(0); } while (0)
; #define PG8_WAIT_V(n) asm volatile("s_waitcnt vmcnt(" #n ")" ::: "memory")
; #define PG8_BAR __builtin_amdgcn_s_barrier()
; template <class Epi, class Sched, bool ALIGN_EPI = false, bool SP2 = false>
; __device__ __forceinline__ void gemm_phase(PG8_LAS unsigned char* lds, const Gemm g, const Sched& S, const Epi& E, const int wid) {
;     ...
;         for (int t = 0; t < nt; t += 2) {
;             const bool last = (t == nt - 2);
;             const char* a1 = cA + (size_t)(t + 1) * kstep;
;             const char* a2 = last ? nA : cA + (size_t)(t + 2) * kstep; const char* b2 = last ? nB : cB + (size_t)(t + 2) * kstep;
;             const char* a3 = a2 + kstep; const char* b3 = b2 + kstep;
;             if (last && has_next) S.a_ready(nxt);
;             if constexpr (SP2) {
;             PG8_LDB(B0, 0, 0); PG8_LDB(B1, 0, 1); PG8_SCHED; PG8_LDA(At, 0, 0); PG8_STAGE(PG8_SA(1, 1), a1 + hstepA, voffA);
;             PG8_WAIT_V(8); PG8_WAIT_L(0); PG8_BAR; PG8_MMA(0, 0, At, B0); PG8_MMA(0, 1, At, B1); PG8_BAR; PG8_SCHED;
;             PG8_LDA(At, 0, 1); PG8_STAGE(PG8_SB(0, 0), b2, voffB); PG8_STAGE(PG8_SB(0, 1), b2 + hstepB, voffB); PG8_STAGE(PG8_SA(0, 0), a2, voffA);
;             PG8_WAIT_V(8); PG8_WAIT_L(0); PG8_BAR; PG8_MMA(1, 0, At, B0); PG8_MMA(1, 1, At, B1); PG8_BAR; PG8_SCHED;
.LBB0_575:
	s_add_i32 vcc_lo, s58, 2
	s_add_u32 s56, s62, 0x100
	s_addc_u32 s57, s63, 0
	s_add_i32 s9, 0, 0x10000
	s_cmp_eq_u32 s73, s58
	s_cselect_b32 s61, s47, s57
	s_cselect_b32 s60, s46, s56
	v_add_u32_e32 v143, s9, v141
	s_cselect_b32 s59, s55, s83
	s_cselect_b32 s58, s54, s82
	s_add_i32 vcc_hi, 0, 0x14000
	ds_read_b128 v[170:173], v143
	ds_read_b128 v[174:177], v143 offset:1024
	ds_read_b128 v[178:181], v143 offset:2048
	ds_read_b128 v[182:185], v143 offset:3072
	v_add_u32_e32 v143, vcc_hi, v141
	ds_read_b128 v[186:189], v143
	ds_read_b128 v[190:193], v143 offset:1024
	ds_read_b128 v[194:197], v143 offset:2048
	ds_read_b128 v[198:201], v143 offset:3072
	v_lshl_add_u64 v[160:161], s[62:63], 0, v[134:135]
	s_add_i32 m0, s67, 0xc000
	ds_read_b128 v[202:205], v142
	ds_read_b128 v[206:209], v142 offset:1024
	ds_read_b128 v[210:213], v142 offset:2048
	ds_read_b128 v[214:217], v142 offset:3072
	ds_read_b128 v[218:221], v142 offset:4096
	ds_read_b128 v[222:225], v142 offset:5120
	ds_read_b128 v[226:229], v142 offset:6144
	ds_read_b128 v[230:233], v142 offset:7168
	global_load_lds_dwordx4 v[160:161], off
	v_lshl_add_u64 v[160:161], s[62:63], 0, v[136:137]
	s_add_i32 m0, s67, 0xe000
	s_nop 0
	global_load_lds_dwordx4 v[160:161], off
	s_waitcnt vmcnt(8)
	s_waitcnt lgkmcnt(0)
	s_setprio 1
	s_barrier
	v_mfma_f32_16x16x32_bf16 v[124:127], v[170:173], v[202:205], v[124:127]
	v_mfma_f32_16x16x32_bf16 v[120:123], v[178:181], v[202:205], v[120:123]
	v_mfma_f32_16x16x32_bf16 v[108:111], v[170:173], v[210:213], v[108:111]
	v_mfma_f32_16x16x32_bf16 v[104:107], v[178:181], v[210:213], v[104:107]
	v_mfma_f32_16x16x32_bf16 v[92:95], v[170:173], v[218:221], v[92:95]
	v_mfma_f32_16x16x32_bf16 v[88:91], v[178:181], v[218:221], v[88:91]
	v_mfma_f32_16x16x32_bf16 v[80:83], v[170:173], v[226:229], v[80:83]
	v_mfma_f32_16x16x32_bf16 v[76:79], v[178:181], v[226:229], v[76:79]
	v_mfma_f32_16x16x32_bf16 v[124:127], v[174:177], v[206:209], v[124:127]
	v_mfma_f32_16x16x32_bf16 v[120:123], v[182:185], v[206:209], v[120:123]
	v_mfma_f32_16x16x32_bf16 v[108:111], v[174:177], v[214:217], v[108:111]
	v_mfma_f32_16x16x32_bf16 v[104:107], v[182:185], v[214:217], v[104:107]
	v_mfma_f32_16x16x32_bf16 v[92:95], v[174:177], v[222:225], v[92:95]
	v_mfma_f32_16x16x32_bf16 v[88:91], v[182:185], v[222:225], v[88:91]
	v_mfma_f32_16x16x32_bf16 v[80:83], v[174:177], v[230:233], v[80:83]
	v_mfma_f32_16x16x32_bf16 v[76:79], v[182:185], v[230:233], v[76:79]
	s_setprio 0
	s_setprio 1
	v_mfma_f32_16x16x32_bf16 v[116:119], v[186:189], v[202:205], v[116:119]
	v_mfma_f32_16x16x32_bf16 v[112:115], v[194:197], v[202:205], v[112:115]
	v_mfma_f32_16x16x32_bf16 v[100:103], v[186:189], v[210:213], v[100:103]
	v_mfma_f32_16x16x32_bf16 v[96:99], v[194:197], v[210:213], v[96:99]
	v_mfma_f32_16x16x32_bf16 v[84:87], v[186:189], v[218:221], v[84:87]
	v_mfma_f32_16x16x32_bf16 v[72:75], v[194:197], v[218:221], v[72:75]
	v_mfma_f32_16x16x32_bf16 v[68:71], v[186:189], v[226:229], v[68:71]
	v_mfma_f32_16x16x32_bf16 v[64:67], v[194:197], v[226:229], v[64:67]
	v_mfma_f32_16x16x32_bf16 v[116:119], v[190:193], v[206:209], v[116:119]
	v_mfma_f32_16x16x32_bf16 v[112:115], v[198:201], v[206:209], v[112:115]
	v_mfma_f32_16x16x32_bf16 v[100:103], v[190:193], v[214:217], v[100:103]
	v_mfma_f32_16x16x32_bf16 v[96:99], v[198:201], v[214:217], v[96:99]
	v_mfma_f32_16x16x32_bf16 v[84:87], v[190:193], v[222:225], v[84:87]
	v_mfma_f32_16x16x32_bf16 v[72:75], v[198:201], v[222:225], v[72:75]
	v_mfma_f32_16x16x32_bf16 v[68:71], v[190:193], v[230:233], v[68:71]
	v_mfma_f32_16x16x32_bf16 v[64:67], v[198:201], v[230:233], v[64:67]
	s_barrier
	s_setprio 0
	s_add_i32 s9, s9, s0
	v_lshl_add_u64 v[160:161], s[58:59], 0, v[146:147]
	s_mov_b32 m0, s9
	ds_read_b128 v[202:205], v142 offset:16384
	ds_read_b128 v[206:209], v142 offset:17408
	ds_read_b128 v[210:213], v142 offset:18432
	ds_read_b128 v[214:217], v142 offset:19456
	ds_read_b128 v[218:221], v142 offset:20480
	ds_read_b128 v[222:225], v142 offset:21504
	ds_read_b128 v[226:229], v142 offset:22528
	ds_read_b128 v[230:233], v142 offset:23552
	global_load_lds_dwordx4 v[160:161], off
	s_add_i32 m0, s9, 0x2000
	s_add_u32 s62, s58, 0xb0000
	v_lshl_add_u64 v[234:235], s[58:59], 0, v[128:129]
	s_addc_u32 s63, s59, 0
	s_add_i32 s9, vcc_hi, s0
	global_load_lds_dwordx4 v[234:235], off
	v_lshl_add_u64 v[236:237], s[62:63], 0, v[146:147]
	s_mov_b32 m0, s9
	v_lshl_add_u64 v[238:239], s[60:61], 0, v[130:131]
	global_load_lds_dwordx4 v[236:237], off
	v_lshl_add_u64 v[236:237], s[62:63], 0, v[128:129]
	s_add_i32 m0, s9, 0x2000
	s_nop 0
	global_load_lds_dwordx4 v[236:237], off
	v_lshl_add_u64 v[236:237], s[60:61], 0, v[132:133]
	s_mov_b32 m0, s67
	s_nop 0
	global_load_lds_dwordx4 v[236:237], off
	s_mov_b32 m0, s68
	s_nop 0
	global_load_lds_dwordx4 v[238:239], off
	s_waitcnt vmcnt(8)
	s_waitcnt lgkmcnt(0)
	s_setprio 1
	s_barrier
; #define PG8_STAGE(bufoff, gbase, voff) do { _Pragma("unroll") for (int _i = 0; _i < 2; ++_i) \
;         __builtin_amdgcn_global_load_lds((const unsigned*)((const char*)(gbase) + (voff)[_i]), (PG8_LAS unsigned*)(lds + (bufoff) + ldsw + _i * 8192), 16, 0, 0); } while (0)
; #define PG8_LDA(dst, b, h) do { _Pragma("unroll") for (int m = 0; m < 4; ++m) _Pragma("unroll") for (int k = 0; k < 2; ++k) dst[m][k] = *(const PG8_LAS bf16x8*)(lds + PG8_SA(b, h) + aoff + m * 2048 + k * 1024); } while (0)
; #define PG8_LDB(dst, b, h) do { _Pragma("unroll") for (int n = 0; n < 2; ++n) _Pragma("unroll") for (int k = 0; k < 2; ++k) dst[n][k] = *(const PG8_LAS bf16x8*)(lds + PG8_SB(b, h) + boff + n * 2048 + k * 1024); } while (0)
; #define PG8_MMA(ai, bj, At, Bt) do { __builtin_amdgcn_s_setprio(1); _Pragma("unroll") for (int m = 0; m < 4; ++m) _Pragma("unroll") for (int n = 0; n < 2; ++n) _Pragma("unroll") for (int k = 0; k < 2; ++k) \
;         acc[ai][bj][m][n] = __builtin_amdgcn_mfma_f32_16x16x32_bf16(Bt[n][k], At[m][k], acc[ai][bj][m][n], 0, 0, 0); __builtin_amdgcn_s_setprio(0); } while (0)
; #define PG8_WAIT_V(n) asm volatile("s_waitcnt vmcnt(" #n ")" ::: "memory")
; #define PG8_WAIT_L(n) asm volatile("s_waitcnt lgkmcnt(" #n ")" ::: "memory")
; #define PG8_BAR __builtin_amdgcn_s_barrier()
; #define PG8_SCHED __builtin_amdgcn_sched_barrier(0)
; template <class Epi, class Sched, bool ALIGN_EPI = false, bool SP2 = false>
; __device__ __forceinline__ void gemm_phase(PG8_LAS unsigned char* lds, const Gemm g, const Sched& S, const Epi& E, const int wid) {
;     ...
;             PG8_WAIT_V(8); PG8_WAIT_L(0); PG8_BAR; PG8_MMA(1, 0, At, B0); PG8_MMA(1, 1, At, B1); PG8_BAR; PG8_SCHED;
;             PG8_LDB(B0, 1, 0); PG8_LDB(B1, 1, 1); PG8_SCHED; PG8_LDA(At, 1, 0); PG8_STAGE(PG8_SA(0, 1), a2 + hstepA, voffA);
;             PG8_WAIT_V(8); PG8_WAIT_L(0); PG8_BAR; PG8_MMA(0, 0, At, B0); PG8_MMA(0, 1, At, B1); PG8_BAR; PG8_SCHED;
	v_mfma_f32_16x16x32_bf16 v[56:59], v[170:173], v[202:205], v[56:59]
	v_mfma_f32_16x16x32_bf16 v[44:47], v[178:181], v[202:205], v[44:47]
	v_mfma_f32_16x16x32_bf16 v[32:35], v[170:173], v[210:213], v[32:35]
	v_mfma_f32_16x16x32_bf16 v[16:19], v[178:181], v[210:213], v[16:19]
	v_mfma_f32_16x16x32_bf16 v[60:63], v[170:173], v[218:221], v[60:63]
	v_mfma_f32_16x16x32_bf16 v[48:51], v[178:181], v[218:221], v[48:51]
	v_mfma_f32_16x16x32_bf16 v[40:43], v[170:173], v[226:229], v[40:43]
	v_mfma_f32_16x16x32_bf16 v[24:27], v[178:181], v[226:229], v[24:27]
	v_mfma_f32_16x16x32_bf16 v[56:59], v[174:177], v[206:209], v[56:59]
	v_mfma_f32_16x16x32_bf16 v[44:47], v[182:185], v[206:209], v[44:47]
	v_mfma_f32_16x16x32_bf16 v[32:35], v[174:177], v[214:217], v[32:35]
	v_mfma_f32_16x16x32_bf16 v[16:19], v[182:185], v[214:217], v[16:19]
	v_mfma_f32_16x16x32_bf16 v[60:63], v[174:177], v[222:225], v[60:63]
	v_mfma_f32_16x16x32_bf16 v[48:51], v[182:185], v[222:225], v[48:51]
	v_mfma_f32_16x16x32_bf16 v[40:43], v[174:177], v[230:233], v[40:43]
	v_mfma_f32_16x16x32_bf16 v[24:27], v[182:185], v[230:233], v[24:27]
	s_setprio 0
	s_setprio 1
	v_mfma_f32_16x16x32_bf16 v[28:31], v[186:189], v[202:205], v[28:31]
	v_mfma_f32_16x16x32_bf16 v[12:15], v[194:197], v[202:205], v[12:15]
	v_mfma_f32_16x16x32_bf16 v[4:7], v[186:189], v[210:213], v[4:7]
	v_mfma_f32_16x16x32_bf16 v[52:55], v[194:197], v[210:213], v[52:55]
	v_mfma_f32_16x16x32_bf16 v[36:39], v[186:189], v[218:221], v[36:39]
	v_mfma_f32_16x16x32_bf16 v[20:23], v[194:197], v[218:221], v[20:23]
	v_mfma_f32_16x16x32_bf16 v[8:11], v[186:189], v[226:229], v[8:11]
	v_mfma_f32_16x16x32_bf16 v[0:3], v[194:197], v[226:229], v[0:3]
	v_mfma_f32_16x16x32_bf16 v[28:31], v[190:193], v[206:209], v[28:31]
	v_mfma_f32_16x16x32_bf16 v[12:15], v[198:201], v[206:209], v[12:15]
	v_mfma_f32_16x16x32_bf16 v[4:7], v[190:193], v[214:217], v[4:7]
	v_mfma_f32_16x16x32_bf16 v[52:55], v[198:201], v[214:217], v[52:55]
	v_mfma_f32_16x16x32_bf16 v[36:39], v[190:193], v[222:225], v[36:39]
	v_mfma_f32_16x16x32_bf16 v[20:23], v[198:201], v[222:225], v[20:23]
	v_mfma_f32_16x16x32_bf16 v[8:11], v[190:193], v[230:233], v[8:11]
	v_mfma_f32_16x16x32_bf16 v[0:3], v[198:201], v[230:233], v[0:3]
	s_barrier
	s_setprio 0
	s_add_i32 s9, 0, 0x18000
	v_add_u32_e32 v143, s9, v141
	s_add_i32 s62, 0, 0x1c000
	ds_read_b128 v[170:173], v143
	ds_read_b128 v[174:177], v143 offset:1024
	ds_read_b128 v[178:181], v143 offset:2048
	ds_read_b128 v[182:185], v143 offset:3072
	v_add_u32_e32 v143, s62, v141
	ds_read_b128 v[186:189], v143
	ds_read_b128 v[190:193], v143 offset:1024
	ds_read_b128 v[194:197], v143 offset:2048
	ds_read_b128 v[198:201], v143 offset:3072
	s_add_u32 s60, s60, 0xb0000
	s_addc_u32 s61, s61, 0
	s_mov_b32 m0, s69
	v_lshl_add_u64 v[240:241], s[60:61], 0, v[132:133]
	ds_read_b128 v[202:205], v142 offset:32768
	ds_read_b128 v[206:209], v142 offset:33792
	ds_read_b128 v[210:213], v142 offset:34816
	ds_read_b128 v[214:217], v142 offset:35840
	ds_read_b128 v[218:221], v142 offset:36864
	ds_read_b128 v[222:225], v142 offset:37888
	ds_read_b128 v[226:229], v142 offset:38912
	ds_read_b128 v[230:233], v142 offset:39936
	global_load_lds_dwordx4 v[240:241], off
	v_lshl_add_u64 v[240:241], s[60:61], 0, v[130:131]
	s_mov_b32 m0, s70
	s_nop 0
	global_load_lds_dwordx4 v[240:241], off
	s_waitcnt vmcnt(8)
	s_waitcnt lgkmcnt(0)
	s_setprio 1
	s_barrier
	v_mfma_f32_16x16x32_bf16 v[124:127], v[170:173], v[202:205], v[124:127]
	v_mfma_f32_16x16x32_bf16 v[120:123], v[178:181], v[202:205], v[120:123]
	v_mfma_f32_16x16x32_bf16 v[108:111], v[170:173], v[210:213], v[108:111]
	v_mfma_f32_16x16x32_bf16 v[104:107], v[178:181], v[210:213], v[104:107]
	v_mfma_f32_16x16x32_bf16 v[92:95], v[170:173], v[218:221], v[92:95]
	v_mfma_f32_16x16x32_bf16 v[88:91], v[178:181], v[218:221], v[88:91]
	v_mfma_f32_16x16x32_bf16 v[80:83], v[170:173], v[226:229], v[80:83]
	v_mfma_f32_16x16x32_bf16 v[76:79], v[178:181], v[226:229], v[76:79]
	v_mfma_f32_16x16x32_bf16 v[124:127], v[174:177], v[206:209], v[124:127]
	v_mfma_f32_16x16x32_bf16 v[120:123], v[182:185], v[206:209], v[120:123]
	v_mfma_f32_16x16x32_bf16 v[108:111], v[174:177], v[214:217], v[108:111]
	v_mfma_f32_16x16x32_bf16 v[104:107], v[182:185], v[214:217], v[104:107]
	v_mfma_f32_16x16x32_bf16 v[92:95], v[174:177], v[222:225], v[92:95]
	v_mfma_f32_16x16x32_bf16 v[88:91], v[182:185], v[222:225], v[88:91]
	v_mfma_f32_16x16x32_bf16 v[80:83], v[174:177], v[230:233], v[80:83]
	v_mfma_f32_16x16x32_bf16 v[76:79], v[182:185], v[230:233], v[76:79]
	s_setprio 0
	s_setprio 1
	v_mfma_f32_16x16x32_bf16 v[116:119], v[186:189], v[202:205], v[116:119]
	v_mfma_f32_16x16x32_bf16 v[112:115], v[194:197], v[202:205], v[112:115]
	v_mfma_f32_16x16x32_bf16 v[100:103], v[186:189], v[210:213], v[100:103]
	v_mfma_f32_16x16x32_bf16 v[96:99], v[194:197], v[210:213], v[96:99]
	v_mfma_f32_16x16x32_bf16 v[84:87], v[186:189], v[218:221], v[84:87]
	v_mfma_f32_16x16x32_bf16 v[72:75], v[194:197], v[218:221], v[72:75]
	v_mfma_f32_16x16x32_bf16 v[68:71], v[186:189], v[226:229], v[68:71]
	v_mfma_f32_16x16x32_bf16 v[64:67], v[194:197], v[226:229], v[64:67]
	v_mfma_f32_16x16x32_bf16 v[116:119], v[190:193], v[206:209], v[116:119]
	v_mfma_f32_16x16x32_bf16 v[112:115], v[198:201], v[206:209], v[112:115]
	v_mfma_f32_16x16x32_bf16 v[100:103], v[190:193], v[214:217], v[100:103]
	v_mfma_f32_16x16x32_bf16 v[96:99], v[198:201], v[214:217], v[96:99]
	v_mfma_f32_16x16x32_bf16 v[84:87], v[190:193], v[222:225], v[84:87]
	v_mfma_f32_16x16x32_bf16 v[72:75], v[198:201], v[222:225], v[72:75]
	v_mfma_f32_16x16x32_bf16 v[68:71], v[190:193], v[230:233], v[68:71]
	v_mfma_f32_16x16x32_bf16 v[64:67], v[198:201], v[230:233], v[64:67]
	s_barrier
; #define PG8_STAGE(bufoff, gbase, voff) do { _Pragma("unroll") for (int _i = 0; _i < 2; ++_i) \
;         __builtin_amdgcn_global_load_lds((const unsigned*)((const char*)(gbase) + (voff)[_i]), (PG8_LAS unsigned*)(lds + (bufoff) + ldsw + _i * 8192), 16, 0, 0); } while (0)
; #define PG8_LDA(dst, b, h) do { _Pragma("unroll") for (int m = 0; m < 4; ++m) _Pragma("unroll") for (int k = 0; k < 2; ++k) dst[m][k] = *(const PG8_LAS bf16x8*)(lds + PG8_SA(b, h) + aoff + m * 2048 + k * 1024); } while (0)
; #define PG8_MMA(ai, bj, At, Bt) do { __builtin_amdgcn_s_setprio(1); _Pragma("unroll") for (int m = 0; m < 4; ++m) _Pragma("unroll") for (int n = 0; n < 2; ++n) _Pragma("unroll") for (int k = 0; k < 2; ++k) \
;         acc[ai][bj][m][n] = __builtin_amdgcn_mfma_f32_16x16x32_bf16(Bt[n][k], At[m][k], acc[ai][bj][m][n], 0, 0, 0); __builtin_amdgcn_s_setprio(0); } while (0)
; #define PG8_WAIT_V(n) asm volatile("s_waitcnt vmcnt(" #n ")" ::: "memory")
; #define PG8_WAIT_L(n) asm volatile("s_waitcnt lgkmcnt(" #n ")" ::: "memory")
; #define PG8_BAR __builtin_amdgcn_s_barrier()
; #define PG8_SCHED __builtin_amdgcn_sched_barrier(0)
; template <class Epi, class Sched, bool ALIGN_EPI = false, bool SP2 = false>
; __device__ __forceinline__ void gemm_phase(PG8_LAS unsigned char* lds, const Gemm g, const Sched& S, const Epi& E, const int wid) {
;     ...
;         for (int t = 0; t < nt; t += 2) {
;             const bool last = (t == nt - 2);
;             const char* a1 = cA + (size_t)(t + 1) * kstep;
;             const char* a2 = last ? nA : cA + (size_t)(t + 2) * kstep; const char* b2 = last ? nB : cB + (size_t)(t + 2) * kstep;
;     ...
;             PG8_LDA(At, 1, 1); PG8_STAGE(PG8_SB(1, 0), b3, voffB); PG8_STAGE(PG8_SB(1, 1), b3 + hstepB, voffB); PG8_STAGE(PG8_SA(1, 0), a3, voffA);
;             PG8_WAIT_V(8); PG8_WAIT_L(0); PG8_BAR; PG8_MMA(1, 0, At, B0); PG8_MMA(1, 1, At, B1); PG8_BAR; PG8_SCHED;
	s_setprio 0
	s_add_i32 s9, s9, s0
	v_lshl_add_u64 v[160:161], v[160:161], 0, s[80:81]
	s_mov_b32 m0, s9
	ds_read_b128 v[202:205], v142 offset:49152
	ds_read_b128 v[206:209], v142 offset:50176
	ds_read_b128 v[210:213], v142 offset:51200
	ds_read_b128 v[214:217], v142 offset:52224
	ds_read_b128 v[218:221], v142 offset:53248
	ds_read_b128 v[222:225], v142 offset:54272
	ds_read_b128 v[226:229], v142 offset:55296
	ds_read_b128 v[230:233], v142 offset:56320
	global_load_lds_dwordx4 v[160:161], off
	s_add_i32 m0, s9, 0x2000
	s_add_u32 s58, s58, 0xb0080
	v_lshl_add_u64 v[160:161], v[234:235], 0, s[80:81]
	s_addc_u32 s59, s59, 0
	s_add_i32 s9, s62, s0
	global_load_lds_dwordx4 v[160:161], off
	v_lshl_add_u64 v[160:161], s[58:59], 0, v[146:147]
	s_mov_b32 m0, s9
	s_nop 0
	global_load_lds_dwordx4 v[160:161], off
	v_lshl_add_u64 v[160:161], s[58:59], 0, v[128:129]
	s_add_i32 m0, s9, 0x2000
	s_nop 0
	global_load_lds_dwordx4 v[160:161], off
	v_lshl_add_u64 v[160:161], v[236:237], 0, s[80:81]
	s_mov_b32 m0, s71
	s_nop 0
	global_load_lds_dwordx4 v[160:161], off
	v_lshl_add_u64 v[160:161], v[238:239], 0, s[80:81]
	s_mov_b32 m0, s72
	s_nop 0
	global_load_lds_dwordx4 v[160:161], off
	s_waitcnt vmcnt(8)
	s_waitcnt lgkmcnt(0)
	s_setprio 1
	s_barrier
	v_mfma_f32_16x16x32_bf16 v[56:59], v[170:173], v[202:205], v[56:59]
	v_mfma_f32_16x16x32_bf16 v[44:47], v[178:181], v[202:205], v[44:47]
	v_mfma_f32_16x16x32_bf16 v[32:35], v[170:173], v[210:213], v[32:35]
	v_mfma_f32_16x16x32_bf16 v[16:19], v[178:181], v[210:213], v[16:19]
	v_mfma_f32_16x16x32_bf16 v[60:63], v[170:173], v[218:221], v[60:63]
	v_mfma_f32_16x16x32_bf16 v[48:51], v[178:181], v[218:221], v[48:51]
	v_mfma_f32_16x16x32_bf16 v[40:43], v[170:173], v[226:229], v[40:43]
	v_mfma_f32_16x16x32_bf16 v[24:27], v[178:181], v[226:229], v[24:27]
	v_mfma_f32_16x16x32_bf16 v[56:59], v[174:177], v[206:209], v[56:59]
	v_mfma_f32_16x16x32_bf16 v[44:47], v[182:185], v[206:209], v[44:47]
	v_mfma_f32_16x16x32_bf16 v[32:35], v[174:177], v[214:217], v[32:35]
	v_mfma_f32_16x16x32_bf16 v[16:19], v[182:185], v[214:217], v[16:19]
	v_mfma_f32_16x16x32_bf16 v[60:63], v[174:177], v[222:225], v[60:63]
	v_mfma_f32_16x16x32_bf16 v[48:51], v[182:185], v[222:225], v[48:51]
	v_mfma_f32_16x16x32_bf16 v[40:43], v[174:177], v[230:233], v[40:43]
	v_mfma_f32_16x16x32_bf16 v[24:27], v[182:185], v[230:233], v[24:27]
	s_setprio 0
	s_setprio 1
	v_mfma_f32_16x16x32_bf16 v[28:31], v[186:189], v[202:205], v[28:31]
	v_mfma_f32_16x16x32_bf16 v[12:15], v[194:197], v[202:205], v[12:15]
	v_mfma_f32_16x16x32_bf16 v[4:7], v[186:189], v[210:213], v[4:7]
	v_mfma_f32_16x16x32_bf16 v[52:55], v[194:197], v[210:213], v[52:55]
	v_mfma_f32_16x16x32_bf16 v[36:39], v[186:189], v[218:221], v[36:39]
	v_mfma_f32_16x16x32_bf16 v[20:23], v[194:197], v[218:221], v[20:23]
	v_mfma_f32_16x16x32_bf16 v[8:11], v[186:189], v[226:229], v[8:11]
	v_mfma_f32_16x16x32_bf16 v[0:3], v[194:197], v[226:229], v[0:3]
	v_mfma_f32_16x16x32_bf16 v[28:31], v[190:193], v[206:209], v[28:31]
	v_mfma_f32_16x16x32_bf16 v[12:15], v[198:201], v[206:209], v[12:15]
	v_mfma_f32_16x16x32_bf16 v[4:7], v[190:193], v[214:217], v[4:7]
	v_mfma_f32_16x16x32_bf16 v[52:55], v[198:201], v[214:217], v[52:55]
	v_mfma_f32_16x16x32_bf16 v[36:39], v[190:193], v[222:225], v[36:39]
	v_mfma_f32_16x16x32_bf16 v[20:23], v[198:201], v[222:225], v[20:23]
	v_mfma_f32_16x16x32_bf16 v[8:11], v[190:193], v[230:233], v[8:11]
	v_mfma_f32_16x16x32_bf16 v[0:3], v[198:201], v[230:233], v[0:3]
	s_barrier
	s_setprio 0
	s_add_u32 s82, s82, 0x100
	s_addc_u32 s83, s83, 0
	s_cmp_ge_i32 vcc_lo, s5
	s_mov_b64 s[62:63], s[56:57]
	s_mov_b32 s58, vcc_lo
	s_cbranch_scc0 .LBB0_575
	s_mov_b32 s63, 0xe000
	s_mov_b32 s82, 0x24000
	s_mov_b32 s83, 0x26000
	s_mov_b32 s59, 0x28000
	s_mov_b32 s58, 0x2a000
	s_mov_b32 s61, 0x2c000
	s_mov_b32 s60, 0x32000
	s_mov_b32 s56, 0x34000
	s_mov_b32 s57, 0x36000
	s_and_b64 vcc, exec, s[44:45]
	s_cbranch_vccnz .LBB0_561

; #define PG8_STAGE(bufoff, gbase, voff) do { _Pragma("unroll") for (int _i = 0; _i < 2; ++_i) \
;         __builtin_amdgcn_global_load_lds((const unsigned*)((const char*)(gbase) + (voff)[_i]), (PG8_LAS unsigned*)(lds + (bufoff) + ldsw + _i * 8192), 16, 0, 0); } while (0)
; #define PG8_LDA(dst, b, h) do { _Pragma("unroll") for (int m = 0; m < 4; ++m) _Pragma("unroll") for (int k = 0; k < 2; ++k) dst[m][k] = *(const PG8_LAS bf16x8*)(lds + PG8_SA(b, h) + aoff + m * 2048 + k * 1024); } while (0)
; #define PG8_LDB(dst, b, h) do { _Pragma("unroll") for (int n = 0; n < 2; ++n) _Pragma("unroll") for (int k = 0; k < 2; ++k) dst[n][k] = *(const PG8_LAS bf16x8*)(lds + PG8_SB(b, h) + boff + n * 2048 + k * 1024); } while (0)
; #define PG8_MMA(ai, bj, At, Bt) do { __builtin_amdgcn_s_setprio(1); _Pragma("unroll") for (int m = 0; m < 4; ++m) _Pragma("unroll") for (int n = 0; n < 2; ++n) _Pragma("unroll") for (int k = 0; k < 2; ++k) \
;         acc[ai][bj][m][n] = __builtin_amdgcn_mfma_f32_16x16x32_bf16(Bt[n][k], At[m][k], acc[ai][bj][m][n], 0, 0, 0); __builtin_amdgcn_s_setprio(0); } while (0)
; #define PG8_WAIT_V(n) asm volatile("s_waitcnt vmcnt(" #n ")" ::: "memory")
; #define PG8_BAR __builtin_amdgcn_s_barrier()
; template <class Epi, class Sched, bool ALIGN_EPI = false, bool SP2 = false>
; __device__ __forceinline__ void gemm_phase(PG8_LAS unsigned char* lds, const Gemm g, const Sched& S, const Epi& E, const int wid) {
;     ...
;         for (int t = 0; t < nt; t += 2) {
;             const bool last = (t == nt - 2);
;             const char* a1 = cA + (size_t)(t + 1) * kstep;
;             const char* a2 = last ? nA : cA + (size_t)(t + 2) * kstep; const char* b2 = last ? nB : cB + (size_t)(t + 2) * kstep;
;             const char* a3 = a2 + kstep; const char* b3 = b2 + kstep;
;             if (last && has_next) S.a_ready(nxt);
;             if constexpr (SP2) {
;             PG8_LDB(B0, 0, 0); PG8_LDB(B1, 0, 1); PG8_SCHED; PG8_LDA(At, 0, 0); PG8_STAGE(PG8_SA(1, 1), a1 + hstepA, voffA);
;             PG8_WAIT_V(8); PG8_WAIT_L(0); PG8_BAR; PG8_MMA(0, 0, At, B0); PG8_MMA(0, 1, At, B1); PG8_BAR; PG8_SCHED;
;             PG8_LDA(At, 0, 1); PG8_STAGE(PG8_SB(0, 0), b2, voffB); PG8_STAGE(PG8_SB(0, 1), b2 + hstepB, voffB); PG8_STAGE(PG8_SA(0, 0), a2, voffA);
;             PG8_WAIT_V(8); PG8_WAIT_L(0); PG8_BAR; PG8_MMA(1, 0, At, B0); PG8_MMA(1, 1, At, B1); PG8_BAR; PG8_SCHED;
.LBB0_630:
	s_add_i32 vcc_lo, s58, 2
	s_add_u32 s56, s62, 0x100
	s_addc_u32 s57, s63, 0
	s_add_i32 vcc_hi, 0, 0x10000
	s_cmp_eq_u32 s73, s58
	s_cselect_b32 s61, s47, s57
	s_cselect_b32 s60, s46, s56
	s_cselect_b32 s59, s55, s83
	s_cselect_b32 s58, s54, s82
	s_add_i32 s9, 0, 0x14000
	v_add_u32_e32 v178, vcc_hi, v142
	v_add_u32_e32 v194, s9, v142
	ds_read_b128 v[160:163], v178
	ds_read_b128 v[170:173], v178 offset:1024
	ds_read_b128 v[174:177], v178 offset:2048
	ds_read_b128 v[178:181], v178 offset:3072
	ds_read_b128 v[182:185], v194
	ds_read_b128 v[186:189], v194 offset:1024
	ds_read_b128 v[190:193], v194 offset:2048
	ds_read_b128 v[194:197], v194 offset:3072
	v_lshl_add_u64 v[230:231], s[62:63], 0, v[134:135]
	s_add_i32 m0, s66, 0xc000
	ds_read_b128 v[198:201], v143
	ds_read_b128 v[202:205], v143 offset:1024
	ds_read_b128 v[206:209], v143 offset:2048
	ds_read_b128 v[210:213], v143 offset:3072
	ds_read_b128 v[214:217], v143 offset:4096
	ds_read_b128 v[218:221], v143 offset:5120
	ds_read_b128 v[222:225], v143 offset:6144
	ds_read_b128 v[226:229], v143 offset:7168
	global_load_lds_dwordx4 v[230:231], off
	v_lshl_add_u64 v[230:231], s[62:63], 0, v[136:137]
	s_add_i32 m0, s66, 0xe000
	s_nop 0
	global_load_lds_dwordx4 v[230:231], off
	s_waitcnt vmcnt(8)
	s_waitcnt lgkmcnt(0)
	s_setprio 1
	s_barrier
	v_mfma_f32_16x16x32_bf16 v[124:127], v[160:163], v[198:201], v[124:127]
	v_mfma_f32_16x16x32_bf16 v[120:123], v[174:177], v[198:201], v[120:123]
	v_mfma_f32_16x16x32_bf16 v[108:111], v[160:163], v[206:209], v[108:111]
	v_mfma_f32_16x16x32_bf16 v[104:107], v[174:177], v[206:209], v[104:107]
	v_mfma_f32_16x16x32_bf16 v[100:103], v[160:163], v[214:217], v[100:103]
	v_mfma_f32_16x16x32_bf16 v[92:95], v[174:177], v[214:217], v[92:95]
	v_mfma_f32_16x16x32_bf16 v[84:87], v[160:163], v[222:225], v[84:87]
	v_mfma_f32_16x16x32_bf16 v[76:79], v[174:177], v[222:225], v[76:79]
	v_mfma_f32_16x16x32_bf16 v[124:127], v[170:173], v[202:205], v[124:127]
	v_mfma_f32_16x16x32_bf16 v[120:123], v[178:181], v[202:205], v[120:123]
	v_mfma_f32_16x16x32_bf16 v[108:111], v[170:173], v[210:213], v[108:111]
	v_mfma_f32_16x16x32_bf16 v[104:107], v[178:181], v[210:213], v[104:107]
	v_mfma_f32_16x16x32_bf16 v[100:103], v[170:173], v[218:221], v[100:103]
	v_mfma_f32_16x16x32_bf16 v[92:95], v[178:181], v[218:221], v[92:95]
	v_mfma_f32_16x16x32_bf16 v[84:87], v[170:173], v[226:229], v[84:87]
	v_mfma_f32_16x16x32_bf16 v[76:79], v[178:181], v[226:229], v[76:79]
	s_setprio 0
	s_setprio 1
	v_mfma_f32_16x16x32_bf16 v[116:119], v[182:185], v[198:201], v[116:119]
	v_mfma_f32_16x16x32_bf16 v[112:115], v[190:193], v[198:201], v[112:115]
	v_mfma_f32_16x16x32_bf16 v[96:99], v[182:185], v[206:209], v[96:99]
	v_mfma_f32_16x16x32_bf16 v[88:91], v[190:193], v[206:209], v[88:91]
	v_mfma_f32_16x16x32_bf16 v[80:83], v[182:185], v[214:217], v[80:83]
	v_mfma_f32_16x16x32_bf16 v[72:75], v[190:193], v[214:217], v[72:75]
	v_mfma_f32_16x16x32_bf16 v[68:71], v[182:185], v[222:225], v[68:71]
	v_mfma_f32_16x16x32_bf16 v[60:63], v[190:193], v[222:225], v[60:63]
	v_mfma_f32_16x16x32_bf16 v[116:119], v[186:189], v[202:205], v[116:119]
	v_mfma_f32_16x16x32_bf16 v[112:115], v[194:197], v[202:205], v[112:115]
	v_mfma_f32_16x16x32_bf16 v[96:99], v[186:189], v[210:213], v[96:99]
	v_mfma_f32_16x16x32_bf16 v[88:91], v[194:197], v[210:213], v[88:91]
	v_mfma_f32_16x16x32_bf16 v[80:83], v[186:189], v[218:221], v[80:83]
	v_mfma_f32_16x16x32_bf16 v[72:75], v[194:197], v[218:221], v[72:75]
	v_mfma_f32_16x16x32_bf16 v[68:71], v[186:189], v[226:229], v[68:71]
	v_mfma_f32_16x16x32_bf16 v[60:63], v[194:197], v[226:229], v[60:63]
	s_barrier
	s_setprio 0
	s_add_i32 s62, vcc_hi, s0
	v_lshl_add_u64 v[230:231], s[58:59], 0, v[146:147]
	s_mov_b32 m0, s62
	ds_read_b128 v[198:201], v143 offset:16384
	ds_read_b128 v[202:205], v143 offset:17408
	ds_read_b128 v[206:209], v143 offset:18432
	ds_read_b128 v[210:213], v143 offset:19456
	ds_read_b128 v[214:217], v143 offset:20480
	ds_read_b128 v[218:221], v143 offset:21504
	ds_read_b128 v[222:225], v143 offset:22528
	ds_read_b128 v[226:229], v143 offset:23552
	global_load_lds_dwordx4 v[230:231], off
	s_add_i32 m0, s62, 0x2000
	s_add_u32 s62, s58, 0xb0000
	v_lshl_add_u64 v[232:233], s[58:59], 0, v[128:129]
	s_addc_u32 s63, s59, 0
	s_add_i32 s9, s9, s0
	global_load_lds_dwordx4 v[232:233], off
	v_lshl_add_u64 v[234:235], s[62:63], 0, v[146:147]
	s_mov_b32 m0, s9
	v_lshl_add_u64 v[236:237], s[60:61], 0, v[130:131]
	global_load_lds_dwordx4 v[234:235], off
	v_lshl_add_u64 v[234:235], s[62:63], 0, v[128:129]
	s_add_i32 m0, s9, 0x2000
	s_nop 0
	global_load_lds_dwordx4 v[234:235], off
	v_lshl_add_u64 v[234:235], s[60:61], 0, v[132:133]
	s_mov_b32 m0, s66
	s_nop 0
	global_load_lds_dwordx4 v[234:235], off
	s_mov_b32 m0, s67
	s_nop 0
	global_load_lds_dwordx4 v[236:237], off
	s_waitcnt vmcnt(8)
	s_waitcnt lgkmcnt(0)
	s_setprio 1
	s_barrier
; #define PG8_STAGE(bufoff, gbase, voff) do { _Pragma("unroll") for (int _i = 0; _i < 2; ++_i) \
;         __builtin_amdgcn_global_load_lds((const unsigned*)((const char*)(gbase) + (voff)[_i]), (PG8_LAS unsigned*)(lds + (bufoff) + ldsw + _i * 8192), 16, 0, 0); } while (0)
; #define PG8_LDA(dst, b, h) do { _Pragma("unroll") for (int m = 0; m < 4; ++m) _Pragma("unroll") for (int k = 0; k < 2; ++k) dst[m][k] = *(const PG8_LAS bf16x8*)(lds + PG8_SA(b, h) + aoff + m * 2048 + k * 1024); } while (0)
; #define PG8_LDB(dst, b, h) do { _Pragma("unroll") for (int n = 0; n < 2; ++n) _Pragma("unroll") for (int k = 0; k < 2; ++k) dst[n][k] = *(const PG8_LAS bf16x8*)(lds + PG8_SB(b, h) + boff + n * 2048 + k * 1024); } while (0)
; #define PG8_MMA(ai, bj, At, Bt) do { __builtin_amdgcn_s_setprio(1); _Pragma("unroll") for (int m = 0; m < 4; ++m) _Pragma("unroll") for (int n = 0; n < 2; ++n) _Pragma("unroll") for (int k = 0; k < 2; ++k) \
;         acc[ai][bj][m][n] = __builtin_amdgcn_mfma_f32_16x16x32_bf16(Bt[n][k], At[m][k], acc[ai][bj][m][n], 0, 0, 0); __builtin_amdgcn_s_setprio(0); } while (0)
; #define PG8_WAIT_V(n) asm volatile("s_waitcnt vmcnt(" #n ")" ::: "memory")
; #define PG8_WAIT_L(n) asm volatile("s_waitcnt lgkmcnt(" #n ")" ::: "memory")
; #define PG8_BAR __builtin_amdgcn_s_barrier()
; #define PG8_SCHED __builtin_amdgcn_sched_barrier(0)
; template <class Epi, class Sched, bool ALIGN_EPI = false, bool SP2 = false>
; __device__ __forceinline__ void gemm_phase(PG8_LAS unsigned char* lds, const Gemm g, const Sched& S, const Epi& E, const int wid) {
;     ...
;             PG8_WAIT_V(8); PG8_WAIT_L(0); PG8_BAR; PG8_MMA(1, 0, At, B0); PG8_MMA(1, 1, At, B1); PG8_BAR; PG8_SCHED;
;             PG8_LDB(B0, 1, 0); PG8_LDB(B1, 1, 1); PG8_SCHED; PG8_LDA(At, 1, 0); PG8_STAGE(PG8_SA(0, 1), a2 + hstepA, voffA);
;             PG8_WAIT_V(8); PG8_WAIT_L(0); PG8_BAR; PG8_MMA(0, 0, At, B0); PG8_MMA(0, 1, At, B1); PG8_BAR; PG8_SCHED;
	v_mfma_f32_16x16x32_bf16 v[48:51], v[160:163], v[198:201], v[48:51]
	v_mfma_f32_16x16x32_bf16 v[44:47], v[174:177], v[198:201], v[44:47]
	v_mfma_f32_16x16x32_bf16 v[24:27], v[160:163], v[206:209], v[24:27]
	v_mfma_f32_16x16x32_bf16 v[16:19], v[174:177], v[206:209], v[16:19]
	v_mfma_f32_16x16x32_bf16 v[64:67], v[160:163], v[214:217], v[64:67]
	v_mfma_f32_16x16x32_bf16 v[56:59], v[174:177], v[214:217], v[56:59]
	v_mfma_f32_16x16x32_bf16 v[40:43], v[160:163], v[222:225], v[40:43]
	v_mfma_f32_16x16x32_bf16 v[32:35], v[174:177], v[222:225], v[32:35]
	v_mfma_f32_16x16x32_bf16 v[48:51], v[170:173], v[202:205], v[48:51]
	v_mfma_f32_16x16x32_bf16 v[44:47], v[178:181], v[202:205], v[44:47]
	v_mfma_f32_16x16x32_bf16 v[24:27], v[170:173], v[210:213], v[24:27]
	v_mfma_f32_16x16x32_bf16 v[16:19], v[178:181], v[210:213], v[16:19]
	v_mfma_f32_16x16x32_bf16 v[64:67], v[170:173], v[218:221], v[64:67]
	v_mfma_f32_16x16x32_bf16 v[56:59], v[178:181], v[218:221], v[56:59]
	v_mfma_f32_16x16x32_bf16 v[40:43], v[170:173], v[226:229], v[40:43]
	v_mfma_f32_16x16x32_bf16 v[32:35], v[178:181], v[226:229], v[32:35]
	s_setprio 0
	s_setprio 1
	v_mfma_f32_16x16x32_bf16 v[20:23], v[182:185], v[198:201], v[20:23]
	v_mfma_f32_16x16x32_bf16 v[12:15], v[190:193], v[198:201], v[12:15]
	v_mfma_f32_16x16x32_bf16 v[0:3], v[182:185], v[206:209], v[0:3]
	v_mfma_f32_16x16x32_bf16 v[52:55], v[190:193], v[206:209], v[52:55]
	v_mfma_f32_16x16x32_bf16 v[36:39], v[182:185], v[214:217], v[36:39]
	v_mfma_f32_16x16x32_bf16 v[28:31], v[190:193], v[214:217], v[28:31]
	v_mfma_f32_16x16x32_bf16 v[8:11], v[182:185], v[222:225], v[8:11]
	v_mfma_f32_16x16x32_bf16 v[4:7], v[190:193], v[222:225], v[4:7]
	v_mfma_f32_16x16x32_bf16 v[20:23], v[186:189], v[202:205], v[20:23]
	v_mfma_f32_16x16x32_bf16 v[12:15], v[194:197], v[202:205], v[12:15]
	v_mfma_f32_16x16x32_bf16 v[0:3], v[186:189], v[210:213], v[0:3]
	v_mfma_f32_16x16x32_bf16 v[52:55], v[194:197], v[210:213], v[52:55]
	v_mfma_f32_16x16x32_bf16 v[36:39], v[186:189], v[218:221], v[36:39]
	v_mfma_f32_16x16x32_bf16 v[28:31], v[194:197], v[218:221], v[28:31]
	v_mfma_f32_16x16x32_bf16 v[8:11], v[186:189], v[226:229], v[8:11]
	v_mfma_f32_16x16x32_bf16 v[4:7], v[194:197], v[226:229], v[4:7]
	s_barrier
	s_setprio 0
	s_add_i32 s9, 0, 0x18000
	s_add_i32 s62, 0, 0x1c000
	v_add_u32_e32 v178, s9, v142
	v_add_u32_e32 v194, s62, v142
	ds_read_b128 v[160:163], v178
	ds_read_b128 v[170:173], v178 offset:1024
	ds_read_b128 v[174:177], v178 offset:2048
	ds_read_b128 v[178:181], v178 offset:3072
	ds_read_b128 v[182:185], v194
	ds_read_b128 v[186:189], v194 offset:1024
	ds_read_b128 v[190:193], v194 offset:2048
	ds_read_b128 v[194:197], v194 offset:3072
	s_add_u32 s60, s60, 0xb0000
	s_addc_u32 s61, s61, 0
	s_mov_b32 m0, s68
	v_lshl_add_u64 v[238:239], s[60:61], 0, v[132:133]
	ds_read_b128 v[198:201], v143 offset:32768
	ds_read_b128 v[202:205], v143 offset:33792
	ds_read_b128 v[206:209], v143 offset:34816
	ds_read_b128 v[210:213], v143 offset:35840
	ds_read_b128 v[214:217], v143 offset:36864
	ds_read_b128 v[218:221], v143 offset:37888
	ds_read_b128 v[222:225], v143 offset:38912
	ds_read_b128 v[226:229], v143 offset:39936
	global_load_lds_dwordx4 v[238:239], off
	v_lshl_add_u64 v[238:239], s[60:61], 0, v[130:131]
	s_mov_b32 m0, s69
	s_nop 0
	global_load_lds_dwordx4 v[238:239], off
	s_waitcnt vmcnt(8)
	s_waitcnt lgkmcnt(0)
	s_setprio 1
	s_barrier
	v_mfma_f32_16x16x32_bf16 v[124:127], v[160:163], v[198:201], v[124:127]
	v_mfma_f32_16x16x32_bf16 v[120:123], v[174:177], v[198:201], v[120:123]
	v_mfma_f32_16x16x32_bf16 v[108:111], v[160:163], v[206:209], v[108:111]
	v_mfma_f32_16x16x32_bf16 v[104:107], v[174:177], v[206:209], v[104:107]
	v_mfma_f32_16x16x32_bf16 v[100:103], v[160:163], v[214:217], v[100:103]
	v_mfma_f32_16x16x32_bf16 v[92:95], v[174:177], v[214:217], v[92:95]
	v_mfma_f32_16x16x32_bf16 v[84:87], v[160:163], v[222:225], v[84:87]
	v_mfma_f32_16x16x32_bf16 v[76:79], v[174:177], v[222:225], v[76:79]
	v_mfma_f32_16x16x32_bf16 v[124:127], v[170:173], v[202:205], v[124:127]
	v_mfma_f32_16x16x32_bf16 v[120:123], v[178:181], v[202:205], v[120:123]
	v_mfma_f32_16x16x32_bf16 v[108:111], v[170:173], v[210:213], v[108:111]
	v_mfma_f32_16x16x32_bf16 v[104:107], v[178:181], v[210:213], v[104:107]
	v_mfma_f32_16x16x32_bf16 v[100:103], v[170:173], v[218:221], v[100:103]
	v_mfma_f32_16x16x32_bf16 v[92:95], v[178:181], v[218:221], v[92:95]
	v_mfma_f32_16x16x32_bf16 v[84:87], v[170:173], v[226:229], v[84:87]
	v_mfma_f32_16x16x32_bf16 v[76:79], v[178:181], v[226:229], v[76:79]
	s_setprio 0
	s_setprio 1
	v_mfma_f32_16x16x32_bf16 v[116:119], v[182:185], v[198:201], v[116:119]
	v_mfma_f32_16x16x32_bf16 v[112:115], v[190:193], v[198:201], v[112:115]
	v_mfma_f32_16x16x32_bf16 v[96:99], v[182:185], v[206:209], v[96:99]
	v_mfma_f32_16x16x32_bf16 v[88:91], v[190:193], v[206:209], v[88:91]
	v_mfma_f32_16x16x32_bf16 v[80:83], v[182:185], v[214:217], v[80:83]
	v_mfma_f32_16x16x32_bf16 v[72:75], v[190:193], v[214:217], v[72:75]
	v_mfma_f32_16x16x32_bf16 v[68:71], v[182:185], v[222:225], v[68:71]
	v_mfma_f32_16x16x32_bf16 v[60:63], v[190:193], v[222:225], v[60:63]
	v_mfma_f32_16x16x32_bf16 v[116:119], v[186:189], v[202:205], v[116:119]
	v_mfma_f32_16x16x32_bf16 v[112:115], v[194:197], v[202:205], v[112:115]
	v_mfma_f32_16x16x32_bf16 v[96:99], v[186:189], v[210:213], v[96:99]
	v_mfma_f32_16x16x32_bf16 v[88:91], v[194:197], v[210:213], v[88:91]
	v_mfma_f32_16x16x32_bf16 v[80:83], v[186:189], v[218:221], v[80:83]
	v_mfma_f32_16x16x32_bf16 v[72:75], v[194:197], v[218:221], v[72:75]
	v_mfma_f32_16x16x32_bf16 v[68:71], v[186:189], v[226:229], v[68:71]
	v_mfma_f32_16x16x32_bf16 v[60:63], v[194:197], v[226:229], v[60:63]
	s_barrier
; #define PG8_STAGE(bufoff, gbase, voff) do { _Pragma("unroll") for (int _i = 0; _i < 2; ++_i) \
;         __builtin_amdgcn_global_load_lds((const unsigned*)((const char*)(gbase) + (voff)[_i]), (PG8_LAS unsigned*)(lds + (bufoff) + ldsw + _i * 8192), 16, 0, 0); } while (0)
; #define PG8_LDA(dst, b, h) do { _Pragma("unroll") for (int m = 0; m < 4; ++m) _Pragma("unroll") for (int k = 0; k < 2; ++k) dst[m][k] = *(const PG8_LAS bf16x8*)(lds + PG8_SA(b, h) + aoff + m * 2048 + k * 1024); } while (0)
; #define PG8_MMA(ai, bj, At, Bt) do { __builtin_amdgcn_s_setprio(1); _Pragma("unroll") for (int m = 0; m < 4; ++m) _Pragma("unroll") for (int n = 0; n < 2; ++n) _Pragma("unroll") for (int k = 0; k < 2; ++k) \
;         acc[ai][bj][m][n] = __builtin_amdgcn_mfma_f32_16x16x32_bf16(Bt[n][k], At[m][k], acc[ai][bj][m][n], 0, 0, 0); __builtin_amdgcn_s_setprio(0); } while (0)
; #define PG8_WAIT_V(n) asm volatile("s_waitcnt vmcnt(" #n ")" ::: "memory")
; #define PG8_WAIT_L(n) asm volatile("s_waitcnt lgkmcnt(" #n ")" ::: "memory")
; #define PG8_BAR __builtin_amdgcn_s_barrier()
; #define PG8_SCHED __builtin_amdgcn_sched_barrier(0)
; template <class Epi, class Sched, bool ALIGN_EPI = false, bool SP2 = false>
; __device__ __forceinline__ void gemm_phase(PG8_LAS unsigned char* lds, const Gemm g, const Sched& S, const Epi& E, const int wid) {
;     ...
;         for (int t = 0; t < nt; t += 2) {
;             const bool last = (t == nt - 2);
;             const char* a1 = cA + (size_t)(t + 1) * kstep;
;             const char* a2 = last ? nA : cA + (size_t)(t + 2) * kstep; const char* b2 = last ? nB : cB + (size_t)(t + 2) * kstep;
;     ...
;             PG8_LDA(At, 1, 1); PG8_STAGE(PG8_SB(1, 0), b3, voffB); PG8_STAGE(PG8_SB(1, 1), b3 + hstepB, voffB); PG8_STAGE(PG8_SA(1, 0), a3, voffA);
;             PG8_WAIT_V(8); PG8_WAIT_L(0); PG8_BAR; PG8_MMA(1, 0, At, B0); PG8_MMA(1, 1, At, B1); PG8_BAR; PG8_SCHED;
	s_setprio 0
	s_add_i32 s9, s9, s0
	v_lshl_add_u64 v[230:231], v[230:231], 0, s[80:81]
	s_mov_b32 m0, s9
	ds_read_b128 v[198:201], v143 offset:49152
	ds_read_b128 v[202:205], v143 offset:50176
	ds_read_b128 v[206:209], v143 offset:51200
	ds_read_b128 v[210:213], v143 offset:52224
	ds_read_b128 v[214:217], v143 offset:53248
	ds_read_b128 v[218:221], v143 offset:54272
	ds_read_b128 v[222:225], v143 offset:55296
	ds_read_b128 v[226:229], v143 offset:56320
	global_load_lds_dwordx4 v[230:231], off
	s_add_i32 m0, s9, 0x2000
	s_add_u32 s58, s58, 0xb0080
	v_lshl_add_u64 v[230:231], v[232:233], 0, s[80:81]
	s_addc_u32 s59, s59, 0
	s_add_i32 s9, s62, s0
	global_load_lds_dwordx4 v[230:231], off
	v_lshl_add_u64 v[230:231], s[58:59], 0, v[146:147]
	s_mov_b32 m0, s9
	s_nop 0
	global_load_lds_dwordx4 v[230:231], off
	v_lshl_add_u64 v[230:231], s[58:59], 0, v[128:129]
	s_add_i32 m0, s9, 0x2000
	s_nop 0
	global_load_lds_dwordx4 v[230:231], off
	v_lshl_add_u64 v[230:231], v[234:235], 0, s[80:81]
	s_mov_b32 m0, s71
	s_nop 0
	global_load_lds_dwordx4 v[230:231], off
	v_lshl_add_u64 v[230:231], v[236:237], 0, s[80:81]
	s_mov_b32 m0, s72
	s_nop 0
	global_load_lds_dwordx4 v[230:231], off
	s_waitcnt vmcnt(8)
	s_waitcnt lgkmcnt(0)
	s_setprio 1
	s_barrier
	v_mfma_f32_16x16x32_bf16 v[48:51], v[160:163], v[198:201], v[48:51]
	v_mfma_f32_16x16x32_bf16 v[44:47], v[174:177], v[198:201], v[44:47]
	v_mfma_f32_16x16x32_bf16 v[24:27], v[160:163], v[206:209], v[24:27]
	v_mfma_f32_16x16x32_bf16 v[16:19], v[174:177], v[206:209], v[16:19]
	v_mfma_f32_16x16x32_bf16 v[64:67], v[160:163], v[214:217], v[64:67]
	v_mfma_f32_16x16x32_bf16 v[56:59], v[174:177], v[214:217], v[56:59]
	v_mfma_f32_16x16x32_bf16 v[40:43], v[160:163], v[222:225], v[40:43]
	v_mfma_f32_16x16x32_bf16 v[32:35], v[174:177], v[222:225], v[32:35]
	v_mfma_f32_16x16x32_bf16 v[48:51], v[170:173], v[202:205], v[48:51]
	v_mfma_f32_16x16x32_bf16 v[44:47], v[178:181], v[202:205], v[44:47]
	v_mfma_f32_16x16x32_bf16 v[24:27], v[170:173], v[210:213], v[24:27]
	v_mfma_f32_16x16x32_bf16 v[16:19], v[178:181], v[210:213], v[16:19]
	v_mfma_f32_16x16x32_bf16 v[64:67], v[170:173], v[218:221], v[64:67]
	v_mfma_f32_16x16x32_bf16 v[56:59], v[178:181], v[218:221], v[56:59]
	v_mfma_f32_16x16x32_bf16 v[40:43], v[170:173], v[226:229], v[40:43]
	v_mfma_f32_16x16x32_bf16 v[32:35], v[178:181], v[226:229], v[32:35]
	s_setprio 0
	s_setprio 1
	v_mfma_f32_16x16x32_bf16 v[20:23], v[182:185], v[198:201], v[20:23]
	v_mfma_f32_16x16x32_bf16 v[12:15], v[190:193], v[198:201], v[12:15]
	v_mfma_f32_16x16x32_bf16 v[0:3], v[182:185], v[206:209], v[0:3]
	v_mfma_f32_16x16x32_bf16 v[52:55], v[190:193], v[206:209], v[52:55]
	v_mfma_f32_16x16x32_bf16 v[36:39], v[182:185], v[214:217], v[36:39]
	v_mfma_f32_16x16x32_bf16 v[28:31], v[190:193], v[214:217], v[28:31]
	v_mfma_f32_16x16x32_bf16 v[8:11], v[182:185], v[222:225], v[8:11]
	v_mfma_f32_16x16x32_bf16 v[4:7], v[190:193], v[222:225], v[4:7]
	v_mfma_f32_16x16x32_bf16 v[20:23], v[186:189], v[202:205], v[20:23]
	v_mfma_f32_16x16x32_bf16 v[12:15], v[194:197], v[202:205], v[12:15]
	v_mfma_f32_16x16x32_bf16 v[0:3], v[186:189], v[210:213], v[0:3]
	v_mfma_f32_16x16x32_bf16 v[52:55], v[194:197], v[210:213], v[52:55]
	v_mfma_f32_16x16x32_bf16 v[36:39], v[186:189], v[218:221], v[36:39]
	v_mfma_f32_16x16x32_bf16 v[28:31], v[194:197], v[218:221], v[28:31]
	v_mfma_f32_16x16x32_bf16 v[8:11], v[186:189], v[226:229], v[8:11]
	v_mfma_f32_16x16x32_bf16 v[4:7], v[194:197], v[226:229], v[4:7]
	s_barrier
	s_setprio 0
	s_add_u32 s82, s82, 0x100
	s_addc_u32 s83, s83, 0
	s_cmp_ge_i32 vcc_lo, s5
	s_mov_b64 s[62:63], s[56:57]
	s_mov_b32 s58, vcc_lo
	s_cbranch_scc0 .LBB0_630
	s_mov_b32 s63, 0xe000
	s_mov_b32 s82, 0x24000
	s_mov_b32 s83, 0x26000
	s_mov_b32 s59, 0x28000
	s_mov_b32 s58, 0x2a000
	s_mov_b32 s61, 0x2c000
	s_mov_b32 s60, 0x32000
	s_mov_b32 s56, 0x34000
	s_mov_b32 s57, 0x36000
	s_and_b64 vcc, exec, s[44:45]
	s_cbranch_vccnz .LBB0_616

; __device__ __forceinline__ int fresh_lane() { int l; asm volatile("v_mbcnt_lo_u32_b32 %0, -1, 0\n\tv_mbcnt_hi_u32_b32 %0, -1, %0" : "=v"(l)); return l; }
; #define PG8_STAGE(bufoff, gbase, voff) do { _Pragma("unroll") for (int _i = 0; _i < 2; ++_i) \
;         __builtin_amdgcn_global_load_lds((const unsigned*)((const char*)(gbase) + (voff)[_i]), (PG8_LAS unsigned*)(lds + (bufoff) + ldsw + _i * 8192), 16, 0, 0); } while (0)
; #define PG8_WAIT_V(n) asm volatile("s_waitcnt vmcnt(" #n ")" ::: "memory")
; #define PG8_BAR __builtin_amdgcn_s_barrier()
; template <class Epi, class Sched, bool ALIGN_EPI = false, bool SP2 = false>
; __device__ __forceinline__ void gemm_phase(PG8_LAS unsigned char* lds, const Gemm g, const Sched& S, const Epi& E, const int wid) {
;     const int lane = fresh_lane(), tid = wid * 64 + lane, wr = wid >> 2, wc = wid & 3, fr = lane & 15, fq = lane >> 4;
;     int nt = g.K / BK; asm volatile("" : "+s"(nt));
;     unsigned voffA[2], voffB[2];
; #pragma unroll
;     for (int i = 0; i < 2; ++i) { int R, C; stage_rc(tid * 16 + i * 8192, R, C); const int Rb = Epi::PERM ? ((R & ~31) + perm32(R & 31)) : R;
;         voffA[i] = (unsigned)(R * g.lda + C) * 2u; voffB[i] = (unsigned)(Rb * g.ldb + C) * 2u; }
;     const size_t kstep = (size_t)(BK * 2);
;     const size_t hstepA = (size_t)HALF * g.lda * 2, hstepB = (size_t)HALF * g.ldb * 2;
;     const size_t tstepA = 2 * hstepA, tstepB = 2 * hstepB;
;     const unsigned ldsw = (unsigned)wid * 1024u;
;     const int aoff = lds_byte(wr * 64 + fr, fq * 8), boff = lds_byte(wc * 32 + fr, fq * 8);
;     ...
;     if constexpr (SP2) {
;         PG8_STAGE(PG8_SB(0, 0), cB, voffB); PG8_STAGE(PG8_SB(0, 1), cB + hstepB, voffB); PG8_STAGE(PG8_SA(0, 0), cA, voffA); PG8_STAGE(PG8_SA(0, 1), cA + hstepA, voffA);
;         if (wr == 1) PG8_BAR;
;         PG8_WAIT_V(2); PG8_BAR;
;         PG8_STAGE(PG8_SB(1, 0), cB + kstep, voffB); PG8_STAGE(PG8_SA(1, 0), cA + kstep, voffA); PG8_STAGE(PG8_SB(1, 1), cB + hstepB + kstep, voffB);
;         PG8_WAIT_V(6); PG8_BAR;
.LBB0_698:
	v_and_b32_e32 v160, 15, v6
	v_or_b32_e32 v7, s72, v160
	v_lshlrev_b32_e32 v18, 6, v7
	v_and_b32_e32 v19, 48, v6
	s_movk_i32 s4, 0x3c0
	v_readlane_b32 s54, v249, 59
	v_ashrrev_i32_e32 v17, 6, v6
	v_and_or_b32 v18, v18, s4, v19
	v_readlane_b32 s4, v250, 27
	v_lshlrev_b32_e32 v7, 2, v7
	v_mov_b32_e32 v137, v147
	v_readlane_b32 s55, v249, 60
	v_ashrrev_i32_e32 v16, 4, v6
	v_lshl_add_u32 v20, v17, 10, s4
	v_and_b32_e32 v7, 32, v7
	v_readlane_b32 s4, v250, 28
	v_lshlrev_b32_e32 v6, 2, v6
	v_lshl_add_u64 v[8:9], s[54:55], 0, v[136:137]
	v_mov_b32_e32 v133, v147
	v_readlane_b32 s52, v249, 55
	v_bitop3_b32 v18, v18, v20, v7 bitop3:0xde
	v_lshl_or_b32 v7, v160, 6, v19
	v_add_lshl_u32 v17, v17, s4, 10
	v_and_b32_e32 v6, 32, v6
	v_lshl_add_u64 v[10:11], s[54:55], 0, v[132:133]
	v_mov_b32_e32 v139, v147
	v_readlane_b32 s53, v249, 56
	v_bitop3_b32 v162, v7, v17, v6 bitop3:0xde
	v_lshl_add_u64 v[6:7], v[8:9], 0, s[80:81]
	s_add_i32 m0, s59, 0x18000
	v_lshl_add_u64 v[12:13], s[52:53], 0, v[138:139]
	v_mov_b32_e32 v135, v147
	global_load_lds_dwordx4 v[6:7], off
	v_lshl_add_u64 v[6:7], v[10:11], 0, s[80:81]
	s_add_i32 m0, s59, 0x1a000
	s_add_i32 s63, s59, 0x8000
	v_lshl_add_u64 v[14:15], s[52:53], 0, v[134:135]
	global_load_lds_dwordx4 v[6:7], off
	v_lshl_add_u64 v[6:7], v[12:13], 0, s[80:81]
	s_mov_b32 m0, s63
	s_add_i32 s64, s59, 0xa000
	v_readlane_b32 s4, v249, 61
	global_load_lds_dwordx4 v[6:7], off
	v_lshl_add_u64 v[6:7], v[14:15], 0, s[80:81]
	s_mov_b32 m0, s64
	v_readlane_b32 s5, v249, 62
	global_load_lds_dwordx4 v[6:7], off
	s_nop 0
	v_lshl_add_u64 v[6:7], s[4:5], 0, v[136:137]
	s_add_i32 m0, s59, 0x1c000
	v_lshlrev_b32_e32 v161, 3, v16
	global_load_lds_dwordx4 v[6:7], off
	v_lshl_add_u64 v[6:7], s[4:5], 0, v[132:133]
	s_add_i32 m0, s59, 0x1e000
	s_cmp_gt_i32 s58, 0
	global_load_lds_dwordx4 v[6:7], off
	s_waitcnt vmcnt(8)
	s_barrier
	v_lshlrev_b32_e32 v6, 5, v16
	v_and_or_b32 v163, v6, 32, v160
	v_lshlrev_b32_e32 v6, 2, v16
	v_lshlrev_b32_e32 v7, 3, v160
	v_and_or_b32 v172, v6, 4, v7
	v_lshlrev_b32_e32 v6, 8, v16
	v_and_b32_e32 v173, 0x200, v6
	v_lshlrev_b32_e32 v6, 14, v3
	v_and_b32_e32 v6, 0xffff8000, v6
	v_lshl_add_u32 v4, v4, 11, v6
	v_and_b32_e32 v3, 1, v3
	v_lshl_or_b32 v3, v3, 6, v4
	v_lshl_add_u32 v140, v5, 1, v3
	v_lshlrev_b32_e32 v3, 14, v0
	v_and_b32_e32 v3, 0xffff8000, v3
	s_waitcnt vmcnt(6)
	v_lshl_add_u32 v1, v1, 11, v3
	v_and_b32_e32 v0, 1, v0
	v_readlane_b32 s8, v250, 21
	v_lshl_or_b32 v0, v0, 6, v1
	s_mov_b32 s65, 0
	s_cselect_b64 s[4:5], -1, 0
	s_add_i32 s66, s58, -2
	v_or_b32_e32 v170, 16, v163
	v_add_u32_e32 v171, s8, v161
	v_or_b32_e32 v174, 0x80, v172
	v_or_b32_e32 v175, 0x400, v173
	v_mov_b32_e32 v141, v147
	v_lshl_add_u32 v142, v2, 1, v0
	v_mov_b32_e32 v143, v147
	v_add_u32_e32 v176, 0, v18
	v_readlane_b32 s67, v249, 52
	v_readlane_b32 s68, v249, 51
	s_barrier
	s_branch .LBB0_701

; #define PG8_STAGE(bufoff, gbase, voff) do { _Pragma("unroll") for (int _i = 0; _i < 2; ++_i) \
;         __builtin_amdgcn_global_load_lds((const unsigned*)((const char*)(gbase) + (voff)[_i]), (PG8_LAS unsigned*)(lds + (bufoff) + ldsw + _i * 8192), 16, 0, 0); } while (0)
; #define PG8_LDA(dst, b, h) do { _Pragma("unroll") for (int m = 0; m < 4; ++m) _Pragma("unroll") for (int k = 0; k < 2; ++k) dst[m][k] = *(const PG8_LAS bf16x8*)(lds + PG8_SA(b, h) + aoff + m * 2048 + k * 1024); } while (0)
; #define PG8_LDB(dst, b, h) do { _Pragma("unroll") for (int n = 0; n < 2; ++n) _Pragma("unroll") for (int k = 0; k < 2; ++k) dst[n][k] = *(const PG8_LAS bf16x8*)(lds + PG8_SB(b, h) + boff + n * 2048 + k * 1024); } while (0)
; #define PG8_MMA(ai, bj, At, Bt) do { __builtin_amdgcn_s_setprio(1); _Pragma("unroll") for (int m = 0; m < 4; ++m) _Pragma("unroll") for (int n = 0; n < 2; ++n) _Pragma("unroll") for (int k = 0; k < 2; ++k) \
;         acc[ai][bj][m][n] = __builtin_amdgcn_mfma_f32_16x16x32_bf16(Bt[n][k], At[m][k], acc[ai][bj][m][n], 0, 0, 0); __builtin_amdgcn_s_setprio(0); } while (0)
; #define PG8_WAIT_V(n) asm volatile("s_waitcnt vmcnt(" #n ")" ::: "memory")
; #define PG8_BAR __builtin_amdgcn_s_barrier()
; template <class Epi, class Sched, bool ALIGN_EPI = false, bool SP2 = false>
; __device__ __forceinline__ void gemm_phase(PG8_LAS unsigned char* lds, const Gemm g, const Sched& S, const Epi& E, const int wid) {
;     ...
;         for (int t = 0; t < nt; t += 2) {
;             const bool last = (t == nt - 2);
;             const char* a1 = cA + (size_t)(t + 1) * kstep;
;             const char* a2 = last ? nA : cA + (size_t)(t + 2) * kstep; const char* b2 = last ? nB : cB + (size_t)(t + 2) * kstep;
;             const char* a3 = a2 + kstep; const char* b3 = b2 + kstep;
;             if (last && has_next) S.a_ready(nxt);
;             if constexpr (SP2) {
;             PG8_LDB(B0, 0, 0); PG8_LDB(B1, 0, 1); PG8_SCHED; PG8_LDA(At, 0, 0); PG8_STAGE(PG8_SA(1, 1), a1 + hstepA, voffA);
;             PG8_WAIT_V(8); PG8_WAIT_L(0); PG8_BAR; PG8_MMA(0, 0, At, B0); PG8_MMA(0, 1, At, B1); PG8_BAR; PG8_SCHED;
;             PG8_LDA(At, 0, 1); PG8_STAGE(PG8_SB(0, 0), b2, voffB); PG8_STAGE(PG8_SB(0, 1), b2 + hstepB, voffB); PG8_STAGE(PG8_SA(0, 0), a2, voffA);
;             PG8_WAIT_V(8); PG8_WAIT_L(0); PG8_BAR; PG8_MMA(1, 0, At, B0); PG8_MMA(1, 1, At, B1); PG8_BAR; PG8_SCHED;
.LBB0_716:
	s_add_i32 s69, s49, 2
	s_add_u32 s9, s52, 0xfffc0080
	s_addc_u32 s54, s53, -1
	s_add_i32 s70, 0, 0x10000
	s_cmp_eq_u32 s66, s49
	s_cselect_b32 s57, s47, s54
	s_cselect_b32 s56, s46, s9
	v_add_u32_e32 v146, s70, v162
	s_cselect_b32 s55, s51, s11
	s_cselect_b32 s54, s50, s8
	s_add_i32 s9, 0, 0x14000
	ds_read_b128 v[128:131], v146
	ds_read_b128 v[178:181], v146 offset:1024
	ds_read_b128 v[182:185], v146 offset:2048
	ds_read_b128 v[186:189], v146 offset:3072
	v_add_u32_e32 v146, s9, v162
	ds_read_b128 v[190:193], v146
	ds_read_b128 v[194:197], v146 offset:1024
	ds_read_b128 v[198:201], v146 offset:2048
	ds_read_b128 v[202:205], v146 offset:3072
	v_lshl_add_u64 v[238:239], s[52:53], 0, v[140:141]
	s_add_i32 m0, s59, 0xc000
	ds_read_b128 v[206:209], v176
	ds_read_b128 v[210:213], v176 offset:1024
	ds_read_b128 v[214:217], v176 offset:2048
	ds_read_b128 v[218:221], v176 offset:3072
	ds_read_b128 v[222:225], v176 offset:4096
	ds_read_b128 v[226:229], v176 offset:5120
	ds_read_b128 v[230:233], v176 offset:6144
	ds_read_b128 v[234:237], v176 offset:7168
	global_load_lds_dwordx4 v[238:239], off
	v_lshl_add_u64 v[238:239], s[52:53], 0, v[142:143]
	s_add_i32 m0, s59, 0xe000
	s_nop 0
	global_load_lds_dwordx4 v[238:239], off
	s_waitcnt vmcnt(8)
	s_waitcnt lgkmcnt(0)
	s_setprio 1
	s_barrier
	v_mfma_f32_16x16x32_bf16 v[124:127], v[128:131], v[206:209], v[124:127]
	v_mfma_f32_16x16x32_bf16 v[120:123], v[182:185], v[206:209], v[120:123]
	v_mfma_f32_16x16x32_bf16 v[108:111], v[128:131], v[214:217], v[108:111]
	v_mfma_f32_16x16x32_bf16 v[104:107], v[182:185], v[214:217], v[104:107]
	v_mfma_f32_16x16x32_bf16 v[92:95], v[128:131], v[222:225], v[92:95]
	v_mfma_f32_16x16x32_bf16 v[88:91], v[182:185], v[222:225], v[88:91]
	v_mfma_f32_16x16x32_bf16 v[76:79], v[128:131], v[230:233], v[76:79]
	v_mfma_f32_16x16x32_bf16 v[72:75], v[182:185], v[230:233], v[72:75]
	v_mfma_f32_16x16x32_bf16 v[124:127], v[178:181], v[210:213], v[124:127]
	v_mfma_f32_16x16x32_bf16 v[120:123], v[186:189], v[210:213], v[120:123]
	v_mfma_f32_16x16x32_bf16 v[108:111], v[178:181], v[218:221], v[108:111]
	v_mfma_f32_16x16x32_bf16 v[104:107], v[186:189], v[218:221], v[104:107]
	v_mfma_f32_16x16x32_bf16 v[92:95], v[178:181], v[226:229], v[92:95]
	v_mfma_f32_16x16x32_bf16 v[88:91], v[186:189], v[226:229], v[88:91]
	v_mfma_f32_16x16x32_bf16 v[76:79], v[178:181], v[234:237], v[76:79]
	v_mfma_f32_16x16x32_bf16 v[72:75], v[186:189], v[234:237], v[72:75]
	s_setprio 0
	s_setprio 1
	v_mfma_f32_16x16x32_bf16 v[116:119], v[190:193], v[206:209], v[116:119]
	v_mfma_f32_16x16x32_bf16 v[112:115], v[198:201], v[206:209], v[112:115]
	v_mfma_f32_16x16x32_bf16 v[100:103], v[190:193], v[214:217], v[100:103]
	v_mfma_f32_16x16x32_bf16 v[96:99], v[198:201], v[214:217], v[96:99]
	v_mfma_f32_16x16x32_bf16 v[84:87], v[190:193], v[222:225], v[84:87]
	v_mfma_f32_16x16x32_bf16 v[80:83], v[198:201], v[222:225], v[80:83]
	v_mfma_f32_16x16x32_bf16 v[68:71], v[190:193], v[230:233], v[68:71]
	v_mfma_f32_16x16x32_bf16 v[64:67], v[198:201], v[230:233], v[64:67]
	v_mfma_f32_16x16x32_bf16 v[116:119], v[194:197], v[210:213], v[116:119]
	v_mfma_f32_16x16x32_bf16 v[112:115], v[202:205], v[210:213], v[112:115]
	v_mfma_f32_16x16x32_bf16 v[100:103], v[194:197], v[218:221], v[100:103]
	v_mfma_f32_16x16x32_bf16 v[96:99], v[202:205], v[218:221], v[96:99]
	v_mfma_f32_16x16x32_bf16 v[84:87], v[194:197], v[226:229], v[84:87]
	v_mfma_f32_16x16x32_bf16 v[80:83], v[202:205], v[226:229], v[80:83]
	v_mfma_f32_16x16x32_bf16 v[68:71], v[194:197], v[234:237], v[68:71]
	v_mfma_f32_16x16x32_bf16 v[64:67], v[202:205], v[234:237], v[64:67]
	s_barrier
	s_setprio 0
	s_add_i32 s49, s70, s0
	v_lshl_add_u64 v[238:239], s[54:55], 0, v[136:137]
	s_mov_b32 m0, s49
	ds_read_b128 v[206:209], v176 offset:16384
	ds_read_b128 v[210:213], v176 offset:17408
	ds_read_b128 v[214:217], v176 offset:18432
	ds_read_b128 v[218:221], v176 offset:19456
	ds_read_b128 v[222:225], v176 offset:20480
	ds_read_b128 v[226:229], v176 offset:21504
	ds_read_b128 v[230:233], v176 offset:22528
	ds_read_b128 v[234:237], v176 offset:23552
	global_load_lds_dwordx4 v[238:239], off
	s_add_i32 m0, s49, 0x2000
	s_add_u32 s70, s54, 0x40000
	v_lshl_add_u64 v[240:241], s[54:55], 0, v[132:133]
	s_addc_u32 s71, s55, 0
	s_add_i32 s9, s9, s0
	global_load_lds_dwordx4 v[240:241], off
	v_lshl_add_u64 v[242:243], s[70:71], 0, v[136:137]
	s_mov_b32 m0, s9
	v_lshl_add_u64 v[244:245], s[56:57], 0, v[134:135]
	global_load_lds_dwordx4 v[242:243], off
	v_lshl_add_u64 v[242:243], s[70:71], 0, v[132:133]
	s_add_i32 m0, s9, 0x2000
	s_nop 0
	global_load_lds_dwordx4 v[242:243], off
	v_lshl_add_u64 v[242:243], s[56:57], 0, v[138:139]
	s_mov_b32 m0, s59
	s_nop 0
	global_load_lds_dwordx4 v[242:243], off
	s_mov_b32 m0, s60
	s_nop 0
	global_load_lds_dwordx4 v[244:245], off
	s_waitcnt vmcnt(8)
	s_waitcnt lgkmcnt(0)
	s_setprio 1
	s_barrier
; #define PG8_STAGE(bufoff, gbase, voff) do { _Pragma("unroll") for (int _i = 0; _i < 2; ++_i) \
;         __builtin_amdgcn_global_load_lds((const unsigned*)((const char*)(gbase) + (voff)[_i]), (PG8_LAS unsigned*)(lds + (bufoff) + ldsw + _i * 8192), 16, 0, 0); } while (0)
; #define PG8_LDA(dst, b, h) do { _Pragma("unroll") for (int m = 0; m < 4; ++m) _Pragma("unroll") for (int k = 0; k < 2; ++k) dst[m][k] = *(const PG8_LAS bf16x8*)(lds + PG8_SA(b, h) + aoff + m * 2048 + k * 1024); } while (0)
; #define PG8_LDB(dst, b, h) do { _Pragma("unroll") for (int n = 0; n < 2; ++n) _Pragma("unroll") for (int k = 0; k < 2; ++k) dst[n][k] = *(const PG8_LAS bf16x8*)(lds + PG8_SB(b, h) + boff + n * 2048 + k * 1024); } while (0)
; #define PG8_MMA(ai, bj, At, Bt) do { __builtin_amdgcn_s_setprio(1); _Pragma("unroll") for (int m = 0; m < 4; ++m) _Pragma("unroll") for (int n = 0; n < 2; ++n) _Pragma("unroll") for (int k = 0; k < 2; ++k) \
;         acc[ai][bj][m][n] = __builtin_amdgcn_mfma_f32_16x16x32_bf16(Bt[n][k], At[m][k], acc[ai][bj][m][n], 0, 0, 0); __builtin_amdgcn_s_setprio(0); } while (0)
; #define PG8_WAIT_V(n) asm volatile("s_waitcnt vmcnt(" #n ")" ::: "memory")
; #define PG8_WAIT_L(n) asm volatile("s_waitcnt lgkmcnt(" #n ")" ::: "memory")
; #define PG8_BAR __builtin_amdgcn_s_barrier()
; #define PG8_SCHED __builtin_amdgcn_sched_barrier(0)
; template <class Epi, class Sched, bool ALIGN_EPI = false, bool SP2 = false>
; __device__ __forceinline__ void gemm_phase(PG8_LAS unsigned char* lds, const Gemm g, const Sched& S, const Epi& E, const int wid) {
;     ...
;             PG8_WAIT_V(8); PG8_WAIT_L(0); PG8_BAR; PG8_MMA(1, 0, At, B0); PG8_MMA(1, 1, At, B1); PG8_BAR; PG8_SCHED;
;             PG8_LDB(B0, 1, 0); PG8_LDB(B1, 1, 1); PG8_SCHED; PG8_LDA(At, 1, 0); PG8_STAGE(PG8_SA(0, 1), a2 + hstepA, voffA);
;             PG8_WAIT_V(8); PG8_WAIT_L(0); PG8_BAR; PG8_MMA(0, 0, At, B0); PG8_MMA(0, 1, At, B1); PG8_BAR; PG8_SCHED;
	v_mfma_f32_16x16x32_bf16 v[60:63], v[128:131], v[206:209], v[60:63]
	v_mfma_f32_16x16x32_bf16 v[56:59], v[182:185], v[206:209], v[56:59]
	v_mfma_f32_16x16x32_bf16 v[44:47], v[128:131], v[214:217], v[44:47]
	v_mfma_f32_16x16x32_bf16 v[40:43], v[182:185], v[214:217], v[40:43]
	v_mfma_f32_16x16x32_bf16 v[28:31], v[128:131], v[222:225], v[28:31]
	v_mfma_f32_16x16x32_bf16 v[24:27], v[182:185], v[222:225], v[24:27]
	v_mfma_f32_16x16x32_bf16 v[12:15], v[128:131], v[230:233], v[12:15]
	v_mfma_f32_16x16x32_bf16 v[8:11], v[182:185], v[230:233], v[8:11]
	v_mfma_f32_16x16x32_bf16 v[60:63], v[178:181], v[210:213], v[60:63]
	v_mfma_f32_16x16x32_bf16 v[56:59], v[186:189], v[210:213], v[56:59]
	v_mfma_f32_16x16x32_bf16 v[44:47], v[178:181], v[218:221], v[44:47]
	v_mfma_f32_16x16x32_bf16 v[40:43], v[186:189], v[218:221], v[40:43]
	v_mfma_f32_16x16x32_bf16 v[28:31], v[178:181], v[226:229], v[28:31]
	v_mfma_f32_16x16x32_bf16 v[24:27], v[186:189], v[226:229], v[24:27]
	v_mfma_f32_16x16x32_bf16 v[12:15], v[178:181], v[234:237], v[12:15]
	v_mfma_f32_16x16x32_bf16 v[8:11], v[186:189], v[234:237], v[8:11]
	s_setprio 0
	s_setprio 1
	v_mfma_f32_16x16x32_bf16 v[52:55], v[190:193], v[206:209], v[52:55]
	v_mfma_f32_16x16x32_bf16 v[48:51], v[198:201], v[206:209], v[48:51]
	v_mfma_f32_16x16x32_bf16 v[36:39], v[190:193], v[214:217], v[36:39]
	v_mfma_f32_16x16x32_bf16 v[32:35], v[198:201], v[214:217], v[32:35]
	v_mfma_f32_16x16x32_bf16 v[20:23], v[190:193], v[222:225], v[20:23]
	v_mfma_f32_16x16x32_bf16 v[16:19], v[198:201], v[222:225], v[16:19]
	v_mfma_f32_16x16x32_bf16 v[4:7], v[190:193], v[230:233], v[4:7]
	v_mfma_f32_16x16x32_bf16 v[0:3], v[198:201], v[230:233], v[0:3]
	v_mfma_f32_16x16x32_bf16 v[52:55], v[194:197], v[210:213], v[52:55]
	v_mfma_f32_16x16x32_bf16 v[48:51], v[202:205], v[210:213], v[48:51]
	v_mfma_f32_16x16x32_bf16 v[36:39], v[194:197], v[218:221], v[36:39]
	v_mfma_f32_16x16x32_bf16 v[32:35], v[202:205], v[218:221], v[32:35]
	v_mfma_f32_16x16x32_bf16 v[20:23], v[194:197], v[226:229], v[20:23]
	v_mfma_f32_16x16x32_bf16 v[16:19], v[202:205], v[226:229], v[16:19]
	v_mfma_f32_16x16x32_bf16 v[4:7], v[194:197], v[234:237], v[4:7]
	v_mfma_f32_16x16x32_bf16 v[0:3], v[202:205], v[234:237], v[0:3]
	s_barrier
	s_setprio 0
	s_add_i32 s9, 0, 0x18000
	v_add_u32_e32 v146, s9, v162
	s_add_i32 s49, 0, 0x1c000
	ds_read_b128 v[128:131], v146
	ds_read_b128 v[178:181], v146 offset:1024
	ds_read_b128 v[182:185], v146 offset:2048
	ds_read_b128 v[186:189], v146 offset:3072
	v_add_u32_e32 v146, s49, v162
	ds_read_b128 v[190:193], v146
	ds_read_b128 v[194:197], v146 offset:1024
	ds_read_b128 v[198:201], v146 offset:2048
	ds_read_b128 v[202:205], v146 offset:3072
	s_add_u32 s56, s56, 0x40000
	s_addc_u32 s57, s57, 0
	s_mov_b32 m0, s61
	v_lshl_add_u64 v[246:247], s[56:57], 0, v[138:139]
	ds_read_b128 v[206:209], v176 offset:32768
	ds_read_b128 v[210:213], v176 offset:33792
	ds_read_b128 v[214:217], v176 offset:34816
	ds_read_b128 v[218:221], v176 offset:35840
	ds_read_b128 v[222:225], v176 offset:36864
	ds_read_b128 v[226:229], v176 offset:37888
	ds_read_b128 v[230:233], v176 offset:38912
	ds_read_b128 v[234:237], v176 offset:39936
	global_load_lds_dwordx4 v[246:247], off
	v_lshl_add_u64 v[246:247], s[56:57], 0, v[134:135]
	s_mov_b32 m0, s62
	s_nop 0
	global_load_lds_dwordx4 v[246:247], off
	s_waitcnt vmcnt(8)
	s_waitcnt lgkmcnt(0)
	s_setprio 1
	s_barrier
	v_mfma_f32_16x16x32_bf16 v[124:127], v[128:131], v[206:209], v[124:127]
	v_mfma_f32_16x16x32_bf16 v[120:123], v[182:185], v[206:209], v[120:123]
	v_mfma_f32_16x16x32_bf16 v[108:111], v[128:131], v[214:217], v[108:111]
	v_mfma_f32_16x16x32_bf16 v[104:107], v[182:185], v[214:217], v[104:107]
	v_mfma_f32_16x16x32_bf16 v[92:95], v[128:131], v[222:225], v[92:95]
	v_mfma_f32_16x16x32_bf16 v[88:91], v[182:185], v[222:225], v[88:91]
	v_mfma_f32_16x16x32_bf16 v[76:79], v[128:131], v[230:233], v[76:79]
	v_mfma_f32_16x16x32_bf16 v[72:75], v[182:185], v[230:233], v[72:75]
	v_mfma_f32_16x16x32_bf16 v[124:127], v[178:181], v[210:213], v[124:127]
	v_mfma_f32_16x16x32_bf16 v[120:123], v[186:189], v[210:213], v[120:123]
	v_mfma_f32_16x16x32_bf16 v[108:111], v[178:181], v[218:221], v[108:111]
	v_mfma_f32_16x16x32_bf16 v[104:107], v[186:189], v[218:221], v[104:107]
	v_mfma_f32_16x16x32_bf16 v[92:95], v[178:181], v[226:229], v[92:95]
	v_mfma_f32_16x16x32_bf16 v[88:91], v[186:189], v[226:229], v[88:91]
	v_mfma_f32_16x16x32_bf16 v[76:79], v[178:181], v[234:237], v[76:79]
	v_mfma_f32_16x16x32_bf16 v[72:75], v[186:189], v[234:237], v[72:75]
	s_setprio 0
	s_setprio 1
	v_mfma_f32_16x16x32_bf16 v[116:119], v[190:193], v[206:209], v[116:119]
	v_mfma_f32_16x16x32_bf16 v[112:115], v[198:201], v[206:209], v[112:115]
	v_mfma_f32_16x16x32_bf16 v[100:103], v[190:193], v[214:217], v[100:103]
	v_mfma_f32_16x16x32_bf16 v[96:99], v[198:201], v[214:217], v[96:99]
	v_mfma_f32_16x16x32_bf16 v[84:87], v[190:193], v[222:225], v[84:87]
	v_mfma_f32_16x16x32_bf16 v[80:83], v[198:201], v[222:225], v[80:83]
	v_mfma_f32_16x16x32_bf16 v[68:71], v[190:193], v[230:233], v[68:71]
	v_mfma_f32_16x16x32_bf16 v[64:67], v[198:201], v[230:233], v[64:67]
	v_mfma_f32_16x16x32_bf16 v[116:119], v[194:197], v[210:213], v[116:119]
	v_mfma_f32_16x16x32_bf16 v[112:115], v[202:205], v[210:213], v[112:115]
	v_mfma_f32_16x16x32_bf16 v[100:103], v[194:197], v[218:221], v[100:103]
	v_mfma_f32_16x16x32_bf16 v[96:99], v[202:205], v[218:221], v[96:99]
	v_mfma_f32_16x16x32_bf16 v[84:87], v[194:197], v[226:229], v[84:87]
	v_mfma_f32_16x16x32_bf16 v[80:83], v[202:205], v[226:229], v[80:83]
	v_mfma_f32_16x16x32_bf16 v[68:71], v[194:197], v[234:237], v[68:71]
	v_mfma_f32_16x16x32_bf16 v[64:67], v[202:205], v[234:237], v[64:67]
	s_barrier
; #define PG8_STAGE(bufoff, gbase, voff) do { _Pragma("unroll") for (int _i = 0; _i < 2; ++_i) \
;         __builtin_amdgcn_global_load_lds((const unsigned*)((const char*)(gbase) + (voff)[_i]), (PG8_LAS unsigned*)(lds + (bufoff) + ldsw + _i * 8192), 16, 0, 0); } while (0)
; #define PG8_LDA(dst, b, h) do { _Pragma("unroll") for (int m = 0; m < 4; ++m) _Pragma("unroll") for (int k = 0; k < 2; ++k) dst[m][k] = *(const PG8_LAS bf16x8*)(lds + PG8_SA(b, h) + aoff + m * 2048 + k * 1024); } while (0)
; #define PG8_MMA(ai, bj, At, Bt) do { __builtin_amdgcn_s_setprio(1); _Pragma("unroll") for (int m = 0; m < 4; ++m) _Pragma("unroll") for (int n = 0; n < 2; ++n) _Pragma("unroll") for (int k = 0; k < 2; ++k) \
;         acc[ai][bj][m][n] = __builtin_amdgcn_mfma_f32_16x16x32_bf16(Bt[n][k], At[m][k], acc[ai][bj][m][n], 0, 0, 0); __builtin_amdgcn_s_setprio(0); } while (0)
; #define PG8_WAIT_V(n) asm volatile("s_waitcnt vmcnt(" #n ")" ::: "memory")
; #define PG8_WAIT_L(n) asm volatile("s_waitcnt lgkmcnt(" #n ")" ::: "memory")
; #define PG8_BAR __builtin_amdgcn_s_barrier()
; #define PG8_SCHED __builtin_amdgcn_sched_barrier(0)
; template <class Epi, class Sched, bool ALIGN_EPI = false, bool SP2 = false>
; __device__ __forceinline__ void gemm_phase(PG8_LAS unsigned char* lds, const Gemm g, const Sched& S, const Epi& E, const int wid) {
;     ...
;         for (int t = 0; t < nt; t += 2) {
;             const bool last = (t == nt - 2);
;             const char* a1 = cA + (size_t)(t + 1) * kstep;
;             const char* a2 = last ? nA : cA + (size_t)(t + 2) * kstep; const char* b2 = last ? nB : cB + (size_t)(t + 2) * kstep;
;     ...
;             PG8_LDA(At, 1, 1); PG8_STAGE(PG8_SB(1, 0), b3, voffB); PG8_STAGE(PG8_SB(1, 1), b3 + hstepB, voffB); PG8_STAGE(PG8_SA(1, 0), a3, voffA);
;             PG8_WAIT_V(8); PG8_WAIT_L(0); PG8_BAR; PG8_MMA(1, 0, At, B0); PG8_MMA(1, 1, At, B1); PG8_BAR; PG8_SCHED;
	s_setprio 0
	s_add_i32 s9, s9, s0
	v_lshl_add_u64 v[238:239], v[238:239], 0, s[80:81]
	s_mov_b32 m0, s9
	ds_read_b128 v[206:209], v176 offset:49152
	ds_read_b128 v[210:213], v176 offset:50176
	ds_read_b128 v[214:217], v176 offset:51200
	ds_read_b128 v[218:221], v176 offset:52224
	ds_read_b128 v[222:225], v176 offset:53248
	ds_read_b128 v[226:229], v176 offset:54272
	ds_read_b128 v[230:233], v176 offset:55296
	ds_read_b128 v[234:237], v176 offset:56320
	global_load_lds_dwordx4 v[238:239], off
	s_add_i32 m0, s9, 0x2000
	s_add_u32 s54, s54, 0x40080
	v_lshl_add_u64 v[238:239], v[240:241], 0, s[80:81]
	s_addc_u32 s55, s55, 0
	s_add_i32 s9, s49, s0
	global_load_lds_dwordx4 v[238:239], off
	v_lshl_add_u64 v[238:239], s[54:55], 0, v[136:137]
	s_mov_b32 m0, s9
	s_nop 0
	global_load_lds_dwordx4 v[238:239], off
	v_lshl_add_u64 v[238:239], s[54:55], 0, v[132:133]
	s_add_i32 m0, s9, 0x2000
	s_nop 0
	global_load_lds_dwordx4 v[238:239], off
	v_lshl_add_u64 v[238:239], v[242:243], 0, s[80:81]
	s_mov_b32 m0, s63
	s_nop 0
	global_load_lds_dwordx4 v[238:239], off
	v_lshl_add_u64 v[238:239], v[244:245], 0, s[80:81]
	s_mov_b32 m0, s64
	s_nop 0
	global_load_lds_dwordx4 v[238:239], off
	s_waitcnt vmcnt(8)
	s_waitcnt lgkmcnt(0)
	s_setprio 1
	s_barrier
	v_mfma_f32_16x16x32_bf16 v[60:63], v[128:131], v[206:209], v[60:63]
	v_mfma_f32_16x16x32_bf16 v[56:59], v[182:185], v[206:209], v[56:59]
	v_mfma_f32_16x16x32_bf16 v[44:47], v[128:131], v[214:217], v[44:47]
	v_mfma_f32_16x16x32_bf16 v[40:43], v[182:185], v[214:217], v[40:43]
	v_mfma_f32_16x16x32_bf16 v[28:31], v[128:131], v[222:225], v[28:31]
	v_mfma_f32_16x16x32_bf16 v[24:27], v[182:185], v[222:225], v[24:27]
	v_mfma_f32_16x16x32_bf16 v[12:15], v[128:131], v[230:233], v[12:15]
	v_mfma_f32_16x16x32_bf16 v[8:11], v[182:185], v[230:233], v[8:11]
	v_mfma_f32_16x16x32_bf16 v[60:63], v[178:181], v[210:213], v[60:63]
	v_mfma_f32_16x16x32_bf16 v[56:59], v[186:189], v[210:213], v[56:59]
	v_mfma_f32_16x16x32_bf16 v[44:47], v[178:181], v[218:221], v[44:47]
	v_mfma_f32_16x16x32_bf16 v[40:43], v[186:189], v[218:221], v[40:43]
	v_mfma_f32_16x16x32_bf16 v[28:31], v[178:181], v[226:229], v[28:31]
	v_mfma_f32_16x16x32_bf16 v[24:27], v[186:189], v[226:229], v[24:27]
	v_mfma_f32_16x16x32_bf16 v[12:15], v[178:181], v[234:237], v[12:15]
	v_mfma_f32_16x16x32_bf16 v[8:11], v[186:189], v[234:237], v[8:11]
	s_setprio 0
	s_setprio 1
	v_mfma_f32_16x16x32_bf16 v[52:55], v[190:193], v[206:209], v[52:55]
	v_mfma_f32_16x16x32_bf16 v[48:51], v[198:201], v[206:209], v[48:51]
	v_mfma_f32_16x16x32_bf16 v[36:39], v[190:193], v[214:217], v[36:39]
	v_mfma_f32_16x16x32_bf16 v[32:35], v[198:201], v[214:217], v[32:35]
	v_mfma_f32_16x16x32_bf16 v[20:23], v[190:193], v[222:225], v[20:23]
	v_mfma_f32_16x16x32_bf16 v[16:19], v[198:201], v[222:225], v[16:19]
	v_mfma_f32_16x16x32_bf16 v[4:7], v[190:193], v[230:233], v[4:7]
	v_mfma_f32_16x16x32_bf16 v[0:3], v[198:201], v[230:233], v[0:3]
	v_mfma_f32_16x16x32_bf16 v[52:55], v[194:197], v[210:213], v[52:55]
	v_mfma_f32_16x16x32_bf16 v[48:51], v[202:205], v[210:213], v[48:51]
	v_mfma_f32_16x16x32_bf16 v[36:39], v[194:197], v[218:221], v[36:39]
	v_mfma_f32_16x16x32_bf16 v[32:35], v[202:205], v[218:221], v[32:35]
	v_mfma_f32_16x16x32_bf16 v[20:23], v[194:197], v[226:229], v[20:23]
	v_mfma_f32_16x16x32_bf16 v[16:19], v[202:205], v[226:229], v[16:19]
	v_mfma_f32_16x16x32_bf16 v[4:7], v[194:197], v[234:237], v[4:7]
	v_mfma_f32_16x16x32_bf16 v[0:3], v[202:205], v[234:237], v[0:3]
	s_barrier
	s_setprio 0
	s_add_u32 s52, s52, 0x100
	s_addc_u32 s53, s53, 0
	s_add_u32 s8, s8, 0x100
	s_addc_u32 s11, s11, 0
	s_cmp_ge_i32 s69, s58
	s_mov_b32 s49, s69
	s_cbranch_scc0 .LBB0_716
	s_mov_b32 s70, 0x1a000
	s_mov_b32 s71, 0xa000
	s_mov_b32 s56, 0x34000
	s_mov_b32 s57, 0x36000
	s_and_b64 vcc, exec, s[6:7]
	s_cbranch_vccz .LBB0_719

; #define PG8_STAGE(bufoff, gbase, voff) do { _Pragma("unroll") for (int _i = 0; _i < 2; ++_i) \
;         __builtin_amdgcn_global_load_lds((const unsigned*)((const char*)(gbase) + (voff)[_i]), (PG8_LAS unsigned*)(lds + (bufoff) + ldsw + _i * 8192), 16, 0, 0); } while (0)
; #define PG8_LDA(dst, b, h) do { _Pragma("unroll") for (int m = 0; m < 4; ++m) _Pragma("unroll") for (int k = 0; k < 2; ++k) dst[m][k] = *(const PG8_LAS bf16x8*)(lds + PG8_SA(b, h) + aoff + m * 2048 + k * 1024); } while (0)
; #define PG8_LDB(dst, b, h) do { _Pragma("unroll") for (int n = 0; n < 2; ++n) _Pragma("unroll") for (int k = 0; k < 2; ++k) dst[n][k] = *(const PG8_LAS bf16x8*)(lds + PG8_SB(b, h) + boff + n * 2048 + k * 1024); } while (0)
; #define PG8_MMA(ai, bj, At, Bt) do { __builtin_amdgcn_s_setprio(1); _Pragma("unroll") for (int m = 0; m < 4; ++m) _Pragma("unroll") for (int n = 0; n < 2; ++n) _Pragma("unroll") for (int k = 0; k < 2; ++k) \
;         acc[ai][bj][m][n] = __builtin_amdgcn_mfma_f32_16x16x32_bf16(Bt[n][k], At[m][k], acc[ai][bj][m][n], 0, 0, 0); __builtin_amdgcn_s_setprio(0); } while (0)
; #define PG8_WAIT_V(n) asm volatile("s_waitcnt vmcnt(" #n ")" ::: "memory")
; #define PG8_BAR __builtin_amdgcn_s_barrier()
; template <class Epi, class Sched, bool ALIGN_EPI = false, bool SP2 = false>
; __device__ __forceinline__ void gemm_phase(PG8_LAS unsigned char* lds, const Gemm g, const Sched& S, const Epi& E, const int wid) {
;     ...
;         for (int t = 0; t < nt; t += 2) {
;             const bool last = (t == nt - 2);
;             const char* a1 = cA + (size_t)(t + 1) * kstep;
;             const char* a2 = last ? nA : cA + (size_t)(t + 2) * kstep; const char* b2 = last ? nB : cB + (size_t)(t + 2) * kstep;
;             const char* a3 = a2 + kstep; const char* b3 = b2 + kstep;
;             if (last && has_next) S.a_ready(nxt);
;             if constexpr (SP2) {
;             PG8_LDB(B0, 0, 0); PG8_LDB(B1, 0, 1); PG8_SCHED; PG8_LDA(At, 0, 0); PG8_STAGE(PG8_SA(1, 1), a1 + hstepA, voffA);
;             PG8_WAIT_V(8); PG8_WAIT_L(0); PG8_BAR; PG8_MMA(0, 0, At, B0); PG8_MMA(0, 1, At, B1); PG8_BAR; PG8_SCHED;
;             PG8_LDA(At, 0, 1); PG8_STAGE(PG8_SB(0, 0), b2, voffB); PG8_STAGE(PG8_SB(0, 1), b2 + hstepB, voffB); PG8_STAGE(PG8_SA(0, 0), a2, voffA);
;             PG8_WAIT_V(8); PG8_WAIT_L(0); PG8_BAR; PG8_MMA(1, 0, At, B0); PG8_MMA(1, 1, At, B1); PG8_BAR; PG8_SCHED;
.LBB0_830:
	s_add_i32 s73, s60, 2
	s_add_u32 s9, s58, 0xfffc0080
	s_addc_u32 s61, s59, -1
	s_add_i32 s74, 0, 0x10000
	s_cmp_eq_u32 s71, s60
	s_cselect_b32 s63, s55, s61
	s_cselect_b32 s62, s54, s9
	s_cselect_b32 s61, s57, s53
	s_cselect_b32 s60, s56, s51
	s_add_i32 s9, 0, 0x14000
	v_add_u32_e32 v178, s74, v142
	v_add_u32_e32 v194, s9, v142
	ds_read_b128 v[160:163], v178
	ds_read_b128 v[170:173], v178 offset:1024
	ds_read_b128 v[174:177], v178 offset:2048
	ds_read_b128 v[178:181], v178 offset:3072
	ds_read_b128 v[182:185], v194
	ds_read_b128 v[186:189], v194 offset:1024
	ds_read_b128 v[190:193], v194 offset:2048
	ds_read_b128 v[194:197], v194 offset:3072
	v_lshl_add_u64 v[230:231], s[58:59], 0, v[134:135]
	s_add_i32 m0, s64, 0xc000
	ds_read_b128 v[198:201], v143
	ds_read_b128 v[202:205], v143 offset:1024
	ds_read_b128 v[206:209], v143 offset:2048
	ds_read_b128 v[210:213], v143 offset:3072
	ds_read_b128 v[214:217], v143 offset:4096
	ds_read_b128 v[218:221], v143 offset:5120
	ds_read_b128 v[222:225], v143 offset:6144
	ds_read_b128 v[226:229], v143 offset:7168
	global_load_lds_dwordx4 v[230:231], off
	v_lshl_add_u64 v[230:231], s[58:59], 0, v[136:137]
	s_add_i32 m0, s64, 0xe000
	s_nop 0
	global_load_lds_dwordx4 v[230:231], off
	s_waitcnt vmcnt(8)
	s_waitcnt lgkmcnt(0)
	s_setprio 1
	s_barrier
	v_mfma_f32_16x16x32_bf16 v[124:127], v[160:163], v[198:201], v[124:127]
	v_mfma_f32_16x16x32_bf16 v[120:123], v[174:177], v[198:201], v[120:123]
	v_mfma_f32_16x16x32_bf16 v[108:111], v[160:163], v[206:209], v[108:111]
	v_mfma_f32_16x16x32_bf16 v[104:107], v[174:177], v[206:209], v[104:107]
	v_mfma_f32_16x16x32_bf16 v[100:103], v[160:163], v[214:217], v[100:103]
	v_mfma_f32_16x16x32_bf16 v[92:95], v[174:177], v[214:217], v[92:95]
	v_mfma_f32_16x16x32_bf16 v[84:87], v[160:163], v[222:225], v[84:87]
	v_mfma_f32_16x16x32_bf16 v[76:79], v[174:177], v[222:225], v[76:79]
	v_mfma_f32_16x16x32_bf16 v[124:127], v[170:173], v[202:205], v[124:127]
	v_mfma_f32_16x16x32_bf16 v[120:123], v[178:181], v[202:205], v[120:123]
	v_mfma_f32_16x16x32_bf16 v[108:111], v[170:173], v[210:213], v[108:111]
	v_mfma_f32_16x16x32_bf16 v[104:107], v[178:181], v[210:213], v[104:107]
	v_mfma_f32_16x16x32_bf16 v[100:103], v[170:173], v[218:221], v[100:103]
	v_mfma_f32_16x16x32_bf16 v[92:95], v[178:181], v[218:221], v[92:95]
	v_mfma_f32_16x16x32_bf16 v[84:87], v[170:173], v[226:229], v[84:87]
	v_mfma_f32_16x16x32_bf16 v[76:79], v[178:181], v[226:229], v[76:79]
	s_setprio 0
	s_setprio 1
	v_mfma_f32_16x16x32_bf16 v[116:119], v[182:185], v[198:201], v[116:119]
	v_mfma_f32_16x16x32_bf16 v[112:115], v[190:193], v[198:201], v[112:115]
	v_mfma_f32_16x16x32_bf16 v[96:99], v[182:185], v[206:209], v[96:99]
	v_mfma_f32_16x16x32_bf16 v[88:91], v[190:193], v[206:209], v[88:91]
	v_mfma_f32_16x16x32_bf16 v[80:83], v[182:185], v[214:217], v[80:83]
	v_mfma_f32_16x16x32_bf16 v[72:75], v[190:193], v[214:217], v[72:75]
	v_mfma_f32_16x16x32_bf16 v[68:71], v[182:185], v[222:225], v[68:71]
	v_mfma_f32_16x16x32_bf16 v[56:59], v[190:193], v[222:225], v[56:59]
	v_mfma_f32_16x16x32_bf16 v[116:119], v[186:189], v[202:205], v[116:119]
	v_mfma_f32_16x16x32_bf16 v[112:115], v[194:197], v[202:205], v[112:115]
	v_mfma_f32_16x16x32_bf16 v[96:99], v[186:189], v[210:213], v[96:99]
	v_mfma_f32_16x16x32_bf16 v[88:91], v[194:197], v[210:213], v[88:91]
	v_mfma_f32_16x16x32_bf16 v[80:83], v[186:189], v[218:221], v[80:83]
	v_mfma_f32_16x16x32_bf16 v[72:75], v[194:197], v[218:221], v[72:75]
	v_mfma_f32_16x16x32_bf16 v[68:71], v[186:189], v[226:229], v[68:71]
	v_mfma_f32_16x16x32_bf16 v[56:59], v[194:197], v[226:229], v[56:59]
	s_barrier
	s_setprio 0
	s_add_i32 s74, s74, s0
	v_lshl_add_u64 v[230:231], s[60:61], 0, v[146:147]
	s_mov_b32 m0, s74
	ds_read_b128 v[198:201], v143 offset:16384
	ds_read_b128 v[202:205], v143 offset:17408
	ds_read_b128 v[206:209], v143 offset:18432
	ds_read_b128 v[210:213], v143 offset:19456
	ds_read_b128 v[214:217], v143 offset:20480
	ds_read_b128 v[218:221], v143 offset:21504
	ds_read_b128 v[222:225], v143 offset:22528
	ds_read_b128 v[226:229], v143 offset:23552
	global_load_lds_dwordx4 v[230:231], off
	s_add_i32 m0, s74, 0x2000
	s_add_u32 s74, s60, 0x40000
	v_lshl_add_u64 v[232:233], s[60:61], 0, v[128:129]
	s_addc_u32 s75, s61, 0
	s_add_i32 s9, s9, s0
	global_load_lds_dwordx4 v[232:233], off
	v_lshl_add_u64 v[234:235], s[74:75], 0, v[146:147]
	s_mov_b32 m0, s9
	v_lshl_add_u64 v[236:237], s[62:63], 0, v[130:131]
	global_load_lds_dwordx4 v[234:235], off
	v_lshl_add_u64 v[234:235], s[74:75], 0, v[128:129]
	s_add_i32 m0, s9, 0x2000
	s_nop 0
	global_load_lds_dwordx4 v[234:235], off
	v_lshl_add_u64 v[234:235], s[62:63], 0, v[132:133]
	s_mov_b32 m0, s64
	s_nop 0
	global_load_lds_dwordx4 v[234:235], off
	s_mov_b32 m0, s65
	s_nop 0
	global_load_lds_dwordx4 v[236:237], off
	s_waitcnt vmcnt(8)
	s_waitcnt lgkmcnt(0)
	s_setprio 1
	s_barrier
; #define PG8_STAGE(bufoff, gbase, voff) do { _Pragma("unroll") for (int _i = 0; _i < 2; ++_i) \
;         __builtin_amdgcn_global_load_lds((const unsigned*)((const char*)(gbase) + (voff)[_i]), (PG8_LAS unsigned*)(lds + (bufoff) + ldsw + _i * 8192), 16, 0, 0); } while (0)
; #define PG8_LDA(dst, b, h) do { _Pragma("unroll") for (int m = 0; m < 4; ++m) _Pragma("unroll") for (int k = 0; k < 2; ++k) dst[m][k] = *(const PG8_LAS bf16x8*)(lds + PG8_SA(b, h) + aoff + m * 2048 + k * 1024); } while (0)
; #define PG8_LDB(dst, b, h) do { _Pragma("unroll") for (int n = 0; n < 2; ++n) _Pragma("unroll") for (int k = 0; k < 2; ++k) dst[n][k] = *(const PG8_LAS bf16x8*)(lds + PG8_SB(b, h) + boff + n * 2048 + k * 1024); } while (0)
; #define PG8_MMA(ai, bj, At, Bt) do { __builtin_amdgcn_s_setprio(1); _Pragma("unroll") for (int m = 0; m < 4; ++m) _Pragma("unroll") for (int n = 0; n < 2; ++n) _Pragma("unroll") for (int k = 0; k < 2; ++k) \
;         acc[ai][bj][m][n] = __builtin_amdgcn_mfma_f32_16x16x32_bf16(Bt[n][k], At[m][k], acc[ai][bj][m][n], 0, 0, 0); __builtin_amdgcn_s_setprio(0); } while (0)
; #define PG8_WAIT_V(n) asm volatile("s_waitcnt vmcnt(" #n ")" ::: "memory")
; #define PG8_WAIT_L(n) asm volatile("s_waitcnt lgkmcnt(" #n ")" ::: "memory")
; #define PG8_BAR __builtin_amdgcn_s_barrier()
; #define PG8_SCHED __builtin_amdgcn_sched_barrier(0)
; template <class Epi, class Sched, bool ALIGN_EPI = false, bool SP2 = false>
; __device__ __forceinline__ void gemm_phase(PG8_LAS unsigned char* lds, const Gemm g, const Sched& S, const Epi& E, const int wid) {
;     ...
;             PG8_WAIT_V(8); PG8_WAIT_L(0); PG8_BAR; PG8_MMA(1, 0, At, B0); PG8_MMA(1, 1, At, B1); PG8_BAR; PG8_SCHED;
;             PG8_LDB(B0, 1, 0); PG8_LDB(B1, 1, 1); PG8_SCHED; PG8_LDA(At, 1, 0); PG8_STAGE(PG8_SA(0, 1), a2 + hstepA, voffA);
;             PG8_WAIT_V(8); PG8_WAIT_L(0); PG8_BAR; PG8_MMA(0, 0, At, B0); PG8_MMA(0, 1, At, B1); PG8_BAR; PG8_SCHED;
	v_mfma_f32_16x16x32_bf16 v[44:47], v[160:163], v[198:201], v[44:47]
	v_mfma_f32_16x16x32_bf16 v[40:43], v[174:177], v[198:201], v[40:43]
	v_mfma_f32_16x16x32_bf16 v[20:23], v[160:163], v[206:209], v[20:23]
	v_mfma_f32_16x16x32_bf16 v[12:15], v[174:177], v[206:209], v[12:15]
	v_mfma_f32_16x16x32_bf16 v[64:67], v[160:163], v[214:217], v[64:67]
	v_mfma_f32_16x16x32_bf16 v[52:55], v[174:177], v[214:217], v[52:55]
	v_mfma_f32_16x16x32_bf16 v[36:39], v[160:163], v[222:225], v[36:39]
	v_mfma_f32_16x16x32_bf16 v[28:31], v[174:177], v[222:225], v[28:31]
	v_mfma_f32_16x16x32_bf16 v[44:47], v[170:173], v[202:205], v[44:47]
	v_mfma_f32_16x16x32_bf16 v[40:43], v[178:181], v[202:205], v[40:43]
	v_mfma_f32_16x16x32_bf16 v[20:23], v[170:173], v[210:213], v[20:23]
	v_mfma_f32_16x16x32_bf16 v[12:15], v[178:181], v[210:213], v[12:15]
	v_mfma_f32_16x16x32_bf16 v[64:67], v[170:173], v[218:221], v[64:67]
	v_mfma_f32_16x16x32_bf16 v[52:55], v[178:181], v[218:221], v[52:55]
	v_mfma_f32_16x16x32_bf16 v[36:39], v[170:173], v[226:229], v[36:39]
	v_mfma_f32_16x16x32_bf16 v[28:31], v[178:181], v[226:229], v[28:31]
	s_setprio 0
	s_setprio 1
	v_mfma_f32_16x16x32_bf16 v[16:19], v[182:185], v[198:201], v[16:19]
	v_mfma_f32_16x16x32_bf16 v[8:11], v[190:193], v[198:201], v[8:11]
	v_mfma_f32_16x16x32_bf16 v[60:63], v[182:185], v[206:209], v[60:63]
	v_mfma_f32_16x16x32_bf16 v[48:51], v[190:193], v[206:209], v[48:51]
	v_mfma_f32_16x16x32_bf16 v[32:35], v[182:185], v[214:217], v[32:35]
	v_mfma_f32_16x16x32_bf16 v[24:27], v[190:193], v[214:217], v[24:27]
	v_mfma_f32_16x16x32_bf16 v[4:7], v[182:185], v[222:225], v[4:7]
	v_mfma_f32_16x16x32_bf16 v[0:3], v[190:193], v[222:225], v[0:3]
	v_mfma_f32_16x16x32_bf16 v[16:19], v[186:189], v[202:205], v[16:19]
	v_mfma_f32_16x16x32_bf16 v[8:11], v[194:197], v[202:205], v[8:11]
	v_mfma_f32_16x16x32_bf16 v[60:63], v[186:189], v[210:213], v[60:63]
	v_mfma_f32_16x16x32_bf16 v[48:51], v[194:197], v[210:213], v[48:51]
	v_mfma_f32_16x16x32_bf16 v[32:35], v[186:189], v[218:221], v[32:35]
	v_mfma_f32_16x16x32_bf16 v[24:27], v[194:197], v[218:221], v[24:27]
	v_mfma_f32_16x16x32_bf16 v[4:7], v[186:189], v[226:229], v[4:7]
	v_mfma_f32_16x16x32_bf16 v[0:3], v[194:197], v[226:229], v[0:3]
	s_barrier
	s_setprio 0
	s_add_i32 s9, 0, 0x18000
	s_add_i32 s74, 0, 0x1c000
	v_add_u32_e32 v178, s9, v142
	v_add_u32_e32 v194, s74, v142
	ds_read_b128 v[160:163], v178
	ds_read_b128 v[170:173], v178 offset:1024
	ds_read_b128 v[174:177], v178 offset:2048
	ds_read_b128 v[178:181], v178 offset:3072
	ds_read_b128 v[182:185], v194
	ds_read_b128 v[186:189], v194 offset:1024
	ds_read_b128 v[190:193], v194 offset:2048
	ds_read_b128 v[194:197], v194 offset:3072
	s_add_u32 s62, s62, 0x40000
	s_addc_u32 s63, s63, 0
	s_mov_b32 m0, s66
	v_lshl_add_u64 v[238:239], s[62:63], 0, v[132:133]
	ds_read_b128 v[198:201], v143 offset:32768
	ds_read_b128 v[202:205], v143 offset:33792
	ds_read_b128 v[206:209], v143 offset:34816
	ds_read_b128 v[210:213], v143 offset:35840
	ds_read_b128 v[214:217], v143 offset:36864
	ds_read_b128 v[218:221], v143 offset:37888
	ds_read_b128 v[222:225], v143 offset:38912
	ds_read_b128 v[226:229], v143 offset:39936
	global_load_lds_dwordx4 v[238:239], off
	v_lshl_add_u64 v[238:239], s[62:63], 0, v[130:131]
	s_mov_b32 m0, s67
	s_nop 0
	global_load_lds_dwordx4 v[238:239], off
	s_waitcnt vmcnt(8)
	s_waitcnt lgkmcnt(0)
	s_setprio 1
	s_barrier
	v_mfma_f32_16x16x32_bf16 v[124:127], v[160:163], v[198:201], v[124:127]
	v_mfma_f32_16x16x32_bf16 v[120:123], v[174:177], v[198:201], v[120:123]
	v_mfma_f32_16x16x32_bf16 v[108:111], v[160:163], v[206:209], v[108:111]
	v_mfma_f32_16x16x32_bf16 v[104:107], v[174:177], v[206:209], v[104:107]
	v_mfma_f32_16x16x32_bf16 v[100:103], v[160:163], v[214:217], v[100:103]
	v_mfma_f32_16x16x32_bf16 v[92:95], v[174:177], v[214:217], v[92:95]
	v_mfma_f32_16x16x32_bf16 v[84:87], v[160:163], v[222:225], v[84:87]
	v_mfma_f32_16x16x32_bf16 v[76:79], v[174:177], v[222:225], v[76:79]
	v_mfma_f32_16x16x32_bf16 v[124:127], v[170:173], v[202:205], v[124:127]
	v_mfma_f32_16x16x32_bf16 v[120:123], v[178:181], v[202:205], v[120:123]
	v_mfma_f32_16x16x32_bf16 v[108:111], v[170:173], v[210:213], v[108:111]
	v_mfma_f32_16x16x32_bf16 v[104:107], v[178:181], v[210:213], v[104:107]
	v_mfma_f32_16x16x32_bf16 v[100:103], v[170:173], v[218:221], v[100:103]
	v_mfma_f32_16x16x32_bf16 v[92:95], v[178:181], v[218:221], v[92:95]
	v_mfma_f32_16x16x32_bf16 v[84:87], v[170:173], v[226:229], v[84:87]
	v_mfma_f32_16x16x32_bf16 v[76:79], v[178:181], v[226:229], v[76:79]
	s_setprio 0
	s_setprio 1
	v_mfma_f32_16x16x32_bf16 v[116:119], v[182:185], v[198:201], v[116:119]
	v_mfma_f32_16x16x32_bf16 v[112:115], v[190:193], v[198:201], v[112:115]
	v_mfma_f32_16x16x32_bf16 v[96:99], v[182:185], v[206:209], v[96:99]
	v_mfma_f32_16x16x32_bf16 v[88:91], v[190:193], v[206:209], v[88:91]
	v_mfma_f32_16x16x32_bf16 v[80:83], v[182:185], v[214:217], v[80:83]
	v_mfma_f32_16x16x32_bf16 v[72:75], v[190:193], v[214:217], v[72:75]
	v_mfma_f32_16x16x32_bf16 v[68:71], v[182:185], v[222:225], v[68:71]
	v_mfma_f32_16x16x32_bf16 v[56:59], v[190:193], v[222:225], v[56:59]
	v_mfma_f32_16x16x32_bf16 v[116:119], v[186:189], v[202:205], v[116:119]
	v_mfma_f32_16x16x32_bf16 v[112:115], v[194:197], v[202:205], v[112:115]
	v_mfma_f32_16x16x32_bf16 v[96:99], v[186:189], v[210:213], v[96:99]
	v_mfma_f32_16x16x32_bf16 v[88:91], v[194:197], v[210:213], v[88:91]
	v_mfma_f32_16x16x32_bf16 v[80:83], v[186:189], v[218:221], v[80:83]
	v_mfma_f32_16x16x32_bf16 v[72:75], v[194:197], v[218:221], v[72:75]
	v_mfma_f32_16x16x32_bf16 v[68:71], v[186:189], v[226:229], v[68:71]
	v_mfma_f32_16x16x32_bf16 v[56:59], v[194:197], v[226:229], v[56:59]
	s_barrier
; #define PG8_STAGE(bufoff, gbase, voff) do { _Pragma("unroll") for (int _i = 0; _i < 2; ++_i) \
;         __builtin_amdgcn_global_load_lds((const unsigned*)((const char*)(gbase) + (voff)[_i]), (PG8_LAS unsigned*)(lds + (bufoff) + ldsw + _i * 8192), 16, 0, 0); } while (0)
; #define PG8_LDA(dst, b, h) do { _Pragma("unroll") for (int m = 0; m < 4; ++m) _Pragma("unroll") for (int k = 0; k < 2; ++k) dst[m][k] = *(const PG8_LAS bf16x8*)(lds + PG8_SA(b, h) + aoff + m * 2048 + k * 1024); } while (0)
; #define PG8_MMA(ai, bj, At, Bt) do { __builtin_amdgcn_s_setprio(1); _Pragma("unroll") for (int m = 0; m < 4; ++m) _Pragma("unroll") for (int n = 0; n < 2; ++n) _Pragma("unroll") for (int k = 0; k < 2; ++k) \
;         acc[ai][bj][m][n] = __builtin_amdgcn_mfma_f32_16x16x32_bf16(Bt[n][k], At[m][k], acc[ai][bj][m][n], 0, 0, 0); __builtin_amdgcn_s_setprio(0); } while (0)
; #define PG8_WAIT_V(n) asm volatile("s_waitcnt vmcnt(" #n ")" ::: "memory")
; #define PG8_WAIT_L(n) asm volatile("s_waitcnt lgkmcnt(" #n ")" ::: "memory")
; #define PG8_BAR __builtin_amdgcn_s_barrier()
; #define PG8_SCHED __builtin_amdgcn_sched_barrier(0)
; template <class Epi, class Sched, bool ALIGN_EPI = false, bool SP2 = false>
; __device__ __forceinline__ void gemm_phase(PG8_LAS unsigned char* lds, const Gemm g, const Sched& S, const Epi& E, const int wid) {
;     ...
;         for (int t = 0; t < nt; t += 2) {
;             const bool last = (t == nt - 2);
;             const char* a1 = cA + (size_t)(t + 1) * kstep;
;             const char* a2 = last ? nA : cA + (size_t)(t + 2) * kstep; const char* b2 = last ? nB : cB + (size_t)(t + 2) * kstep;
;     ...
;             PG8_LDA(At, 1, 1); PG8_STAGE(PG8_SB(1, 0), b3, voffB); PG8_STAGE(PG8_SB(1, 1), b3 + hstepB, voffB); PG8_STAGE(PG8_SA(1, 0), a3, voffA);
;             PG8_WAIT_V(8); PG8_WAIT_L(0); PG8_BAR; PG8_MMA(1, 0, At, B0); PG8_MMA(1, 1, At, B1); PG8_BAR; PG8_SCHED;
	s_setprio 0
	s_add_i32 s9, s9, s0
	v_lshl_add_u64 v[230:231], v[230:231], 0, s[80:81]
	s_mov_b32 m0, s9
	ds_read_b128 v[198:201], v143 offset:49152
	ds_read_b128 v[202:205], v143 offset:50176
	ds_read_b128 v[206:209], v143 offset:51200
	ds_read_b128 v[210:213], v143 offset:52224
	ds_read_b128 v[214:217], v143 offset:53248
	ds_read_b128 v[218:221], v143 offset:54272
	ds_read_b128 v[222:225], v143 offset:55296
	ds_read_b128 v[226:229], v143 offset:56320
	global_load_lds_dwordx4 v[230:231], off
	s_add_i32 m0, s9, 0x2000
	s_add_u32 s60, s60, 0x40080
	v_lshl_add_u64 v[230:231], v[232:233], 0, s[80:81]
	s_addc_u32 s61, s61, 0
	s_add_i32 s9, s74, s0
	global_load_lds_dwordx4 v[230:231], off
	v_lshl_add_u64 v[230:231], s[60:61], 0, v[146:147]
	s_mov_b32 m0, s9
	s_nop 0
	global_load_lds_dwordx4 v[230:231], off
	v_lshl_add_u64 v[230:231], s[60:61], 0, v[128:129]
	s_add_i32 m0, s9, 0x2000
	s_nop 0
	global_load_lds_dwordx4 v[230:231], off
	v_lshl_add_u64 v[230:231], v[234:235], 0, s[80:81]
	s_mov_b32 m0, s69
	s_nop 0
	global_load_lds_dwordx4 v[230:231], off
	v_lshl_add_u64 v[230:231], v[236:237], 0, s[80:81]
	s_mov_b32 m0, s70
	s_nop 0
	global_load_lds_dwordx4 v[230:231], off
	s_waitcnt vmcnt(8)
	s_waitcnt lgkmcnt(0)
	s_setprio 1
	s_barrier
	v_mfma_f32_16x16x32_bf16 v[44:47], v[160:163], v[198:201], v[44:47]
	v_mfma_f32_16x16x32_bf16 v[40:43], v[174:177], v[198:201], v[40:43]
	v_mfma_f32_16x16x32_bf16 v[20:23], v[160:163], v[206:209], v[20:23]
	v_mfma_f32_16x16x32_bf16 v[12:15], v[174:177], v[206:209], v[12:15]
	v_mfma_f32_16x16x32_bf16 v[64:67], v[160:163], v[214:217], v[64:67]
	v_mfma_f32_16x16x32_bf16 v[52:55], v[174:177], v[214:217], v[52:55]
	v_mfma_f32_16x16x32_bf16 v[36:39], v[160:163], v[222:225], v[36:39]
	v_mfma_f32_16x16x32_bf16 v[28:31], v[174:177], v[222:225], v[28:31]
	v_mfma_f32_16x16x32_bf16 v[44:47], v[170:173], v[202:205], v[44:47]
	v_mfma_f32_16x16x32_bf16 v[40:43], v[178:181], v[202:205], v[40:43]
	v_mfma_f32_16x16x32_bf16 v[20:23], v[170:173], v[210:213], v[20:23]
	v_mfma_f32_16x16x32_bf16 v[12:15], v[178:181], v[210:213], v[12:15]
	v_mfma_f32_16x16x32_bf16 v[64:67], v[170:173], v[218:221], v[64:67]
	v_mfma_f32_16x16x32_bf16 v[52:55], v[178:181], v[218:221], v[52:55]
	v_mfma_f32_16x16x32_bf16 v[36:39], v[170:173], v[226:229], v[36:39]
	v_mfma_f32_16x16x32_bf16 v[28:31], v[178:181], v[226:229], v[28:31]
	s_setprio 0
	s_setprio 1
	v_mfma_f32_16x16x32_bf16 v[16:19], v[182:185], v[198:201], v[16:19]
	v_mfma_f32_16x16x32_bf16 v[8:11], v[190:193], v[198:201], v[8:11]
	v_mfma_f32_16x16x32_bf16 v[60:63], v[182:185], v[206:209], v[60:63]
	v_mfma_f32_16x16x32_bf16 v[48:51], v[190:193], v[206:209], v[48:51]
	v_mfma_f32_16x16x32_bf16 v[32:35], v[182:185], v[214:217], v[32:35]
	v_mfma_f32_16x16x32_bf16 v[24:27], v[190:193], v[214:217], v[24:27]
	v_mfma_f32_16x16x32_bf16 v[4:7], v[182:185], v[222:225], v[4:7]
	v_mfma_f32_16x16x32_bf16 v[0:3], v[190:193], v[222:225], v[0:3]
	v_mfma_f32_16x16x32_bf16 v[16:19], v[186:189], v[202:205], v[16:19]
	v_mfma_f32_16x16x32_bf16 v[8:11], v[194:197], v[202:205], v[8:11]
	v_mfma_f32_16x16x32_bf16 v[60:63], v[186:189], v[210:213], v[60:63]
	v_mfma_f32_16x16x32_bf16 v[48:51], v[194:197], v[210:213], v[48:51]
	v_mfma_f32_16x16x32_bf16 v[32:35], v[186:189], v[218:221], v[32:35]
	v_mfma_f32_16x16x32_bf16 v[24:27], v[194:197], v[218:221], v[24:27]
	v_mfma_f32_16x16x32_bf16 v[4:7], v[186:189], v[226:229], v[4:7]
	v_mfma_f32_16x16x32_bf16 v[0:3], v[194:197], v[226:229], v[0:3]
	s_barrier
	s_setprio 0
	s_add_u32 s58, s58, 0x100
	s_addc_u32 s59, s59, 0
	s_add_u32 s51, s51, 0x100
	s_addc_u32 s53, s53, 0
	s_cmp_ge_i32 s73, s5
	s_mov_b32 s60, s73
	s_cbranch_scc0 .LBB0_830
	s_mov_b32 s73, 0x18000
	s_mov_b32 s74, 0x1e000
	s_mov_b32 s75, 0xc000
	s_mov_b32 s63, 0xe000
	s_mov_b32 s59, 0x28000
	s_mov_b32 s58, 0x2a000
	s_mov_b32 s61, 0x2c000
	s_mov_b32 s60, 0x32000
